# mLSTM scan rewritten: gate chain once per wave plus lane-parallel expf, 32-deep dC prefetch, n-scan second pass
# baseline (speedup 1.0000x reference)
; __device__ __forceinline__ void mlstm_scan(bf16* DC, float* DN, float* SC, int wg, int G, int tid) {
;     for (int unit = wg; unit < 32 * 8; unit += G) {
;         const int chain = unit >> 3, slice = unit & 7;
;         unsigned* dc = (unsigned*)(DC + (size_t)chain * NSTEP * 8192 + slice * 1024) + tid;
;         float* dn = DN + (size_t)chain * NSTEP * 64 + (tid & 63);
;         float* sc = SC + (size_t)chain * NSTEP * 4;
;         const bool has_n = (slice == 0) && (tid < 64), rec_m = (slice == 0) && (tid == 0);
;         float C0 = 0.f, C1 = 0.f, n = 0.f, m = 0.f;
;         for (int i = 0; i < NSTEP; i += 12) {
;             unsigned v[12]; float nv[12], g[12], am[12];
; #pragma unroll
;             for (int k = 0; k < 12; ++k) { v[k] = dc[(size_t)(i + k) * 4096]; g[k] = sc[(i + k) * 4]; am[k] = sc[(i + k) * 4 + 1]; nv[k] = has_n ? dn[(i + k) * 64] : 0.f; }
.LBB0_655:
	s_ashr_i32 s4, s13, 3
	s_and_b32 s5, s13, 7
	s_mul_i32 s8, s4, 0x210000
	s_lshl_b32 s9, s5, 11
	s_add_u32 s8, s8, s9
	s_add_u32 s8, s8, 0x1ea00000
	s_add_u32 s8, s70, s8
	s_addc_u32 s9, s71, 0
	s_mul_i32 s10, s4, 0x840
	s_add_u32 s14, s70, s10
	s_addc_u32 s15, s71, 0
	s_mul_i32 s10, s4, 0x8400
	s_add_u32 s10, s10, 0x26e00000
	s_add_u32 s16, s70, s10
	s_addc_u32 s17, s71, 0
	v_cmp_gt_u32_e32 vcc, 64, v2
	s_cmp_eq_u32 s5, 0
	s_cselect_b64 s[6:7], vcc, 0
	v_mbcnt_lo_u32_b32 v8, -1, 0
	v_mbcnt_hi_u32_b32 v8, -1, v8
	v_lshlrev_b32_e32 v9, 4, v8
	v_add_u32_e32 v9, v232, v9
	v_lshlrev_b32_e32 v10, 2, v2
	v_add_u32_e32 v11, 0x80000, v10
	v_lshlrev_b32_e32 v12, 2, v8
	v_add_u32_e32 v13, 0x2000, v12
	global_load_dwordx2 v[14:15], v9, s[14:15]
	global_load_dwordx2 v[16:17], v9, s[14:15] offset:1024
	s_mov_b64 exec, 15
	global_load_dwordx2 v[18:19], v9, s[14:15] offset:2048
	s_mov_b64 exec, -1
	s_mov_b64 s[10:11], s[8:9]
	global_load_dword v34, v10, s[10:11]
	s_add_u32 s10, s10, 0x4000
	s_addc_u32 s11, s11, 0
	global_load_dword v35, v10, s[10:11]
	s_add_u32 s10, s10, 0x4000
	s_addc_u32 s11, s11, 0
	global_load_dword v36, v10, s[10:11]
	s_add_u32 s10, s10, 0x4000
	s_addc_u32 s11, s11, 0
	global_load_dword v37, v10, s[10:11]
	s_add_u32 s10, s10, 0x4000
	s_addc_u32 s11, s11, 0
	global_load_dword v38, v10, s[10:11]
	s_add_u32 s10, s10, 0x4000
	s_addc_u32 s11, s11, 0
	global_load_dword v39, v10, s[10:11]
	s_add_u32 s10, s10, 0x4000
	s_addc_u32 s11, s11, 0
	global_load_dword v40, v10, s[10:11]
	s_add_u32 s10, s10, 0x4000
	s_addc_u32 s11, s11, 0
	global_load_dword v41, v10, s[10:11]
	s_add_u32 s10, s10, 0x4000
	s_addc_u32 s11, s11, 0
	global_load_dword v42, v10, s[10:11]
	s_add_u32 s10, s10, 0x4000
	s_addc_u32 s11, s11, 0
	global_load_dword v43, v10, s[10:11]
	s_add_u32 s10, s10, 0x4000
	s_addc_u32 s11, s11, 0
	global_load_dword v44, v10, s[10:11]
	s_add_u32 s10, s10, 0x4000
	s_addc_u32 s11, s11, 0
	global_load_dword v45, v10, s[10:11]
	s_add_u32 s10, s10, 0x4000
	s_addc_u32 s11, s11, 0
	global_load_dword v46, v10, s[10:11]
	s_add_u32 s10, s10, 0x4000
	s_addc_u32 s11, s11, 0
	global_load_dword v47, v10, s[10:11]
	s_add_u32 s10, s10, 0x4000
	s_addc_u32 s11, s11, 0
	global_load_dword v48, v10, s[10:11]
	s_add_u32 s10, s10, 0x4000
	s_addc_u32 s11, s11, 0
	global_load_dword v49, v10, s[10:11]
	s_add_u32 s10, s10, 0x4000
	s_addc_u32 s11, s11, 0
	global_load_dword v50, v10, s[10:11]
	s_add_u32 s10, s10, 0x4000
	s_addc_u32 s11, s11, 0
	global_load_dword v51, v10, s[10:11]
	s_add_u32 s10, s10, 0x4000
	s_addc_u32 s11, s11, 0
	global_load_dword v52, v10, s[10:11]
	s_add_u32 s10, s10, 0x4000
	s_addc_u32 s11, s11, 0
	global_load_dword v53, v10, s[10:11]
	s_add_u32 s10, s10, 0x4000
	s_addc_u32 s11, s11, 0
	global_load_dword v54, v10, s[10:11]
	s_add_u32 s10, s10, 0x4000
	s_addc_u32 s11, s11, 0
	global_load_dword v55, v10, s[10:11]
	s_add_u32 s10, s10, 0x4000
	s_addc_u32 s11, s11, 0
	global_load_dword v56, v10, s[10:11]
	s_add_u32 s10, s10, 0x4000
	s_addc_u32 s11, s11, 0
	global_load_dword v57, v10, s[10:11]
	s_add_u32 s10, s10, 0x4000
	s_addc_u32 s11, s11, 0
	global_load_dword v58, v10, s[10:11]
	s_add_u32 s10, s10, 0x4000
	s_addc_u32 s11, s11, 0
	global_load_dword v59, v10, s[10:11]
	s_add_u32 s10, s10, 0x4000
	s_addc_u32 s11, s11, 0
	global_load_dword v60, v10, s[10:11]
	s_add_u32 s10, s10, 0x4000
	s_addc_u32 s11, s11, 0
	global_load_dword v61, v10, s[10:11]
	s_add_u32 s10, s10, 0x4000
	s_addc_u32 s11, s11, 0
	global_load_dword v62, v10, s[10:11]
	s_add_u32 s10, s10, 0x4000
	s_addc_u32 s11, s11, 0
	global_load_dword v63, v10, s[10:11]
	s_add_u32 s10, s10, 0x4000
	s_addc_u32 s11, s11, 0
	global_load_dword v64, v10, s[10:11]
	s_add_u32 s10, s10, 0x4000
	s_addc_u32 s11, s11, 0
	global_load_dword v65, v10, s[10:11]
	s_add_u32 s10, s10, 0x4000
	s_addc_u32 s11, s11, 0
	v_mov_b32_e32 v20, 0
	v_mov_b32_e32 v22, 0
	v_mov_b32_e32 v25, 0
	v_mov_b32_e32 v23, 0
	v_mov_b32_e32 v26, 0
	v_mov_b32_e32 v24, 0
	v_mov_b32_e32 v27, 0
	v_mov_b32_e32 v68, 0
	v_mov_b32_e32 v69, 0
	v_mov_b32_e32 v70, 0
	s_waitcnt vmcnt(32)
	v_readlane_b32 s2, v14, 0
	v_readlane_b32 s3, v15, 0
	s_nop 1
	v_add_f32_e32 v21, s2, v20
	v_readlane_b32 s4, v14, 1
	v_max_f32_e32 v20, s3, v21
	v_readlane_b32 s5, v15, 1
	v_readfirstlane_b32 s10, v20
	v_add_f32_e32 v21, s4, v20
	v_readlane_b32 s2, v14, 2
	v_max_f32_e32 v20, s5, v21
	v_readlane_b32 s3, v15, 2
	v_readfirstlane_b32 s11, v20
	v_writelane_b32 v22, s10, 0
	v_writelane_b32 v25, s10, 1
	v_add_f32_e32 v21, s2, v20
	v_readlane_b32 s4, v14, 3
	v_max_f32_e32 v20, s3, v21
	v_readlane_b32 s5, v15, 3
	v_readfirstlane_b32 s10, v20
	v_writelane_b32 v22, s11, 1
	v_writelane_b32 v25, s11, 2
	v_add_f32_e32 v21, s4, v20
	v_readlane_b32 s2, v14, 4
	v_max_f32_e32 v20, s5, v21
	v_readlane_b32 s3, v15, 4
	v_readfirstlane_b32 s11, v20
	v_writelane_b32 v22, s10, 2
	v_writelane_b32 v25, s10, 3
	v_add_f32_e32 v21, s2, v20
	v_readlane_b32 s4, v14, 5
	v_max_f32_e32 v20, s3, v21
	v_readlane_b32 s5, v15, 5
	v_readfirstlane_b32 s10, v20
	v_writelane_b32 v22, s11, 3
	v_writelane_b32 v25, s11, 4
	v_add_f32_e32 v21, s4, v20
	v_readlane_b32 s2, v14, 6
	v_max_f32_e32 v20, s5, v21
	v_readlane_b32 s3, v15, 6
	v_readfirstlane_b32 s11, v20
	v_writelane_b32 v22, s10, 4
	v_writelane_b32 v25, s10, 5
	v_add_f32_e32 v21, s2, v20
	v_readlane_b32 s4, v14, 7
	v_max_f32_e32 v20, s3, v21
	v_readlane_b32 s5, v15, 7
	v_readfirstlane_b32 s10, v20
	v_writelane_b32 v22, s11, 5
	v_writelane_b32 v25, s11, 6
	v_add_f32_e32 v21, s4, v20
	v_readlane_b32 s2, v14, 8
	v_max_f32_e32 v20, s5, v21
	v_readlane_b32 s3, v15, 8
	v_readfirstlane_b32 s11, v20
	v_writelane_b32 v22, s10, 6
	v_writelane_b32 v25, s10, 7
; __device__ __forceinline__ void mlstm_scan(bf16* DC, float* DN, float* SC, int wg, int G, int tid) {
;     ...
;                 const float mn = fmaxf(g[k] + m, am[k]), decay = expf(g[k] + m - mn), grow = expf(am[k] - mn);
;     ...
;                 m = mn;
	v_add_f32_e32 v21, s2, v20
	v_readlane_b32 s4, v14, 9
	v_max_f32_e32 v20, s3, v21
	v_readlane_b32 s5, v15, 9
	v_readfirstlane_b32 s10, v20
	v_writelane_b32 v22, s11, 7
	v_writelane_b32 v25, s11, 8
	v_add_f32_e32 v21, s4, v20
	v_readlane_b32 s2, v14, 10
	v_max_f32_e32 v20, s5, v21
	v_readlane_b32 s3, v15, 10
	v_readfirstlane_b32 s11, v20
	v_writelane_b32 v22, s10, 8
	v_writelane_b32 v25, s10, 9
	v_add_f32_e32 v21, s2, v20
	v_readlane_b32 s4, v14, 11
	v_max_f32_e32 v20, s3, v21
	v_readlane_b32 s5, v15, 11
	v_readfirstlane_b32 s10, v20
	v_writelane_b32 v22, s11, 9
	v_writelane_b32 v25, s11, 10
	v_add_f32_e32 v21, s4, v20
	v_readlane_b32 s2, v14, 12
	v_max_f32_e32 v20, s5, v21
	v_readlane_b32 s3, v15, 12
	v_readfirstlane_b32 s11, v20
	v_writelane_b32 v22, s10, 10
	v_writelane_b32 v25, s10, 11
	v_add_f32_e32 v21, s2, v20
	v_readlane_b32 s4, v14, 13
	v_max_f32_e32 v20, s3, v21
	v_readlane_b32 s5, v15, 13
	v_readfirstlane_b32 s10, v20
	v_writelane_b32 v22, s11, 11
	v_writelane_b32 v25, s11, 12
	v_add_f32_e32 v21, s4, v20
	v_readlane_b32 s2, v14, 14
	v_max_f32_e32 v20, s5, v21
	v_readlane_b32 s3, v15, 14
	v_readfirstlane_b32 s11, v20
	v_writelane_b32 v22, s10, 12
	v_writelane_b32 v25, s10, 13
	v_add_f32_e32 v21, s2, v20
	v_readlane_b32 s4, v14, 15
	v_max_f32_e32 v20, s3, v21
	v_readlane_b32 s5, v15, 15
	v_readfirstlane_b32 s10, v20
	v_writelane_b32 v22, s11, 13
	v_writelane_b32 v25, s11, 14
	v_add_f32_e32 v21, s4, v20
	v_readlane_b32 s2, v14, 16
	v_max_f32_e32 v20, s5, v21
	v_readlane_b32 s3, v15, 16
	v_readfirstlane_b32 s11, v20
	v_writelane_b32 v22, s10, 14
	v_writelane_b32 v25, s10, 15
	v_add_f32_e32 v21, s2, v20
	v_readlane_b32 s4, v14, 17
	v_max_f32_e32 v20, s3, v21
	v_readlane_b32 s5, v15, 17
	v_readfirstlane_b32 s10, v20
	v_writelane_b32 v22, s11, 15
	v_writelane_b32 v25, s11, 16
	v_add_f32_e32 v21, s4, v20
	v_readlane_b32 s2, v14, 18
	v_max_f32_e32 v20, s5, v21
	v_readlane_b32 s3, v15, 18
	v_readfirstlane_b32 s11, v20
	v_writelane_b32 v22, s10, 16
	v_writelane_b32 v25, s10, 17
	v_add_f32_e32 v21, s2, v20
	v_readlane_b32 s4, v14, 19
	v_max_f32_e32 v20, s3, v21
	v_readlane_b32 s5, v15, 19
	v_readfirstlane_b32 s10, v20
	v_writelane_b32 v22, s11, 17
	v_writelane_b32 v25, s11, 18
	v_add_f32_e32 v21, s4, v20
	v_readlane_b32 s2, v14, 20
	v_max_f32_e32 v20, s5, v21
	v_readlane_b32 s3, v15, 20
	v_readfirstlane_b32 s11, v20
	v_writelane_b32 v22, s10, 18
	v_writelane_b32 v25, s10, 19
	v_add_f32_e32 v21, s2, v20
	v_readlane_b32 s4, v14, 21
	v_max_f32_e32 v20, s3, v21
	v_readlane_b32 s5, v15, 21
	v_readfirstlane_b32 s10, v20
	v_writelane_b32 v22, s11, 19
	v_writelane_b32 v25, s11, 20
	v_add_f32_e32 v21, s4, v20
	v_readlane_b32 s2, v14, 22
	v_max_f32_e32 v20, s5, v21
	v_readlane_b32 s3, v15, 22
	v_readfirstlane_b32 s11, v20
	v_writelane_b32 v22, s10, 20
	v_writelane_b32 v25, s10, 21
	v_add_f32_e32 v21, s2, v20
	v_readlane_b32 s4, v14, 23
	v_max_f32_e32 v20, s3, v21
	v_readlane_b32 s5, v15, 23
	v_readfirstlane_b32 s10, v20
	v_writelane_b32 v22, s11, 21
	v_writelane_b32 v25, s11, 22
	v_add_f32_e32 v21, s4, v20
	v_readlane_b32 s2, v14, 24
	v_max_f32_e32 v20, s5, v21
	v_readlane_b32 s3, v15, 24
	v_readfirstlane_b32 s11, v20
	v_writelane_b32 v22, s10, 22
	v_writelane_b32 v25, s10, 23
	v_add_f32_e32 v21, s2, v20
	v_readlane_b32 s4, v14, 25
	v_max_f32_e32 v20, s3, v21
	v_readlane_b32 s5, v15, 25
	v_readfirstlane_b32 s10, v20
	v_writelane_b32 v22, s11, 23
	v_writelane_b32 v25, s11, 24
	v_add_f32_e32 v21, s4, v20
	v_readlane_b32 s2, v14, 26
	v_max_f32_e32 v20, s5, v21
	v_readlane_b32 s3, v15, 26
	v_readfirstlane_b32 s11, v20
	v_writelane_b32 v22, s10, 24
	v_writelane_b32 v25, s10, 25
	v_add_f32_e32 v21, s2, v20
	v_readlane_b32 s4, v14, 27
	v_max_f32_e32 v20, s3, v21
	v_readlane_b32 s5, v15, 27
	v_readfirstlane_b32 s10, v20
	v_writelane_b32 v22, s11, 25
	v_writelane_b32 v25, s11, 26
	v_add_f32_e32 v21, s4, v20
	v_readlane_b32 s2, v14, 28
	v_max_f32_e32 v20, s5, v21
	v_readlane_b32 s3, v15, 28
	v_readfirstlane_b32 s11, v20
	v_writelane_b32 v22, s10, 26
	v_writelane_b32 v25, s10, 27
	v_add_f32_e32 v21, s2, v20
	v_readlane_b32 s4, v14, 29
	v_max_f32_e32 v20, s3, v21
	v_readlane_b32 s5, v15, 29
	v_readfirstlane_b32 s10, v20
	v_writelane_b32 v22, s11, 27
	v_writelane_b32 v25, s11, 28
	v_add_f32_e32 v21, s4, v20
	v_readlane_b32 s2, v14, 30
	v_max_f32_e32 v20, s5, v21
	v_readlane_b32 s3, v15, 30
	v_readfirstlane_b32 s11, v20
	v_writelane_b32 v22, s10, 28
	v_writelane_b32 v25, s10, 29
	v_add_f32_e32 v21, s2, v20
	v_readlane_b32 s4, v14, 31
	v_max_f32_e32 v20, s3, v21
	v_readlane_b32 s5, v15, 31
	v_readfirstlane_b32 s10, v20
	v_writelane_b32 v22, s11, 29
	v_writelane_b32 v25, s11, 30
	v_add_f32_e32 v21, s4, v20
	v_readlane_b32 s2, v14, 32
	v_max_f32_e32 v20, s5, v21
	v_readlane_b32 s3, v15, 32
	v_readfirstlane_b32 s11, v20
	v_writelane_b32 v22, s10, 30
	v_writelane_b32 v25, s10, 31
	v_add_f32_e32 v21, s2, v20
	v_readlane_b32 s4, v14, 33
	v_max_f32_e32 v20, s3, v21
	v_readlane_b32 s5, v15, 33
	v_readfirstlane_b32 s10, v20
	v_writelane_b32 v22, s11, 31
	v_writelane_b32 v25, s11, 32
	v_add_f32_e32 v21, s4, v20
	v_readlane_b32 s2, v14, 34
	v_max_f32_e32 v20, s5, v21
	v_readlane_b32 s3, v15, 34
	v_readfirstlane_b32 s11, v20
	v_writelane_b32 v22, s10, 32
	v_writelane_b32 v25, s10, 33
	v_add_f32_e32 v21, s2, v20
	v_readlane_b32 s4, v14, 35
	v_max_f32_e32 v20, s3, v21
	v_readlane_b32 s5, v15, 35
	v_readfirstlane_b32 s10, v20
	v_writelane_b32 v22, s11, 33
	v_writelane_b32 v25, s11, 34
	v_add_f32_e32 v21, s4, v20
	v_readlane_b32 s2, v14, 36
	v_max_f32_e32 v20, s5, v21
	v_readlane_b32 s3, v15, 36
	v_readfirstlane_b32 s11, v20
	v_writelane_b32 v22, s10, 34
	v_writelane_b32 v25, s10, 35
; __device__ __forceinline__ void mlstm_scan(bf16* DC, float* DN, float* SC, int wg, int G, int tid) {
;     ...
;                 const float mn = fmaxf(g[k] + m, am[k]), decay = expf(g[k] + m - mn), grow = expf(am[k] - mn);
;     ...
;                 m = mn;
	v_add_f32_e32 v21, s2, v20
	v_readlane_b32 s4, v14, 37
	v_max_f32_e32 v20, s3, v21
	v_readlane_b32 s5, v15, 37
	v_readfirstlane_b32 s10, v20
	v_writelane_b32 v22, s11, 35
	v_writelane_b32 v25, s11, 36
	v_add_f32_e32 v21, s4, v20
	v_readlane_b32 s2, v14, 38
	v_max_f32_e32 v20, s5, v21
	v_readlane_b32 s3, v15, 38
	v_readfirstlane_b32 s11, v20
	v_writelane_b32 v22, s10, 36
	v_writelane_b32 v25, s10, 37
	v_add_f32_e32 v21, s2, v20
	v_readlane_b32 s4, v14, 39
	v_max_f32_e32 v20, s3, v21
	v_readlane_b32 s5, v15, 39
	v_readfirstlane_b32 s10, v20
	v_writelane_b32 v22, s11, 37
	v_writelane_b32 v25, s11, 38
	v_add_f32_e32 v21, s4, v20
	v_readlane_b32 s2, v14, 40
	v_max_f32_e32 v20, s5, v21
	v_readlane_b32 s3, v15, 40
	v_readfirstlane_b32 s11, v20
	v_writelane_b32 v22, s10, 38
	v_writelane_b32 v25, s10, 39
	v_add_f32_e32 v21, s2, v20
	v_readlane_b32 s4, v14, 41
	v_max_f32_e32 v20, s3, v21
	v_readlane_b32 s5, v15, 41
	v_readfirstlane_b32 s10, v20
	v_writelane_b32 v22, s11, 39
	v_writelane_b32 v25, s11, 40
	v_add_f32_e32 v21, s4, v20
	v_readlane_b32 s2, v14, 42
	v_max_f32_e32 v20, s5, v21
	v_readlane_b32 s3, v15, 42
	v_readfirstlane_b32 s11, v20
	v_writelane_b32 v22, s10, 40
	v_writelane_b32 v25, s10, 41
	v_add_f32_e32 v21, s2, v20
	v_readlane_b32 s4, v14, 43
	v_max_f32_e32 v20, s3, v21
	v_readlane_b32 s5, v15, 43
	v_readfirstlane_b32 s10, v20
	v_writelane_b32 v22, s11, 41
	v_writelane_b32 v25, s11, 42
	v_add_f32_e32 v21, s4, v20
	v_readlane_b32 s2, v14, 44
	v_max_f32_e32 v20, s5, v21
	v_readlane_b32 s3, v15, 44
	v_readfirstlane_b32 s11, v20
	v_writelane_b32 v22, s10, 42
	v_writelane_b32 v25, s10, 43
	v_add_f32_e32 v21, s2, v20
	v_readlane_b32 s4, v14, 45
	v_max_f32_e32 v20, s3, v21
	v_readlane_b32 s5, v15, 45
	v_readfirstlane_b32 s10, v20
	v_writelane_b32 v22, s11, 43
	v_writelane_b32 v25, s11, 44
	v_add_f32_e32 v21, s4, v20
	v_readlane_b32 s2, v14, 46
	v_max_f32_e32 v20, s5, v21
	v_readlane_b32 s3, v15, 46
	v_readfirstlane_b32 s11, v20
	v_writelane_b32 v22, s10, 44
	v_writelane_b32 v25, s10, 45
	v_add_f32_e32 v21, s2, v20
	v_readlane_b32 s4, v14, 47
	v_max_f32_e32 v20, s3, v21
	v_readlane_b32 s5, v15, 47
	v_readfirstlane_b32 s10, v20
	v_writelane_b32 v22, s11, 45
	v_writelane_b32 v25, s11, 46
	v_add_f32_e32 v21, s4, v20
	v_readlane_b32 s2, v14, 48
	v_max_f32_e32 v20, s5, v21
	v_readlane_b32 s3, v15, 48
	v_readfirstlane_b32 s11, v20
	v_writelane_b32 v22, s10, 46
	v_writelane_b32 v25, s10, 47
	v_add_f32_e32 v21, s2, v20
	v_readlane_b32 s4, v14, 49
	v_max_f32_e32 v20, s3, v21
	v_readlane_b32 s5, v15, 49
	v_readfirstlane_b32 s10, v20
	v_writelane_b32 v22, s11, 47
	v_writelane_b32 v25, s11, 48
	v_add_f32_e32 v21, s4, v20
	v_readlane_b32 s2, v14, 50
	v_max_f32_e32 v20, s5, v21
	v_readlane_b32 s3, v15, 50
	v_readfirstlane_b32 s11, v20
	v_writelane_b32 v22, s10, 48
	v_writelane_b32 v25, s10, 49
	v_add_f32_e32 v21, s2, v20
	v_readlane_b32 s4, v14, 51
	v_max_f32_e32 v20, s3, v21
	v_readlane_b32 s5, v15, 51
	v_readfirstlane_b32 s10, v20
	v_writelane_b32 v22, s11, 49
	v_writelane_b32 v25, s11, 50
	v_add_f32_e32 v21, s4, v20
	v_readlane_b32 s2, v14, 52
	v_max_f32_e32 v20, s5, v21
	v_readlane_b32 s3, v15, 52
	v_readfirstlane_b32 s11, v20
	v_writelane_b32 v22, s10, 50
	v_writelane_b32 v25, s10, 51
	v_add_f32_e32 v21, s2, v20
	v_readlane_b32 s4, v14, 53
	v_max_f32_e32 v20, s3, v21
	v_readlane_b32 s5, v15, 53
	v_readfirstlane_b32 s10, v20
	v_writelane_b32 v22, s11, 51
	v_writelane_b32 v25, s11, 52
	v_add_f32_e32 v21, s4, v20
	v_readlane_b32 s2, v14, 54
	v_max_f32_e32 v20, s5, v21
	v_readlane_b32 s3, v15, 54
	v_readfirstlane_b32 s11, v20
	v_writelane_b32 v22, s10, 52
	v_writelane_b32 v25, s10, 53
	v_add_f32_e32 v21, s2, v20
	v_readlane_b32 s4, v14, 55
	v_max_f32_e32 v20, s3, v21
	v_readlane_b32 s5, v15, 55
	v_readfirstlane_b32 s10, v20
	v_writelane_b32 v22, s11, 53
	v_writelane_b32 v25, s11, 54
	v_add_f32_e32 v21, s4, v20
	v_readlane_b32 s2, v14, 56
	v_max_f32_e32 v20, s5, v21
	v_readlane_b32 s3, v15, 56
	v_readfirstlane_b32 s11, v20
	v_writelane_b32 v22, s10, 54
	v_writelane_b32 v25, s10, 55
	v_add_f32_e32 v21, s2, v20
	v_readlane_b32 s4, v14, 57
	v_max_f32_e32 v20, s3, v21
	v_readlane_b32 s5, v15, 57
	v_readfirstlane_b32 s10, v20
	v_writelane_b32 v22, s11, 55
	v_writelane_b32 v25, s11, 56
	v_add_f32_e32 v21, s4, v20
	v_readlane_b32 s2, v14, 58
	v_max_f32_e32 v20, s5, v21
	v_readlane_b32 s3, v15, 58
	v_readfirstlane_b32 s11, v20
	v_writelane_b32 v22, s10, 56
	v_writelane_b32 v25, s10, 57
	v_add_f32_e32 v21, s2, v20
	v_readlane_b32 s4, v14, 59
	v_max_f32_e32 v20, s3, v21
	v_readlane_b32 s5, v15, 59
	v_readfirstlane_b32 s10, v20
	v_writelane_b32 v22, s11, 57
	v_writelane_b32 v25, s11, 58
	v_add_f32_e32 v21, s4, v20
	v_readlane_b32 s2, v14, 60
	v_max_f32_e32 v20, s5, v21
	v_readlane_b32 s3, v15, 60
	v_readfirstlane_b32 s11, v20
	v_writelane_b32 v22, s10, 58
	v_writelane_b32 v25, s10, 59
	v_add_f32_e32 v21, s2, v20
	v_readlane_b32 s4, v14, 61
	v_max_f32_e32 v20, s3, v21
	v_readlane_b32 s5, v15, 61
	v_readfirstlane_b32 s10, v20
	v_writelane_b32 v22, s11, 59
	v_writelane_b32 v25, s11, 60
	v_add_f32_e32 v21, s4, v20
	v_readlane_b32 s2, v14, 62
	v_max_f32_e32 v20, s5, v21
	v_readlane_b32 s3, v15, 62
	v_readfirstlane_b32 s11, v20
	v_writelane_b32 v22, s10, 60
	v_writelane_b32 v25, s10, 61
	v_add_f32_e32 v21, s2, v20
	v_readlane_b32 s4, v14, 63
	v_max_f32_e32 v20, s3, v21
	v_readlane_b32 s5, v15, 63
	v_readfirstlane_b32 s10, v20
	v_writelane_b32 v22, s11, 61
	v_writelane_b32 v25, s11, 62
	v_add_f32_e32 v21, s4, v20
	v_readlane_b32 s2, v16, 0
	v_max_f32_e32 v20, s5, v21
	v_readlane_b32 s3, v17, 0
	v_readfirstlane_b32 s11, v20
	v_writelane_b32 v22, s10, 62
	v_writelane_b32 v25, s10, 63
; __device__ __forceinline__ void mlstm_scan(bf16* DC, float* DN, float* SC, int wg, int G, int tid) {
;     ...
;                 const float mn = fmaxf(g[k] + m, am[k]), decay = expf(g[k] + m - mn), grow = expf(am[k] - mn);
;     ...
;                 m = mn;
	v_add_f32_e32 v21, s2, v20
	v_readlane_b32 s4, v16, 1
	v_max_f32_e32 v20, s3, v21
	v_readlane_b32 s5, v17, 1
	v_readfirstlane_b32 s10, v20
	v_writelane_b32 v22, s11, 63
	v_writelane_b32 v26, s11, 0
	v_add_f32_e32 v21, s4, v20
	v_readlane_b32 s2, v16, 2
	v_max_f32_e32 v20, s5, v21
	v_readlane_b32 s3, v17, 2
	v_readfirstlane_b32 s11, v20
	v_writelane_b32 v23, s10, 0
	v_writelane_b32 v26, s10, 1
	v_add_f32_e32 v21, s2, v20
	v_readlane_b32 s4, v16, 3
	v_max_f32_e32 v20, s3, v21
	v_readlane_b32 s5, v17, 3
	v_readfirstlane_b32 s10, v20
	v_writelane_b32 v23, s11, 1
	v_writelane_b32 v26, s11, 2
	v_add_f32_e32 v21, s4, v20
	v_readlane_b32 s2, v16, 4
	v_max_f32_e32 v20, s5, v21
	v_readlane_b32 s3, v17, 4
	v_readfirstlane_b32 s11, v20
	v_writelane_b32 v23, s10, 2
	v_writelane_b32 v26, s10, 3
	v_add_f32_e32 v21, s2, v20
	v_readlane_b32 s4, v16, 5
	v_max_f32_e32 v20, s3, v21
	v_readlane_b32 s5, v17, 5
	v_readfirstlane_b32 s10, v20
	v_writelane_b32 v23, s11, 3
	v_writelane_b32 v26, s11, 4
	v_add_f32_e32 v21, s4, v20
	v_readlane_b32 s2, v16, 6
	v_max_f32_e32 v20, s5, v21
	v_readlane_b32 s3, v17, 6
	v_readfirstlane_b32 s11, v20
	v_writelane_b32 v23, s10, 4
	v_writelane_b32 v26, s10, 5
	v_add_f32_e32 v21, s2, v20
	v_readlane_b32 s4, v16, 7
	v_max_f32_e32 v20, s3, v21
	v_readlane_b32 s5, v17, 7
	v_readfirstlane_b32 s10, v20
	v_writelane_b32 v23, s11, 5
	v_writelane_b32 v26, s11, 6
	v_add_f32_e32 v21, s4, v20
	v_readlane_b32 s2, v16, 8
	v_max_f32_e32 v20, s5, v21
	v_readlane_b32 s3, v17, 8
	v_readfirstlane_b32 s11, v20
	v_writelane_b32 v23, s10, 6
	v_writelane_b32 v26, s10, 7
	v_add_f32_e32 v21, s2, v20
	v_readlane_b32 s4, v16, 9
	v_max_f32_e32 v20, s3, v21
	v_readlane_b32 s5, v17, 9
	v_readfirstlane_b32 s10, v20
	v_writelane_b32 v23, s11, 7
	v_writelane_b32 v26, s11, 8
	v_add_f32_e32 v21, s4, v20
	v_readlane_b32 s2, v16, 10
	v_max_f32_e32 v20, s5, v21
	v_readlane_b32 s3, v17, 10
	v_readfirstlane_b32 s11, v20
	v_writelane_b32 v23, s10, 8
	v_writelane_b32 v26, s10, 9
	v_add_f32_e32 v21, s2, v20
	v_readlane_b32 s4, v16, 11
	v_max_f32_e32 v20, s3, v21
	v_readlane_b32 s5, v17, 11
	v_readfirstlane_b32 s10, v20
	v_writelane_b32 v23, s11, 9
	v_writelane_b32 v26, s11, 10
	v_add_f32_e32 v21, s4, v20
	v_readlane_b32 s2, v16, 12
	v_max_f32_e32 v20, s5, v21
	v_readlane_b32 s3, v17, 12
	v_readfirstlane_b32 s11, v20
	v_writelane_b32 v23, s10, 10
	v_writelane_b32 v26, s10, 11
	v_add_f32_e32 v21, s2, v20
	v_readlane_b32 s4, v16, 13
	v_max_f32_e32 v20, s3, v21
	v_readlane_b32 s5, v17, 13
	v_readfirstlane_b32 s10, v20
	v_writelane_b32 v23, s11, 11
	v_writelane_b32 v26, s11, 12
	v_add_f32_e32 v21, s4, v20
	v_readlane_b32 s2, v16, 14
	v_max_f32_e32 v20, s5, v21
	v_readlane_b32 s3, v17, 14
	v_readfirstlane_b32 s11, v20
	v_writelane_b32 v23, s10, 12
	v_writelane_b32 v26, s10, 13
	v_add_f32_e32 v21, s2, v20
	v_readlane_b32 s4, v16, 15
	v_max_f32_e32 v20, s3, v21
	v_readlane_b32 s5, v17, 15
	v_readfirstlane_b32 s10, v20
	v_writelane_b32 v23, s11, 13
	v_writelane_b32 v26, s11, 14
	v_add_f32_e32 v21, s4, v20
	v_readlane_b32 s2, v16, 16
	v_max_f32_e32 v20, s5, v21
	v_readlane_b32 s3, v17, 16
	v_readfirstlane_b32 s11, v20
	v_writelane_b32 v23, s10, 14
	v_writelane_b32 v26, s10, 15
	v_add_f32_e32 v21, s2, v20
	v_readlane_b32 s4, v16, 17
	v_max_f32_e32 v20, s3, v21
	v_readlane_b32 s5, v17, 17
	v_readfirstlane_b32 s10, v20
	v_writelane_b32 v23, s11, 15
	v_writelane_b32 v26, s11, 16
	v_add_f32_e32 v21, s4, v20
	v_readlane_b32 s2, v16, 18
	v_max_f32_e32 v20, s5, v21
	v_readlane_b32 s3, v17, 18
	v_readfirstlane_b32 s11, v20
	v_writelane_b32 v23, s10, 16
	v_writelane_b32 v26, s10, 17
	v_add_f32_e32 v21, s2, v20
	v_readlane_b32 s4, v16, 19
	v_max_f32_e32 v20, s3, v21
	v_readlane_b32 s5, v17, 19
	v_readfirstlane_b32 s10, v20
	v_writelane_b32 v23, s11, 17
	v_writelane_b32 v26, s11, 18
	v_add_f32_e32 v21, s4, v20
	v_readlane_b32 s2, v16, 20
	v_max_f32_e32 v20, s5, v21
	v_readlane_b32 s3, v17, 20
	v_readfirstlane_b32 s11, v20
	v_writelane_b32 v23, s10, 18
	v_writelane_b32 v26, s10, 19
	v_add_f32_e32 v21, s2, v20
	v_readlane_b32 s4, v16, 21
	v_max_f32_e32 v20, s3, v21
	v_readlane_b32 s5, v17, 21
	v_readfirstlane_b32 s10, v20
	v_writelane_b32 v23, s11, 19
	v_writelane_b32 v26, s11, 20
	v_add_f32_e32 v21, s4, v20
	v_readlane_b32 s2, v16, 22
	v_max_f32_e32 v20, s5, v21
	v_readlane_b32 s3, v17, 22
	v_readfirstlane_b32 s11, v20
	v_writelane_b32 v23, s10, 20
	v_writelane_b32 v26, s10, 21
	v_add_f32_e32 v21, s2, v20
	v_readlane_b32 s4, v16, 23
	v_max_f32_e32 v20, s3, v21
	v_readlane_b32 s5, v17, 23
	v_readfirstlane_b32 s10, v20
	v_writelane_b32 v23, s11, 21
	v_writelane_b32 v26, s11, 22
	v_add_f32_e32 v21, s4, v20
	v_readlane_b32 s2, v16, 24
	v_max_f32_e32 v20, s5, v21
	v_readlane_b32 s3, v17, 24
	v_readfirstlane_b32 s11, v20
	v_writelane_b32 v23, s10, 22
	v_writelane_b32 v26, s10, 23
	v_add_f32_e32 v21, s2, v20
	v_readlane_b32 s4, v16, 25
	v_max_f32_e32 v20, s3, v21
	v_readlane_b32 s5, v17, 25
	v_readfirstlane_b32 s10, v20
	v_writelane_b32 v23, s11, 23
	v_writelane_b32 v26, s11, 24
	v_add_f32_e32 v21, s4, v20
	v_readlane_b32 s2, v16, 26
	v_max_f32_e32 v20, s5, v21
	v_readlane_b32 s3, v17, 26
	v_readfirstlane_b32 s11, v20
	v_writelane_b32 v23, s10, 24
	v_writelane_b32 v26, s10, 25
	v_add_f32_e32 v21, s2, v20
	v_readlane_b32 s4, v16, 27
	v_max_f32_e32 v20, s3, v21
	v_readlane_b32 s5, v17, 27
	v_readfirstlane_b32 s10, v20
	v_writelane_b32 v23, s11, 25
	v_writelane_b32 v26, s11, 26
	v_add_f32_e32 v21, s4, v20
	v_readlane_b32 s2, v16, 28
	v_max_f32_e32 v20, s5, v21
	v_readlane_b32 s3, v17, 28
	v_readfirstlane_b32 s11, v20
	v_writelane_b32 v23, s10, 26
	v_writelane_b32 v26, s10, 27
	v_add_f32_e32 v21, s2, v20
; __device__ __forceinline__ void mlstm_scan(bf16* DC, float* DN, float* SC, int wg, int G, int tid) {
;     ...
;                 const float mn = fmaxf(g[k] + m, am[k]), decay = expf(g[k] + m - mn), grow = expf(am[k] - mn);
;     ...
;                 m = mn;
	v_readlane_b32 s4, v16, 29
	v_max_f32_e32 v20, s3, v21
	v_readlane_b32 s5, v17, 29
	v_readfirstlane_b32 s10, v20
	v_writelane_b32 v23, s11, 27
	v_writelane_b32 v26, s11, 28
	v_add_f32_e32 v21, s4, v20
	v_readlane_b32 s2, v16, 30
	v_max_f32_e32 v20, s5, v21
	v_readlane_b32 s3, v17, 30
	v_readfirstlane_b32 s11, v20
	v_writelane_b32 v23, s10, 28
	v_writelane_b32 v26, s10, 29
	v_add_f32_e32 v21, s2, v20
	v_readlane_b32 s4, v16, 31
	v_max_f32_e32 v20, s3, v21
	v_readlane_b32 s5, v17, 31
	v_readfirstlane_b32 s10, v20
	v_writelane_b32 v23, s11, 29
	v_writelane_b32 v26, s11, 30
	v_add_f32_e32 v21, s4, v20
	v_readlane_b32 s2, v16, 32
	v_max_f32_e32 v20, s5, v21
	v_readlane_b32 s3, v17, 32
	v_readfirstlane_b32 s11, v20
	v_writelane_b32 v23, s10, 30
	v_writelane_b32 v26, s10, 31
	v_add_f32_e32 v21, s2, v20
	v_readlane_b32 s4, v16, 33
	v_max_f32_e32 v20, s3, v21
	v_readlane_b32 s5, v17, 33
	v_readfirstlane_b32 s10, v20
	v_writelane_b32 v23, s11, 31
	v_writelane_b32 v26, s11, 32
	v_add_f32_e32 v21, s4, v20
	v_readlane_b32 s2, v16, 34
	v_max_f32_e32 v20, s5, v21
	v_readlane_b32 s3, v17, 34
	v_readfirstlane_b32 s11, v20
	v_writelane_b32 v23, s10, 32
	v_writelane_b32 v26, s10, 33
	v_add_f32_e32 v21, s2, v20
	v_readlane_b32 s4, v16, 35
	v_max_f32_e32 v20, s3, v21
	v_readlane_b32 s5, v17, 35
	v_readfirstlane_b32 s10, v20
	v_writelane_b32 v23, s11, 33
	v_writelane_b32 v26, s11, 34
	v_add_f32_e32 v21, s4, v20
	v_readlane_b32 s2, v16, 36
	v_max_f32_e32 v20, s5, v21
	v_readlane_b32 s3, v17, 36
	v_readfirstlane_b32 s11, v20
	v_writelane_b32 v23, s10, 34
	v_writelane_b32 v26, s10, 35
	v_add_f32_e32 v21, s2, v20
	v_readlane_b32 s4, v16, 37
	v_max_f32_e32 v20, s3, v21
	v_readlane_b32 s5, v17, 37
	v_readfirstlane_b32 s10, v20
	v_writelane_b32 v23, s11, 35
	v_writelane_b32 v26, s11, 36
	v_add_f32_e32 v21, s4, v20
	v_readlane_b32 s2, v16, 38
	v_max_f32_e32 v20, s5, v21
	v_readlane_b32 s3, v17, 38
	v_readfirstlane_b32 s11, v20
	v_writelane_b32 v23, s10, 36
	v_writelane_b32 v26, s10, 37
	v_add_f32_e32 v21, s2, v20
	v_readlane_b32 s4, v16, 39
	v_max_f32_e32 v20, s3, v21
	v_readlane_b32 s5, v17, 39
	v_readfirstlane_b32 s10, v20
	v_writelane_b32 v23, s11, 37
	v_writelane_b32 v26, s11, 38
	v_add_f32_e32 v21, s4, v20
	v_readlane_b32 s2, v16, 40
	v_max_f32_e32 v20, s5, v21
	v_readlane_b32 s3, v17, 40
	v_readfirstlane_b32 s11, v20
	v_writelane_b32 v23, s10, 38
	v_writelane_b32 v26, s10, 39
	v_add_f32_e32 v21, s2, v20
	v_readlane_b32 s4, v16, 41
	v_max_f32_e32 v20, s3, v21
	v_readlane_b32 s5, v17, 41
	v_readfirstlane_b32 s10, v20
	v_writelane_b32 v23, s11, 39
	v_writelane_b32 v26, s11, 40
	v_add_f32_e32 v21, s4, v20
	v_readlane_b32 s2, v16, 42
	v_max_f32_e32 v20, s5, v21
	v_readlane_b32 s3, v17, 42
	v_readfirstlane_b32 s11, v20
	v_writelane_b32 v23, s10, 40
	v_writelane_b32 v26, s10, 41
	v_add_f32_e32 v21, s2, v20
	v_readlane_b32 s4, v16, 43
	v_max_f32_e32 v20, s3, v21
	v_readlane_b32 s5, v17, 43
	v_readfirstlane_b32 s10, v20
	v_writelane_b32 v23, s11, 41
	v_writelane_b32 v26, s11, 42
	v_add_f32_e32 v21, s4, v20
	v_readlane_b32 s2, v16, 44
	v_max_f32_e32 v20, s5, v21
	v_readlane_b32 s3, v17, 44
	v_readfirstlane_b32 s11, v20
	v_writelane_b32 v23, s10, 42
	v_writelane_b32 v26, s10, 43
	v_add_f32_e32 v21, s2, v20
	v_readlane_b32 s4, v16, 45
	v_max_f32_e32 v20, s3, v21
	v_readlane_b32 s5, v17, 45
	v_readfirstlane_b32 s10, v20
	v_writelane_b32 v23, s11, 43
	v_writelane_b32 v26, s11, 44
	v_add_f32_e32 v21, s4, v20
	v_readlane_b32 s2, v16, 46
	v_max_f32_e32 v20, s5, v21
	v_readlane_b32 s3, v17, 46
	v_readfirstlane_b32 s11, v20
	v_writelane_b32 v23, s10, 44
	v_writelane_b32 v26, s10, 45
	v_add_f32_e32 v21, s2, v20
	v_readlane_b32 s4, v16, 47
	v_max_f32_e32 v20, s3, v21
	v_readlane_b32 s5, v17, 47
	v_readfirstlane_b32 s10, v20
	v_writelane_b32 v23, s11, 45
	v_writelane_b32 v26, s11, 46
	v_add_f32_e32 v21, s4, v20
	v_readlane_b32 s2, v16, 48
	v_max_f32_e32 v20, s5, v21
	v_readlane_b32 s3, v17, 48
	v_readfirstlane_b32 s11, v20
	v_writelane_b32 v23, s10, 46
	v_writelane_b32 v26, s10, 47
	v_add_f32_e32 v21, s2, v20
	v_readlane_b32 s4, v16, 49
	v_max_f32_e32 v20, s3, v21
	v_readlane_b32 s5, v17, 49
	v_readfirstlane_b32 s10, v20
	v_writelane_b32 v23, s11, 47
	v_writelane_b32 v26, s11, 48
	v_add_f32_e32 v21, s4, v20
	v_readlane_b32 s2, v16, 50
	v_max_f32_e32 v20, s5, v21
	v_readlane_b32 s3, v17, 50
	v_readfirstlane_b32 s11, v20
	v_writelane_b32 v23, s10, 48
	v_writelane_b32 v26, s10, 49
	v_add_f32_e32 v21, s2, v20
	v_readlane_b32 s4, v16, 51
	v_max_f32_e32 v20, s3, v21
	v_readlane_b32 s5, v17, 51
	v_readfirstlane_b32 s10, v20
	v_writelane_b32 v23, s11, 49
	v_writelane_b32 v26, s11, 50
	v_add_f32_e32 v21, s4, v20
	v_readlane_b32 s2, v16, 52
	v_max_f32_e32 v20, s5, v21
	v_readlane_b32 s3, v17, 52
	v_readfirstlane_b32 s11, v20
	v_writelane_b32 v23, s10, 50
	v_writelane_b32 v26, s10, 51
	v_add_f32_e32 v21, s2, v20
	v_readlane_b32 s4, v16, 53
	v_max_f32_e32 v20, s3, v21
	v_readlane_b32 s5, v17, 53
	v_readfirstlane_b32 s10, v20
	v_writelane_b32 v23, s11, 51
	v_writelane_b32 v26, s11, 52
	v_add_f32_e32 v21, s4, v20
	v_readlane_b32 s2, v16, 54
	v_max_f32_e32 v20, s5, v21
	v_readlane_b32 s3, v17, 54
	v_readfirstlane_b32 s11, v20
	v_writelane_b32 v23, s10, 52
	v_writelane_b32 v26, s10, 53
	v_add_f32_e32 v21, s2, v20
	v_readlane_b32 s4, v16, 55
	v_max_f32_e32 v20, s3, v21
	v_readlane_b32 s5, v17, 55
	v_readfirstlane_b32 s10, v20
	v_writelane_b32 v23, s11, 53
	v_writelane_b32 v26, s11, 54
	v_add_f32_e32 v21, s4, v20
	v_readlane_b32 s2, v16, 56
	v_max_f32_e32 v20, s5, v21
	v_readlane_b32 s3, v17, 56
	v_readfirstlane_b32 s11, v20
	v_writelane_b32 v23, s10, 54
	v_writelane_b32 v26, s10, 55
; __device__ __forceinline__ void mlstm_scan(bf16* DC, float* DN, float* SC, int wg, int G, int tid) {
;     ...
;                 const float mn = fmaxf(g[k] + m, am[k]), decay = expf(g[k] + m - mn), grow = expf(am[k] - mn);
;     ...
;                 if (rec_m) sc[(i + k) * 4 + 2] = m;
	v_add_f32_e32 v21, s2, v20
	v_readlane_b32 s4, v16, 57
	v_max_f32_e32 v20, s3, v21
	v_readlane_b32 s5, v17, 57
	v_readfirstlane_b32 s10, v20
	v_writelane_b32 v23, s11, 55
	v_writelane_b32 v26, s11, 56
	v_add_f32_e32 v21, s4, v20
	v_readlane_b32 s2, v16, 58
	v_max_f32_e32 v20, s5, v21
	v_readlane_b32 s3, v17, 58
	v_readfirstlane_b32 s11, v20
	v_writelane_b32 v23, s10, 56
	v_writelane_b32 v26, s10, 57
	v_add_f32_e32 v21, s2, v20
	v_readlane_b32 s4, v16, 59
	v_max_f32_e32 v20, s3, v21
	v_readlane_b32 s5, v17, 59
	v_readfirstlane_b32 s10, v20
	v_writelane_b32 v23, s11, 57
	v_writelane_b32 v26, s11, 58
	v_add_f32_e32 v21, s4, v20
	v_readlane_b32 s2, v16, 60
	v_max_f32_e32 v20, s5, v21
	v_readlane_b32 s3, v17, 60
	v_readfirstlane_b32 s11, v20
	v_writelane_b32 v23, s10, 58
	v_writelane_b32 v26, s10, 59
	v_add_f32_e32 v21, s2, v20
	v_readlane_b32 s4, v16, 61
	v_max_f32_e32 v20, s3, v21
	v_readlane_b32 s5, v17, 61
	v_readfirstlane_b32 s10, v20
	v_writelane_b32 v23, s11, 59
	v_writelane_b32 v26, s11, 60
	v_add_f32_e32 v21, s4, v20
	v_readlane_b32 s2, v16, 62
	v_max_f32_e32 v20, s5, v21
	v_readlane_b32 s3, v17, 62
	v_readfirstlane_b32 s11, v20
	v_writelane_b32 v23, s10, 60
	v_writelane_b32 v26, s10, 61
	v_add_f32_e32 v21, s2, v20
	v_readlane_b32 s4, v16, 63
	v_max_f32_e32 v20, s3, v21
	v_readlane_b32 s5, v17, 63
	v_readfirstlane_b32 s10, v20
	v_writelane_b32 v23, s11, 61
	v_writelane_b32 v26, s11, 62
	v_add_f32_e32 v21, s4, v20
	v_readlane_b32 s2, v18, 0
	v_max_f32_e32 v20, s5, v21
	v_readlane_b32 s3, v19, 0
	v_readfirstlane_b32 s11, v20
	v_writelane_b32 v23, s10, 62
	v_writelane_b32 v26, s10, 63
	v_add_f32_e32 v21, s2, v20
	v_readlane_b32 s4, v18, 1
	v_max_f32_e32 v20, s3, v21
	v_readlane_b32 s5, v19, 1
	v_readfirstlane_b32 s10, v20
	v_writelane_b32 v23, s11, 63
	v_writelane_b32 v27, s11, 0
	v_add_f32_e32 v21, s4, v20
	v_readlane_b32 s2, v18, 2
	v_max_f32_e32 v20, s5, v21
	v_readlane_b32 s3, v19, 2
	v_readfirstlane_b32 s11, v20
	v_writelane_b32 v24, s10, 0
	v_writelane_b32 v27, s10, 1
	v_add_f32_e32 v21, s2, v20
	v_readlane_b32 s4, v18, 3
	v_max_f32_e32 v20, s3, v21
	v_readlane_b32 s5, v19, 3
	v_readfirstlane_b32 s10, v20
	v_writelane_b32 v24, s11, 1
	v_writelane_b32 v27, s11, 2
	v_add_f32_e32 v21, s4, v20
	s_nop 0
	v_max_f32_e32 v20, s5, v21
	s_nop 0
	v_readfirstlane_b32 s11, v20
	v_writelane_b32 v24, s10, 2
	v_writelane_b32 v27, s10, 3
	s_nop 1
	v_writelane_b32 v24, s11, 3
	v_add_f32_e32 v21, v25, v14
	v_sub_f32_e32 v32, v21, v22
	v_mul_f32_e32 v66, 0x3fb8aa3b, v32
	v_fma_f32 v67, v32, s52, -v66
	v_rndne_f32_e32 v31, v66
	v_fmac_f32_e32 v67, 0x32a5705f, v32
	v_sub_f32_e32 v66, v66, v31
	v_add_f32_e32 v66, v66, v67
	v_exp_f32_e32 v66, v66
	v_cvt_i32_f32_e32 v31, v31
	v_cmp_ngt_f32_e32 vcc, s20, v32
	v_ldexp_f32 v66, v66, v31
	s_nop 1
	v_cndmask_b32_e32 v66, 0, v66, vcc
	v_cmp_nlt_f32_e32 vcc, s55, v32
	s_nop 1
	v_cndmask_b32_e32 v71, v234, v66, vcc
	v_sub_f32_e32 v32, v15, v22
	v_mul_f32_e32 v66, 0x3fb8aa3b, v32
	v_fma_f32 v67, v32, s52, -v66
	v_rndne_f32_e32 v31, v66
	v_fmac_f32_e32 v67, 0x32a5705f, v32
	v_sub_f32_e32 v66, v66, v31
	v_add_f32_e32 v66, v66, v67
	v_exp_f32_e32 v66, v66
	v_cvt_i32_f32_e32 v31, v31
	v_cmp_ngt_f32_e32 vcc, s20, v32
	v_ldexp_f32 v66, v66, v31
	s_nop 1
	v_cndmask_b32_e32 v66, 0, v66, vcc
	v_cmp_nlt_f32_e32 vcc, s55, v32
	s_nop 1
	v_cndmask_b32_e32 v28, v234, v66, vcc
	v_add_f32_e32 v21, v26, v16
	v_sub_f32_e32 v32, v21, v23
	v_mul_f32_e32 v66, 0x3fb8aa3b, v32
	v_fma_f32 v67, v32, s52, -v66
	v_rndne_f32_e32 v31, v66
	v_fmac_f32_e32 v67, 0x32a5705f, v32
	v_sub_f32_e32 v66, v66, v31
	v_add_f32_e32 v66, v66, v67
	v_exp_f32_e32 v66, v66
	v_cvt_i32_f32_e32 v31, v31
	v_cmp_ngt_f32_e32 vcc, s20, v32
	v_ldexp_f32 v66, v66, v31
	s_nop 1
	v_cndmask_b32_e32 v66, 0, v66, vcc
	v_cmp_nlt_f32_e32 vcc, s55, v32
	s_nop 1
	v_cndmask_b32_e32 v72, v234, v66, vcc
	v_sub_f32_e32 v32, v17, v23
	v_mul_f32_e32 v66, 0x3fb8aa3b, v32
	v_fma_f32 v67, v32, s52, -v66
	v_rndne_f32_e32 v31, v66
	v_fmac_f32_e32 v67, 0x32a5705f, v32
	v_sub_f32_e32 v66, v66, v31
	v_add_f32_e32 v66, v66, v67
	v_exp_f32_e32 v66, v66
	v_cvt_i32_f32_e32 v31, v31
	v_cmp_ngt_f32_e32 vcc, s20, v32
	v_ldexp_f32 v66, v66, v31
	s_nop 1
	v_cndmask_b32_e32 v66, 0, v66, vcc
	v_cmp_nlt_f32_e32 vcc, s55, v32
	s_nop 1
	v_cndmask_b32_e32 v29, v234, v66, vcc
	v_add_f32_e32 v21, v27, v18
	v_sub_f32_e32 v32, v21, v24
	v_mul_f32_e32 v66, 0x3fb8aa3b, v32
	v_fma_f32 v67, v32, s52, -v66
	v_rndne_f32_e32 v31, v66
	v_fmac_f32_e32 v67, 0x32a5705f, v32
	v_sub_f32_e32 v66, v66, v31
	v_add_f32_e32 v66, v66, v67
	v_exp_f32_e32 v66, v66
	v_cvt_i32_f32_e32 v31, v31
	v_cmp_ngt_f32_e32 vcc, s20, v32
	v_ldexp_f32 v66, v66, v31
	s_nop 1
	v_cndmask_b32_e32 v66, 0, v66, vcc
	v_cmp_nlt_f32_e32 vcc, s55, v32
	s_nop 1
	v_cndmask_b32_e32 v73, v234, v66, vcc
	v_sub_f32_e32 v32, v19, v24
	v_mul_f32_e32 v66, 0x3fb8aa3b, v32
	v_fma_f32 v67, v32, s52, -v66
	v_rndne_f32_e32 v31, v66
	v_fmac_f32_e32 v67, 0x32a5705f, v32
	v_sub_f32_e32 v66, v66, v31
	v_add_f32_e32 v66, v66, v67
	v_exp_f32_e32 v66, v66
	v_cvt_i32_f32_e32 v31, v31
	v_cmp_ngt_f32_e32 vcc, s20, v32
	v_ldexp_f32 v66, v66, v31
	s_nop 1
	v_cndmask_b32_e32 v66, 0, v66, vcc
	v_cmp_nlt_f32_e32 vcc, s55, v32
	s_nop 1
	v_cndmask_b32_e32 v30, v234, v66, vcc
	s_and_b64 vcc, exec, s[6:7]
	s_cbranch_vccz .Lscan_norecm
	global_store_dword v9, v25, s[14:15] offset:8
	global_store_dword v9, v26, s[14:15] offset:1032
	s_mov_b64 exec, 15
	global_store_dword v9, v27, s[14:15] offset:2056
	s_mov_b64 exec, -1
; __device__ __forceinline__ float bf2f(unsigned h) { return __uint_as_float(h << 16); }
; __device__ __forceinline__ unsigned pk2(float lo, float hi) { return pg8::pkbf(lo, hi); }
; __device__ __forceinline__ void mlstm_scan(bf16* DC, float* DN, float* SC, int wg, int G, int tid) {
;     ...
;             for (int k = 0; k < 12; ++k) {
;                 const float mn = fmaxf(g[k] + m, am[k]), decay = expf(g[k] + m - mn), grow = expf(am[k] - mn);
;                 dc[(size_t)(i + k) * 4096] = pk2(C0, C1);
;                 C0 = decay * C0 + grow * bf2f(v[k] & 0xffffu); C1 = decay * C1 + grow * bf2f(v[k] >> 16);
.Lscan_norecm:
	s_waitcnt vmcnt(31)
	v_readlane_b32 s10, v71, 0
	v_readlane_b32 s11, v28, 0
	v_cvt_pk_bf16_f32 v31, v68, v69
	v_lshlrev_b32_e32 v66, 16, v34
	v_and_b32_e32 v67, 0xffff0000, v34
	global_store_dword v10, v31, s[8:9]
	v_mul_f32_e32 v66, s11, v66
	v_mul_f32_e32 v67, s11, v67
	v_fma_f32 v68, v68, s10, v66
	v_fma_f32 v69, v69, s10, v67
	global_load_dword v34, v11, s[8:9]
	s_add_u32 s8, s8, 0x4000
	s_addc_u32 s9, s9, 0
	s_waitcnt vmcnt(32)
	v_readlane_b32 s10, v71, 1
	v_readlane_b32 s11, v28, 1
	v_cvt_pk_bf16_f32 v31, v68, v69
	v_lshlrev_b32_e32 v66, 16, v35
	v_and_b32_e32 v67, 0xffff0000, v35
	global_store_dword v10, v31, s[8:9]
	v_mul_f32_e32 v66, s11, v66
	v_mul_f32_e32 v67, s11, v67
	v_fma_f32 v68, v68, s10, v66
	v_fma_f32 v69, v69, s10, v67
	global_load_dword v35, v11, s[8:9]
	s_add_u32 s8, s8, 0x4000
	s_addc_u32 s9, s9, 0
	s_waitcnt vmcnt(33)
	v_readlane_b32 s10, v71, 2
	v_readlane_b32 s11, v28, 2
	v_cvt_pk_bf16_f32 v31, v68, v69
	v_lshlrev_b32_e32 v66, 16, v36
	v_and_b32_e32 v67, 0xffff0000, v36
	global_store_dword v10, v31, s[8:9]
	v_mul_f32_e32 v66, s11, v66
	v_mul_f32_e32 v67, s11, v67
	v_fma_f32 v68, v68, s10, v66
	v_fma_f32 v69, v69, s10, v67
	global_load_dword v36, v11, s[8:9]
	s_add_u32 s8, s8, 0x4000
	s_addc_u32 s9, s9, 0
	s_waitcnt vmcnt(34)
	v_readlane_b32 s10, v71, 3
	v_readlane_b32 s11, v28, 3
	v_cvt_pk_bf16_f32 v31, v68, v69
	v_lshlrev_b32_e32 v66, 16, v37
	v_and_b32_e32 v67, 0xffff0000, v37
	global_store_dword v10, v31, s[8:9]
	v_mul_f32_e32 v66, s11, v66
	v_mul_f32_e32 v67, s11, v67
	v_fma_f32 v68, v68, s10, v66
	v_fma_f32 v69, v69, s10, v67
	global_load_dword v37, v11, s[8:9]
	s_add_u32 s8, s8, 0x4000
	s_addc_u32 s9, s9, 0
	s_waitcnt vmcnt(35)
	v_readlane_b32 s10, v71, 4
	v_readlane_b32 s11, v28, 4
	v_cvt_pk_bf16_f32 v31, v68, v69
	v_lshlrev_b32_e32 v66, 16, v38
	v_and_b32_e32 v67, 0xffff0000, v38
	global_store_dword v10, v31, s[8:9]
	v_mul_f32_e32 v66, s11, v66
	v_mul_f32_e32 v67, s11, v67
	v_fma_f32 v68, v68, s10, v66
	v_fma_f32 v69, v69, s10, v67
	global_load_dword v38, v11, s[8:9]
	s_add_u32 s8, s8, 0x4000
	s_addc_u32 s9, s9, 0
	s_waitcnt vmcnt(36)
	v_readlane_b32 s10, v71, 5
	v_readlane_b32 s11, v28, 5
	v_cvt_pk_bf16_f32 v31, v68, v69
	v_lshlrev_b32_e32 v66, 16, v39
	v_and_b32_e32 v67, 0xffff0000, v39
	global_store_dword v10, v31, s[8:9]
	v_mul_f32_e32 v66, s11, v66
	v_mul_f32_e32 v67, s11, v67
	v_fma_f32 v68, v68, s10, v66
	v_fma_f32 v69, v69, s10, v67
	global_load_dword v39, v11, s[8:9]
	s_add_u32 s8, s8, 0x4000
	s_addc_u32 s9, s9, 0
	s_waitcnt vmcnt(37)
	v_readlane_b32 s10, v71, 6
	v_readlane_b32 s11, v28, 6
	v_cvt_pk_bf16_f32 v31, v68, v69
	v_lshlrev_b32_e32 v66, 16, v40
	v_and_b32_e32 v67, 0xffff0000, v40
	global_store_dword v10, v31, s[8:9]
	v_mul_f32_e32 v66, s11, v66
	v_mul_f32_e32 v67, s11, v67
	v_fma_f32 v68, v68, s10, v66
	v_fma_f32 v69, v69, s10, v67
	global_load_dword v40, v11, s[8:9]
	s_add_u32 s8, s8, 0x4000
	s_addc_u32 s9, s9, 0
	s_waitcnt vmcnt(38)
	v_readlane_b32 s10, v71, 7
	v_readlane_b32 s11, v28, 7
	v_cvt_pk_bf16_f32 v31, v68, v69
	v_lshlrev_b32_e32 v66, 16, v41
	v_and_b32_e32 v67, 0xffff0000, v41
	global_store_dword v10, v31, s[8:9]
	v_mul_f32_e32 v66, s11, v66
	v_mul_f32_e32 v67, s11, v67
	v_fma_f32 v68, v68, s10, v66
	v_fma_f32 v69, v69, s10, v67
	global_load_dword v41, v11, s[8:9]
	s_add_u32 s8, s8, 0x4000
	s_addc_u32 s9, s9, 0
	s_waitcnt vmcnt(39)
	v_readlane_b32 s10, v71, 8
	v_readlane_b32 s11, v28, 8
	v_cvt_pk_bf16_f32 v31, v68, v69
	v_lshlrev_b32_e32 v66, 16, v42
	v_and_b32_e32 v67, 0xffff0000, v42
	global_store_dword v10, v31, s[8:9]
	v_mul_f32_e32 v66, s11, v66
	v_mul_f32_e32 v67, s11, v67
	v_fma_f32 v68, v68, s10, v66
	v_fma_f32 v69, v69, s10, v67
	global_load_dword v42, v11, s[8:9]
	s_add_u32 s8, s8, 0x4000
	s_addc_u32 s9, s9, 0
	s_waitcnt vmcnt(40)
	v_readlane_b32 s10, v71, 9
	v_readlane_b32 s11, v28, 9
	v_cvt_pk_bf16_f32 v31, v68, v69
	v_lshlrev_b32_e32 v66, 16, v43
	v_and_b32_e32 v67, 0xffff0000, v43
	global_store_dword v10, v31, s[8:9]
	v_mul_f32_e32 v66, s11, v66
	v_mul_f32_e32 v67, s11, v67
	v_fma_f32 v68, v68, s10, v66
	v_fma_f32 v69, v69, s10, v67
	global_load_dword v43, v11, s[8:9]
	s_add_u32 s8, s8, 0x4000
	s_addc_u32 s9, s9, 0
	s_waitcnt vmcnt(41)
	v_readlane_b32 s10, v71, 10
	v_readlane_b32 s11, v28, 10
	v_cvt_pk_bf16_f32 v31, v68, v69
	v_lshlrev_b32_e32 v66, 16, v44
	v_and_b32_e32 v67, 0xffff0000, v44
	global_store_dword v10, v31, s[8:9]
	v_mul_f32_e32 v66, s11, v66
	v_mul_f32_e32 v67, s11, v67
	v_fma_f32 v68, v68, s10, v66
	v_fma_f32 v69, v69, s10, v67
	global_load_dword v44, v11, s[8:9]
	s_add_u32 s8, s8, 0x4000
	s_addc_u32 s9, s9, 0
	s_waitcnt vmcnt(42)
	v_readlane_b32 s10, v71, 11
	v_readlane_b32 s11, v28, 11
	v_cvt_pk_bf16_f32 v31, v68, v69
	v_lshlrev_b32_e32 v66, 16, v45
	v_and_b32_e32 v67, 0xffff0000, v45
	global_store_dword v10, v31, s[8:9]
	v_mul_f32_e32 v66, s11, v66
	v_mul_f32_e32 v67, s11, v67
	v_fma_f32 v68, v68, s10, v66
	v_fma_f32 v69, v69, s10, v67
	global_load_dword v45, v11, s[8:9]
	s_add_u32 s8, s8, 0x4000
	s_addc_u32 s9, s9, 0
	s_waitcnt vmcnt(43)
	v_readlane_b32 s10, v71, 12
	v_readlane_b32 s11, v28, 12
	v_cvt_pk_bf16_f32 v31, v68, v69
	v_lshlrev_b32_e32 v66, 16, v46
	v_and_b32_e32 v67, 0xffff0000, v46
	global_store_dword v10, v31, s[8:9]
	v_mul_f32_e32 v66, s11, v66
	v_mul_f32_e32 v67, s11, v67
	v_fma_f32 v68, v68, s10, v66
	v_fma_f32 v69, v69, s10, v67
	global_load_dword v46, v11, s[8:9]
	s_add_u32 s8, s8, 0x4000
	s_addc_u32 s9, s9, 0
	s_waitcnt vmcnt(44)
; __device__ __forceinline__ float bf2f(unsigned h) { return __uint_as_float(h << 16); }
; __device__ __forceinline__ unsigned pk2(float lo, float hi) { return pg8::pkbf(lo, hi); }
; __device__ __forceinline__ void mlstm_scan(bf16* DC, float* DN, float* SC, int wg, int G, int tid) {
;     ...
;             for (int k = 0; k < 12; ++k) {
;                 const float mn = fmaxf(g[k] + m, am[k]), decay = expf(g[k] + m - mn), grow = expf(am[k] - mn);
;                 dc[(size_t)(i + k) * 4096] = pk2(C0, C1);
;                 C0 = decay * C0 + grow * bf2f(v[k] & 0xffffu); C1 = decay * C1 + grow * bf2f(v[k] >> 16);
	v_readlane_b32 s10, v71, 13
	v_readlane_b32 s11, v28, 13
	v_cvt_pk_bf16_f32 v31, v68, v69
	v_lshlrev_b32_e32 v66, 16, v47
	v_and_b32_e32 v67, 0xffff0000, v47
	global_store_dword v10, v31, s[8:9]
	v_mul_f32_e32 v66, s11, v66
	v_mul_f32_e32 v67, s11, v67
	v_fma_f32 v68, v68, s10, v66
	v_fma_f32 v69, v69, s10, v67
	global_load_dword v47, v11, s[8:9]
	s_add_u32 s8, s8, 0x4000
	s_addc_u32 s9, s9, 0
	s_waitcnt vmcnt(45)
	v_readlane_b32 s10, v71, 14
	v_readlane_b32 s11, v28, 14
	v_cvt_pk_bf16_f32 v31, v68, v69
	v_lshlrev_b32_e32 v66, 16, v48
	v_and_b32_e32 v67, 0xffff0000, v48
	global_store_dword v10, v31, s[8:9]
	v_mul_f32_e32 v66, s11, v66
	v_mul_f32_e32 v67, s11, v67
	v_fma_f32 v68, v68, s10, v66
	v_fma_f32 v69, v69, s10, v67
	global_load_dword v48, v11, s[8:9]
	s_add_u32 s8, s8, 0x4000
	s_addc_u32 s9, s9, 0
	s_waitcnt vmcnt(46)
	v_readlane_b32 s10, v71, 15
	v_readlane_b32 s11, v28, 15
	v_cvt_pk_bf16_f32 v31, v68, v69
	v_lshlrev_b32_e32 v66, 16, v49
	v_and_b32_e32 v67, 0xffff0000, v49
	global_store_dword v10, v31, s[8:9]
	v_mul_f32_e32 v66, s11, v66
	v_mul_f32_e32 v67, s11, v67
	v_fma_f32 v68, v68, s10, v66
	v_fma_f32 v69, v69, s10, v67
	global_load_dword v49, v11, s[8:9]
	s_add_u32 s8, s8, 0x4000
	s_addc_u32 s9, s9, 0
	s_waitcnt vmcnt(47)
	v_readlane_b32 s10, v71, 16
	v_readlane_b32 s11, v28, 16
	v_cvt_pk_bf16_f32 v31, v68, v69
	v_lshlrev_b32_e32 v66, 16, v50
	v_and_b32_e32 v67, 0xffff0000, v50
	global_store_dword v10, v31, s[8:9]
	v_mul_f32_e32 v66, s11, v66
	v_mul_f32_e32 v67, s11, v67
	v_fma_f32 v68, v68, s10, v66
	v_fma_f32 v69, v69, s10, v67
	global_load_dword v50, v11, s[8:9]
	s_add_u32 s8, s8, 0x4000
	s_addc_u32 s9, s9, 0
	s_waitcnt vmcnt(48)
	v_readlane_b32 s10, v71, 17
	v_readlane_b32 s11, v28, 17
	v_cvt_pk_bf16_f32 v31, v68, v69
	v_lshlrev_b32_e32 v66, 16, v51
	v_and_b32_e32 v67, 0xffff0000, v51
	global_store_dword v10, v31, s[8:9]
	v_mul_f32_e32 v66, s11, v66
	v_mul_f32_e32 v67, s11, v67
	v_fma_f32 v68, v68, s10, v66
	v_fma_f32 v69, v69, s10, v67
	global_load_dword v51, v11, s[8:9]
	s_add_u32 s8, s8, 0x4000
	s_addc_u32 s9, s9, 0
	s_waitcnt vmcnt(49)
	v_readlane_b32 s10, v71, 18
	v_readlane_b32 s11, v28, 18
	v_cvt_pk_bf16_f32 v31, v68, v69
	v_lshlrev_b32_e32 v66, 16, v52
	v_and_b32_e32 v67, 0xffff0000, v52
	global_store_dword v10, v31, s[8:9]
	v_mul_f32_e32 v66, s11, v66
	v_mul_f32_e32 v67, s11, v67
	v_fma_f32 v68, v68, s10, v66
	v_fma_f32 v69, v69, s10, v67
	global_load_dword v52, v11, s[8:9]
	s_add_u32 s8, s8, 0x4000
	s_addc_u32 s9, s9, 0
	s_waitcnt vmcnt(50)
	v_readlane_b32 s10, v71, 19
	v_readlane_b32 s11, v28, 19
	v_cvt_pk_bf16_f32 v31, v68, v69
	v_lshlrev_b32_e32 v66, 16, v53
	v_and_b32_e32 v67, 0xffff0000, v53
	global_store_dword v10, v31, s[8:9]
	v_mul_f32_e32 v66, s11, v66
	v_mul_f32_e32 v67, s11, v67
	v_fma_f32 v68, v68, s10, v66
	v_fma_f32 v69, v69, s10, v67
	global_load_dword v53, v11, s[8:9]
	s_add_u32 s8, s8, 0x4000
	s_addc_u32 s9, s9, 0
	s_waitcnt vmcnt(51)
	v_readlane_b32 s10, v71, 20
	v_readlane_b32 s11, v28, 20
	v_cvt_pk_bf16_f32 v31, v68, v69
	v_lshlrev_b32_e32 v66, 16, v54
	v_and_b32_e32 v67, 0xffff0000, v54
	global_store_dword v10, v31, s[8:9]
	v_mul_f32_e32 v66, s11, v66
	v_mul_f32_e32 v67, s11, v67
	v_fma_f32 v68, v68, s10, v66
	v_fma_f32 v69, v69, s10, v67
	global_load_dword v54, v11, s[8:9]
	s_add_u32 s8, s8, 0x4000
	s_addc_u32 s9, s9, 0
	s_waitcnt vmcnt(52)
	v_readlane_b32 s10, v71, 21
	v_readlane_b32 s11, v28, 21
	v_cvt_pk_bf16_f32 v31, v68, v69
	v_lshlrev_b32_e32 v66, 16, v55
	v_and_b32_e32 v67, 0xffff0000, v55
	global_store_dword v10, v31, s[8:9]
	v_mul_f32_e32 v66, s11, v66
	v_mul_f32_e32 v67, s11, v67
	v_fma_f32 v68, v68, s10, v66
	v_fma_f32 v69, v69, s10, v67
	global_load_dword v55, v11, s[8:9]
	s_add_u32 s8, s8, 0x4000
	s_addc_u32 s9, s9, 0
	s_waitcnt vmcnt(53)
	v_readlane_b32 s10, v71, 22
	v_readlane_b32 s11, v28, 22
	v_cvt_pk_bf16_f32 v31, v68, v69
	v_lshlrev_b32_e32 v66, 16, v56
	v_and_b32_e32 v67, 0xffff0000, v56
	global_store_dword v10, v31, s[8:9]
	v_mul_f32_e32 v66, s11, v66
	v_mul_f32_e32 v67, s11, v67
	v_fma_f32 v68, v68, s10, v66
	v_fma_f32 v69, v69, s10, v67
	global_load_dword v56, v11, s[8:9]
	s_add_u32 s8, s8, 0x4000
	s_addc_u32 s9, s9, 0
	s_waitcnt vmcnt(54)
	v_readlane_b32 s10, v71, 23
	v_readlane_b32 s11, v28, 23
	v_cvt_pk_bf16_f32 v31, v68, v69
	v_lshlrev_b32_e32 v66, 16, v57
	v_and_b32_e32 v67, 0xffff0000, v57
	global_store_dword v10, v31, s[8:9]
	v_mul_f32_e32 v66, s11, v66
	v_mul_f32_e32 v67, s11, v67
	v_fma_f32 v68, v68, s10, v66
	v_fma_f32 v69, v69, s10, v67
	global_load_dword v57, v11, s[8:9]
	s_add_u32 s8, s8, 0x4000
	s_addc_u32 s9, s9, 0
	s_waitcnt vmcnt(55)
	v_readlane_b32 s10, v71, 24
	v_readlane_b32 s11, v28, 24
	v_cvt_pk_bf16_f32 v31, v68, v69
	v_lshlrev_b32_e32 v66, 16, v58
	v_and_b32_e32 v67, 0xffff0000, v58
	global_store_dword v10, v31, s[8:9]
	v_mul_f32_e32 v66, s11, v66
	v_mul_f32_e32 v67, s11, v67
	v_fma_f32 v68, v68, s10, v66
	v_fma_f32 v69, v69, s10, v67
	global_load_dword v58, v11, s[8:9]
	s_add_u32 s8, s8, 0x4000
	s_addc_u32 s9, s9, 0
	s_waitcnt vmcnt(56)
	v_readlane_b32 s10, v71, 25
	v_readlane_b32 s11, v28, 25
	v_cvt_pk_bf16_f32 v31, v68, v69
	v_lshlrev_b32_e32 v66, 16, v59
	v_and_b32_e32 v67, 0xffff0000, v59
	global_store_dword v10, v31, s[8:9]
	v_mul_f32_e32 v66, s11, v66
	v_mul_f32_e32 v67, s11, v67
	v_fma_f32 v68, v68, s10, v66
	v_fma_f32 v69, v69, s10, v67
	global_load_dword v59, v11, s[8:9]
	s_add_u32 s8, s8, 0x4000
	s_addc_u32 s9, s9, 0
	s_waitcnt vmcnt(57)
; __device__ __forceinline__ float bf2f(unsigned h) { return __uint_as_float(h << 16); }
; __device__ __forceinline__ unsigned pk2(float lo, float hi) { return pg8::pkbf(lo, hi); }
; __device__ __forceinline__ void mlstm_scan(bf16* DC, float* DN, float* SC, int wg, int G, int tid) {
;     ...
;                 const float mn = fmaxf(g[k] + m, am[k]), decay = expf(g[k] + m - mn), grow = expf(am[k] - mn);
;                 dc[(size_t)(i + k) * 4096] = pk2(C0, C1);
;                 C0 = decay * C0 + grow * bf2f(v[k] & 0xffffu); C1 = decay * C1 + grow * bf2f(v[k] >> 16);
	v_readlane_b32 s10, v71, 26
	v_readlane_b32 s11, v28, 26
	v_cvt_pk_bf16_f32 v31, v68, v69
	v_lshlrev_b32_e32 v66, 16, v60
	v_and_b32_e32 v67, 0xffff0000, v60
	global_store_dword v10, v31, s[8:9]
	v_mul_f32_e32 v66, s11, v66
	v_mul_f32_e32 v67, s11, v67
	v_fma_f32 v68, v68, s10, v66
	v_fma_f32 v69, v69, s10, v67
	global_load_dword v60, v11, s[8:9]
	s_add_u32 s8, s8, 0x4000
	s_addc_u32 s9, s9, 0
	s_waitcnt vmcnt(58)
	v_readlane_b32 s10, v71, 27
	v_readlane_b32 s11, v28, 27
	v_cvt_pk_bf16_f32 v31, v68, v69
	v_lshlrev_b32_e32 v66, 16, v61
	v_and_b32_e32 v67, 0xffff0000, v61
	global_store_dword v10, v31, s[8:9]
	v_mul_f32_e32 v66, s11, v66
	v_mul_f32_e32 v67, s11, v67
	v_fma_f32 v68, v68, s10, v66
	v_fma_f32 v69, v69, s10, v67
	global_load_dword v61, v11, s[8:9]
	s_add_u32 s8, s8, 0x4000
	s_addc_u32 s9, s9, 0
	s_waitcnt vmcnt(59)
	v_readlane_b32 s10, v71, 28
	v_readlane_b32 s11, v28, 28
	v_cvt_pk_bf16_f32 v31, v68, v69
	v_lshlrev_b32_e32 v66, 16, v62
	v_and_b32_e32 v67, 0xffff0000, v62
	global_store_dword v10, v31, s[8:9]
	v_mul_f32_e32 v66, s11, v66
	v_mul_f32_e32 v67, s11, v67
	v_fma_f32 v68, v68, s10, v66
	v_fma_f32 v69, v69, s10, v67
	global_load_dword v62, v11, s[8:9]
	s_add_u32 s8, s8, 0x4000
	s_addc_u32 s9, s9, 0
	s_waitcnt vmcnt(60)
	v_readlane_b32 s10, v71, 29
	v_readlane_b32 s11, v28, 29
	v_cvt_pk_bf16_f32 v31, v68, v69
	v_lshlrev_b32_e32 v66, 16, v63
	v_and_b32_e32 v67, 0xffff0000, v63
	global_store_dword v10, v31, s[8:9]
	v_mul_f32_e32 v66, s11, v66
	v_mul_f32_e32 v67, s11, v67
	v_fma_f32 v68, v68, s10, v66
	v_fma_f32 v69, v69, s10, v67
	global_load_dword v63, v11, s[8:9]
	s_add_u32 s8, s8, 0x4000
	s_addc_u32 s9, s9, 0
	s_waitcnt vmcnt(61)
	v_readlane_b32 s10, v71, 30
	v_readlane_b32 s11, v28, 30
	v_cvt_pk_bf16_f32 v31, v68, v69
	v_lshlrev_b32_e32 v66, 16, v64
	v_and_b32_e32 v67, 0xffff0000, v64
	global_store_dword v10, v31, s[8:9]
	v_mul_f32_e32 v66, s11, v66
	v_mul_f32_e32 v67, s11, v67
	v_fma_f32 v68, v68, s10, v66
	v_fma_f32 v69, v69, s10, v67
	global_load_dword v64, v11, s[8:9]
	s_add_u32 s8, s8, 0x4000
	s_addc_u32 s9, s9, 0
	s_waitcnt vmcnt(62)
	v_readlane_b32 s10, v71, 31
	v_readlane_b32 s11, v28, 31
	v_cvt_pk_bf16_f32 v31, v68, v69
	v_lshlrev_b32_e32 v66, 16, v65
	v_and_b32_e32 v67, 0xffff0000, v65
	global_store_dword v10, v31, s[8:9]
	v_mul_f32_e32 v66, s11, v66
	v_mul_f32_e32 v67, s11, v67
	v_fma_f32 v68, v68, s10, v66
	v_fma_f32 v69, v69, s10, v67
	global_load_dword v65, v11, s[8:9]
	s_add_u32 s8, s8, 0x4000
	s_addc_u32 s9, s9, 0
	s_waitcnt vmcnt(62)
	v_readlane_b32 s10, v71, 32
	v_readlane_b32 s11, v28, 32
	v_cvt_pk_bf16_f32 v31, v68, v69
	v_lshlrev_b32_e32 v66, 16, v34
	v_and_b32_e32 v67, 0xffff0000, v34
	global_store_dword v10, v31, s[8:9]
	v_mul_f32_e32 v66, s11, v66
	v_mul_f32_e32 v67, s11, v67
	v_fma_f32 v68, v68, s10, v66
	v_fma_f32 v69, v69, s10, v67
	global_load_dword v34, v11, s[8:9]
	s_add_u32 s8, s8, 0x4000
	s_addc_u32 s9, s9, 0
	s_waitcnt vmcnt(62)
	v_readlane_b32 s10, v71, 33
	v_readlane_b32 s11, v28, 33
	v_cvt_pk_bf16_f32 v31, v68, v69
	v_lshlrev_b32_e32 v66, 16, v35
	v_and_b32_e32 v67, 0xffff0000, v35
	global_store_dword v10, v31, s[8:9]
	v_mul_f32_e32 v66, s11, v66
	v_mul_f32_e32 v67, s11, v67
	v_fma_f32 v68, v68, s10, v66
	v_fma_f32 v69, v69, s10, v67
	global_load_dword v35, v11, s[8:9]
	s_add_u32 s8, s8, 0x4000
	s_addc_u32 s9, s9, 0
	s_waitcnt vmcnt(62)
	v_readlane_b32 s10, v71, 34
	v_readlane_b32 s11, v28, 34
	v_cvt_pk_bf16_f32 v31, v68, v69
	v_lshlrev_b32_e32 v66, 16, v36
	v_and_b32_e32 v67, 0xffff0000, v36
	global_store_dword v10, v31, s[8:9]
	v_mul_f32_e32 v66, s11, v66
	v_mul_f32_e32 v67, s11, v67
	v_fma_f32 v68, v68, s10, v66
	v_fma_f32 v69, v69, s10, v67
	global_load_dword v36, v11, s[8:9]
	s_add_u32 s8, s8, 0x4000
	s_addc_u32 s9, s9, 0
	s_waitcnt vmcnt(62)
	v_readlane_b32 s10, v71, 35
	v_readlane_b32 s11, v28, 35
	v_cvt_pk_bf16_f32 v31, v68, v69
	v_lshlrev_b32_e32 v66, 16, v37
	v_and_b32_e32 v67, 0xffff0000, v37
	global_store_dword v10, v31, s[8:9]
	v_mul_f32_e32 v66, s11, v66
	v_mul_f32_e32 v67, s11, v67
	v_fma_f32 v68, v68, s10, v66
	v_fma_f32 v69, v69, s10, v67
	global_load_dword v37, v11, s[8:9]
	s_add_u32 s8, s8, 0x4000
	s_addc_u32 s9, s9, 0
	s_waitcnt vmcnt(62)
	v_readlane_b32 s10, v71, 36
	v_readlane_b32 s11, v28, 36
	v_cvt_pk_bf16_f32 v31, v68, v69
	v_lshlrev_b32_e32 v66, 16, v38
	v_and_b32_e32 v67, 0xffff0000, v38
	global_store_dword v10, v31, s[8:9]
	v_mul_f32_e32 v66, s11, v66
	v_mul_f32_e32 v67, s11, v67
	v_fma_f32 v68, v68, s10, v66
	v_fma_f32 v69, v69, s10, v67
	global_load_dword v38, v11, s[8:9]
	s_add_u32 s8, s8, 0x4000
	s_addc_u32 s9, s9, 0
	s_waitcnt vmcnt(62)
	v_readlane_b32 s10, v71, 37
	v_readlane_b32 s11, v28, 37
	v_cvt_pk_bf16_f32 v31, v68, v69
	v_lshlrev_b32_e32 v66, 16, v39
	v_and_b32_e32 v67, 0xffff0000, v39
	global_store_dword v10, v31, s[8:9]
	v_mul_f32_e32 v66, s11, v66
	v_mul_f32_e32 v67, s11, v67
	v_fma_f32 v68, v68, s10, v66
	v_fma_f32 v69, v69, s10, v67
	global_load_dword v39, v11, s[8:9]
	s_add_u32 s8, s8, 0x4000
	s_addc_u32 s9, s9, 0
	s_waitcnt vmcnt(62)
	v_readlane_b32 s10, v71, 38
	v_readlane_b32 s11, v28, 38
	v_cvt_pk_bf16_f32 v31, v68, v69
	v_lshlrev_b32_e32 v66, 16, v40
	v_and_b32_e32 v67, 0xffff0000, v40
	global_store_dword v10, v31, s[8:9]
	v_mul_f32_e32 v66, s11, v66
	v_mul_f32_e32 v67, s11, v67
	v_fma_f32 v68, v68, s10, v66
	v_fma_f32 v69, v69, s10, v67
	global_load_dword v40, v11, s[8:9]
	s_add_u32 s8, s8, 0x4000
	s_addc_u32 s9, s9, 0
	s_waitcnt vmcnt(62)
; __device__ __forceinline__ float bf2f(unsigned h) { return __uint_as_float(h << 16); }
; __device__ __forceinline__ unsigned pk2(float lo, float hi) { return pg8::pkbf(lo, hi); }
; __device__ __forceinline__ void mlstm_scan(bf16* DC, float* DN, float* SC, int wg, int G, int tid) {
;     ...
;                 const float mn = fmaxf(g[k] + m, am[k]), decay = expf(g[k] + m - mn), grow = expf(am[k] - mn);
;                 dc[(size_t)(i + k) * 4096] = pk2(C0, C1);
;                 C0 = decay * C0 + grow * bf2f(v[k] & 0xffffu); C1 = decay * C1 + grow * bf2f(v[k] >> 16);
	v_readlane_b32 s10, v71, 39
	v_readlane_b32 s11, v28, 39
	v_cvt_pk_bf16_f32 v31, v68, v69
	v_lshlrev_b32_e32 v66, 16, v41
	v_and_b32_e32 v67, 0xffff0000, v41
	global_store_dword v10, v31, s[8:9]
	v_mul_f32_e32 v66, s11, v66
	v_mul_f32_e32 v67, s11, v67
	v_fma_f32 v68, v68, s10, v66
	v_fma_f32 v69, v69, s10, v67
	global_load_dword v41, v11, s[8:9]
	s_add_u32 s8, s8, 0x4000
	s_addc_u32 s9, s9, 0
	s_waitcnt vmcnt(62)
	v_readlane_b32 s10, v71, 40
	v_readlane_b32 s11, v28, 40
	v_cvt_pk_bf16_f32 v31, v68, v69
	v_lshlrev_b32_e32 v66, 16, v42
	v_and_b32_e32 v67, 0xffff0000, v42
	global_store_dword v10, v31, s[8:9]
	v_mul_f32_e32 v66, s11, v66
	v_mul_f32_e32 v67, s11, v67
	v_fma_f32 v68, v68, s10, v66
	v_fma_f32 v69, v69, s10, v67
	global_load_dword v42, v11, s[8:9]
	s_add_u32 s8, s8, 0x4000
	s_addc_u32 s9, s9, 0
	s_waitcnt vmcnt(62)
	v_readlane_b32 s10, v71, 41
	v_readlane_b32 s11, v28, 41
	v_cvt_pk_bf16_f32 v31, v68, v69
	v_lshlrev_b32_e32 v66, 16, v43
	v_and_b32_e32 v67, 0xffff0000, v43
	global_store_dword v10, v31, s[8:9]
	v_mul_f32_e32 v66, s11, v66
	v_mul_f32_e32 v67, s11, v67
	v_fma_f32 v68, v68, s10, v66
	v_fma_f32 v69, v69, s10, v67
	global_load_dword v43, v11, s[8:9]
	s_add_u32 s8, s8, 0x4000
	s_addc_u32 s9, s9, 0
	s_waitcnt vmcnt(62)
	v_readlane_b32 s10, v71, 42
	v_readlane_b32 s11, v28, 42
	v_cvt_pk_bf16_f32 v31, v68, v69
	v_lshlrev_b32_e32 v66, 16, v44
	v_and_b32_e32 v67, 0xffff0000, v44
	global_store_dword v10, v31, s[8:9]
	v_mul_f32_e32 v66, s11, v66
	v_mul_f32_e32 v67, s11, v67
	v_fma_f32 v68, v68, s10, v66
	v_fma_f32 v69, v69, s10, v67
	global_load_dword v44, v11, s[8:9]
	s_add_u32 s8, s8, 0x4000
	s_addc_u32 s9, s9, 0
	s_waitcnt vmcnt(62)
	v_readlane_b32 s10, v71, 43
	v_readlane_b32 s11, v28, 43
	v_cvt_pk_bf16_f32 v31, v68, v69
	v_lshlrev_b32_e32 v66, 16, v45
	v_and_b32_e32 v67, 0xffff0000, v45
	global_store_dword v10, v31, s[8:9]
	v_mul_f32_e32 v66, s11, v66
	v_mul_f32_e32 v67, s11, v67
	v_fma_f32 v68, v68, s10, v66
	v_fma_f32 v69, v69, s10, v67
	global_load_dword v45, v11, s[8:9]
	s_add_u32 s8, s8, 0x4000
	s_addc_u32 s9, s9, 0
	s_waitcnt vmcnt(62)
	v_readlane_b32 s10, v71, 44
	v_readlane_b32 s11, v28, 44
	v_cvt_pk_bf16_f32 v31, v68, v69
	v_lshlrev_b32_e32 v66, 16, v46
	v_and_b32_e32 v67, 0xffff0000, v46
	global_store_dword v10, v31, s[8:9]
	v_mul_f32_e32 v66, s11, v66
	v_mul_f32_e32 v67, s11, v67
	v_fma_f32 v68, v68, s10, v66
	v_fma_f32 v69, v69, s10, v67
	global_load_dword v46, v11, s[8:9]
	s_add_u32 s8, s8, 0x4000
	s_addc_u32 s9, s9, 0
	s_waitcnt vmcnt(62)
	v_readlane_b32 s10, v71, 45
	v_readlane_b32 s11, v28, 45
	v_cvt_pk_bf16_f32 v31, v68, v69
	v_lshlrev_b32_e32 v66, 16, v47
	v_and_b32_e32 v67, 0xffff0000, v47
	global_store_dword v10, v31, s[8:9]
	v_mul_f32_e32 v66, s11, v66
	v_mul_f32_e32 v67, s11, v67
	v_fma_f32 v68, v68, s10, v66
	v_fma_f32 v69, v69, s10, v67
	global_load_dword v47, v11, s[8:9]
	s_add_u32 s8, s8, 0x4000
	s_addc_u32 s9, s9, 0
	s_waitcnt vmcnt(62)
	v_readlane_b32 s10, v71, 46
	v_readlane_b32 s11, v28, 46
	v_cvt_pk_bf16_f32 v31, v68, v69
	v_lshlrev_b32_e32 v66, 16, v48
	v_and_b32_e32 v67, 0xffff0000, v48
	global_store_dword v10, v31, s[8:9]
	v_mul_f32_e32 v66, s11, v66
	v_mul_f32_e32 v67, s11, v67
	v_fma_f32 v68, v68, s10, v66
	v_fma_f32 v69, v69, s10, v67
	global_load_dword v48, v11, s[8:9]
	s_add_u32 s8, s8, 0x4000
	s_addc_u32 s9, s9, 0
	s_waitcnt vmcnt(62)
	v_readlane_b32 s10, v71, 47
	v_readlane_b32 s11, v28, 47
	v_cvt_pk_bf16_f32 v31, v68, v69
	v_lshlrev_b32_e32 v66, 16, v49
	v_and_b32_e32 v67, 0xffff0000, v49
	global_store_dword v10, v31, s[8:9]
	v_mul_f32_e32 v66, s11, v66
	v_mul_f32_e32 v67, s11, v67
	v_fma_f32 v68, v68, s10, v66
	v_fma_f32 v69, v69, s10, v67
	global_load_dword v49, v11, s[8:9]
	s_add_u32 s8, s8, 0x4000
	s_addc_u32 s9, s9, 0
	s_waitcnt vmcnt(62)
	v_readlane_b32 s10, v71, 48
	v_readlane_b32 s11, v28, 48
	v_cvt_pk_bf16_f32 v31, v68, v69
	v_lshlrev_b32_e32 v66, 16, v50
	v_and_b32_e32 v67, 0xffff0000, v50
	global_store_dword v10, v31, s[8:9]
	v_mul_f32_e32 v66, s11, v66
	v_mul_f32_e32 v67, s11, v67
	v_fma_f32 v68, v68, s10, v66
	v_fma_f32 v69, v69, s10, v67
	global_load_dword v50, v11, s[8:9]
	s_add_u32 s8, s8, 0x4000
	s_addc_u32 s9, s9, 0
	s_waitcnt vmcnt(62)
	v_readlane_b32 s10, v71, 49
	v_readlane_b32 s11, v28, 49
	v_cvt_pk_bf16_f32 v31, v68, v69
	v_lshlrev_b32_e32 v66, 16, v51
	v_and_b32_e32 v67, 0xffff0000, v51
	global_store_dword v10, v31, s[8:9]
	v_mul_f32_e32 v66, s11, v66
	v_mul_f32_e32 v67, s11, v67
	v_fma_f32 v68, v68, s10, v66
	v_fma_f32 v69, v69, s10, v67
	global_load_dword v51, v11, s[8:9]
	s_add_u32 s8, s8, 0x4000
	s_addc_u32 s9, s9, 0
	s_waitcnt vmcnt(62)
	v_readlane_b32 s10, v71, 50
	v_readlane_b32 s11, v28, 50
	v_cvt_pk_bf16_f32 v31, v68, v69
	v_lshlrev_b32_e32 v66, 16, v52
	v_and_b32_e32 v67, 0xffff0000, v52
	global_store_dword v10, v31, s[8:9]
	v_mul_f32_e32 v66, s11, v66
	v_mul_f32_e32 v67, s11, v67
	v_fma_f32 v68, v68, s10, v66
	v_fma_f32 v69, v69, s10, v67
	global_load_dword v52, v11, s[8:9]
	s_add_u32 s8, s8, 0x4000
	s_addc_u32 s9, s9, 0
	s_waitcnt vmcnt(62)
	v_readlane_b32 s10, v71, 51
	v_readlane_b32 s11, v28, 51
	v_cvt_pk_bf16_f32 v31, v68, v69
	v_lshlrev_b32_e32 v66, 16, v53
	v_and_b32_e32 v67, 0xffff0000, v53
	global_store_dword v10, v31, s[8:9]
	v_mul_f32_e32 v66, s11, v66
	v_mul_f32_e32 v67, s11, v67
	v_fma_f32 v68, v68, s10, v66
	v_fma_f32 v69, v69, s10, v67
	global_load_dword v53, v11, s[8:9]
	s_add_u32 s8, s8, 0x4000
	s_addc_u32 s9, s9, 0
	s_waitcnt vmcnt(62)
; __device__ __forceinline__ float bf2f(unsigned h) { return __uint_as_float(h << 16); }
; __device__ __forceinline__ unsigned pk2(float lo, float hi) { return pg8::pkbf(lo, hi); }
; __device__ __forceinline__ void mlstm_scan(bf16* DC, float* DN, float* SC, int wg, int G, int tid) {
;     ...
;                 const float mn = fmaxf(g[k] + m, am[k]), decay = expf(g[k] + m - mn), grow = expf(am[k] - mn);
;                 dc[(size_t)(i + k) * 4096] = pk2(C0, C1);
;                 C0 = decay * C0 + grow * bf2f(v[k] & 0xffffu); C1 = decay * C1 + grow * bf2f(v[k] >> 16);
	v_readlane_b32 s10, v71, 52
	v_readlane_b32 s11, v28, 52
	v_cvt_pk_bf16_f32 v31, v68, v69
	v_lshlrev_b32_e32 v66, 16, v54
	v_and_b32_e32 v67, 0xffff0000, v54
	global_store_dword v10, v31, s[8:9]
	v_mul_f32_e32 v66, s11, v66
	v_mul_f32_e32 v67, s11, v67
	v_fma_f32 v68, v68, s10, v66
	v_fma_f32 v69, v69, s10, v67
	global_load_dword v54, v11, s[8:9]
	s_add_u32 s8, s8, 0x4000
	s_addc_u32 s9, s9, 0
	s_waitcnt vmcnt(62)
	v_readlane_b32 s10, v71, 53
	v_readlane_b32 s11, v28, 53
	v_cvt_pk_bf16_f32 v31, v68, v69
	v_lshlrev_b32_e32 v66, 16, v55
	v_and_b32_e32 v67, 0xffff0000, v55
	global_store_dword v10, v31, s[8:9]
	v_mul_f32_e32 v66, s11, v66
	v_mul_f32_e32 v67, s11, v67
	v_fma_f32 v68, v68, s10, v66
	v_fma_f32 v69, v69, s10, v67
	global_load_dword v55, v11, s[8:9]
	s_add_u32 s8, s8, 0x4000
	s_addc_u32 s9, s9, 0
	s_waitcnt vmcnt(62)
	v_readlane_b32 s10, v71, 54
	v_readlane_b32 s11, v28, 54
	v_cvt_pk_bf16_f32 v31, v68, v69
	v_lshlrev_b32_e32 v66, 16, v56
	v_and_b32_e32 v67, 0xffff0000, v56
	global_store_dword v10, v31, s[8:9]
	v_mul_f32_e32 v66, s11, v66
	v_mul_f32_e32 v67, s11, v67
	v_fma_f32 v68, v68, s10, v66
	v_fma_f32 v69, v69, s10, v67
	global_load_dword v56, v11, s[8:9]
	s_add_u32 s8, s8, 0x4000
	s_addc_u32 s9, s9, 0
	s_waitcnt vmcnt(62)
	v_readlane_b32 s10, v71, 55
	v_readlane_b32 s11, v28, 55
	v_cvt_pk_bf16_f32 v31, v68, v69
	v_lshlrev_b32_e32 v66, 16, v57
	v_and_b32_e32 v67, 0xffff0000, v57
	global_store_dword v10, v31, s[8:9]
	v_mul_f32_e32 v66, s11, v66
	v_mul_f32_e32 v67, s11, v67
	v_fma_f32 v68, v68, s10, v66
	v_fma_f32 v69, v69, s10, v67
	global_load_dword v57, v11, s[8:9]
	s_add_u32 s8, s8, 0x4000
	s_addc_u32 s9, s9, 0
	s_waitcnt vmcnt(62)
	v_readlane_b32 s10, v71, 56
	v_readlane_b32 s11, v28, 56
	v_cvt_pk_bf16_f32 v31, v68, v69
	v_lshlrev_b32_e32 v66, 16, v58
	v_and_b32_e32 v67, 0xffff0000, v58
	global_store_dword v10, v31, s[8:9]
	v_mul_f32_e32 v66, s11, v66
	v_mul_f32_e32 v67, s11, v67
	v_fma_f32 v68, v68, s10, v66
	v_fma_f32 v69, v69, s10, v67
	global_load_dword v58, v11, s[8:9]
	s_add_u32 s8, s8, 0x4000
	s_addc_u32 s9, s9, 0
	s_waitcnt vmcnt(62)
	v_readlane_b32 s10, v71, 57
	v_readlane_b32 s11, v28, 57
	v_cvt_pk_bf16_f32 v31, v68, v69
	v_lshlrev_b32_e32 v66, 16, v59
	v_and_b32_e32 v67, 0xffff0000, v59
	global_store_dword v10, v31, s[8:9]
	v_mul_f32_e32 v66, s11, v66
	v_mul_f32_e32 v67, s11, v67
	v_fma_f32 v68, v68, s10, v66
	v_fma_f32 v69, v69, s10, v67
	global_load_dword v59, v11, s[8:9]
	s_add_u32 s8, s8, 0x4000
	s_addc_u32 s9, s9, 0
	s_waitcnt vmcnt(62)
	v_readlane_b32 s10, v71, 58
	v_readlane_b32 s11, v28, 58
	v_cvt_pk_bf16_f32 v31, v68, v69
	v_lshlrev_b32_e32 v66, 16, v60
	v_and_b32_e32 v67, 0xffff0000, v60
	global_store_dword v10, v31, s[8:9]
	v_mul_f32_e32 v66, s11, v66
	v_mul_f32_e32 v67, s11, v67
	v_fma_f32 v68, v68, s10, v66
	v_fma_f32 v69, v69, s10, v67
	global_load_dword v60, v11, s[8:9]
	s_add_u32 s8, s8, 0x4000
	s_addc_u32 s9, s9, 0
	s_waitcnt vmcnt(62)
	v_readlane_b32 s10, v71, 59
	v_readlane_b32 s11, v28, 59
	v_cvt_pk_bf16_f32 v31, v68, v69
	v_lshlrev_b32_e32 v66, 16, v61
	v_and_b32_e32 v67, 0xffff0000, v61
	global_store_dword v10, v31, s[8:9]
	v_mul_f32_e32 v66, s11, v66
	v_mul_f32_e32 v67, s11, v67
	v_fma_f32 v68, v68, s10, v66
	v_fma_f32 v69, v69, s10, v67
	global_load_dword v61, v11, s[8:9]
	s_add_u32 s8, s8, 0x4000
	s_addc_u32 s9, s9, 0
	s_waitcnt vmcnt(62)
	v_readlane_b32 s10, v71, 60
	v_readlane_b32 s11, v28, 60
	v_cvt_pk_bf16_f32 v31, v68, v69
	v_lshlrev_b32_e32 v66, 16, v62
	v_and_b32_e32 v67, 0xffff0000, v62
	global_store_dword v10, v31, s[8:9]
	v_mul_f32_e32 v66, s11, v66
	v_mul_f32_e32 v67, s11, v67
	v_fma_f32 v68, v68, s10, v66
	v_fma_f32 v69, v69, s10, v67
	global_load_dword v62, v11, s[8:9]
	s_add_u32 s8, s8, 0x4000
	s_addc_u32 s9, s9, 0
	s_waitcnt vmcnt(62)
	v_readlane_b32 s10, v71, 61
	v_readlane_b32 s11, v28, 61
	v_cvt_pk_bf16_f32 v31, v68, v69
	v_lshlrev_b32_e32 v66, 16, v63
	v_and_b32_e32 v67, 0xffff0000, v63
	global_store_dword v10, v31, s[8:9]
	v_mul_f32_e32 v66, s11, v66
	v_mul_f32_e32 v67, s11, v67
	v_fma_f32 v68, v68, s10, v66
	v_fma_f32 v69, v69, s10, v67
	global_load_dword v63, v11, s[8:9]
	s_add_u32 s8, s8, 0x4000
	s_addc_u32 s9, s9, 0
	s_waitcnt vmcnt(62)
	v_readlane_b32 s10, v71, 62
	v_readlane_b32 s11, v28, 62
	v_cvt_pk_bf16_f32 v31, v68, v69
	v_lshlrev_b32_e32 v66, 16, v64
	v_and_b32_e32 v67, 0xffff0000, v64
	global_store_dword v10, v31, s[8:9]
	v_mul_f32_e32 v66, s11, v66
	v_mul_f32_e32 v67, s11, v67
	v_fma_f32 v68, v68, s10, v66
	v_fma_f32 v69, v69, s10, v67
	global_load_dword v64, v11, s[8:9]
	s_add_u32 s8, s8, 0x4000
	s_addc_u32 s9, s9, 0
	s_waitcnt vmcnt(62)
	v_readlane_b32 s10, v71, 63
	v_readlane_b32 s11, v28, 63
	v_cvt_pk_bf16_f32 v31, v68, v69
	v_lshlrev_b32_e32 v66, 16, v65
	v_and_b32_e32 v67, 0xffff0000, v65
	global_store_dword v10, v31, s[8:9]
	v_mul_f32_e32 v66, s11, v66
	v_mul_f32_e32 v67, s11, v67
	v_fma_f32 v68, v68, s10, v66
	v_fma_f32 v69, v69, s10, v67
	global_load_dword v65, v11, s[8:9]
	s_add_u32 s8, s8, 0x4000
	s_addc_u32 s9, s9, 0
	s_waitcnt vmcnt(62)
	v_readlane_b32 s10, v72, 0
	v_readlane_b32 s11, v29, 0
	v_cvt_pk_bf16_f32 v31, v68, v69
	v_lshlrev_b32_e32 v66, 16, v34
	v_and_b32_e32 v67, 0xffff0000, v34
	global_store_dword v10, v31, s[8:9]
	v_mul_f32_e32 v66, s11, v66
	v_mul_f32_e32 v67, s11, v67
	v_fma_f32 v68, v68, s10, v66
	v_fma_f32 v69, v69, s10, v67
	global_load_dword v34, v11, s[8:9]
	s_add_u32 s8, s8, 0x4000
	s_addc_u32 s9, s9, 0
	s_waitcnt vmcnt(62)
; __device__ __forceinline__ float bf2f(unsigned h) { return __uint_as_float(h << 16); }
; __device__ __forceinline__ unsigned pk2(float lo, float hi) { return pg8::pkbf(lo, hi); }
; __device__ __forceinline__ void mlstm_scan(bf16* DC, float* DN, float* SC, int wg, int G, int tid) {
;     ...
;                 const float mn = fmaxf(g[k] + m, am[k]), decay = expf(g[k] + m - mn), grow = expf(am[k] - mn);
;                 dc[(size_t)(i + k) * 4096] = pk2(C0, C1);
;                 C0 = decay * C0 + grow * bf2f(v[k] & 0xffffu); C1 = decay * C1 + grow * bf2f(v[k] >> 16);
	v_readlane_b32 s10, v72, 1
	v_readlane_b32 s11, v29, 1
	v_cvt_pk_bf16_f32 v31, v68, v69
	v_lshlrev_b32_e32 v66, 16, v35
	v_and_b32_e32 v67, 0xffff0000, v35
	global_store_dword v10, v31, s[8:9]
	v_mul_f32_e32 v66, s11, v66
	v_mul_f32_e32 v67, s11, v67
	v_fma_f32 v68, v68, s10, v66
	v_fma_f32 v69, v69, s10, v67
	global_load_dword v35, v11, s[8:9]
	s_add_u32 s8, s8, 0x4000
	s_addc_u32 s9, s9, 0
	s_waitcnt vmcnt(62)
	v_readlane_b32 s10, v72, 2
	v_readlane_b32 s11, v29, 2
	v_cvt_pk_bf16_f32 v31, v68, v69
	v_lshlrev_b32_e32 v66, 16, v36
	v_and_b32_e32 v67, 0xffff0000, v36
	global_store_dword v10, v31, s[8:9]
	v_mul_f32_e32 v66, s11, v66
	v_mul_f32_e32 v67, s11, v67
	v_fma_f32 v68, v68, s10, v66
	v_fma_f32 v69, v69, s10, v67
	global_load_dword v36, v11, s[8:9]
	s_add_u32 s8, s8, 0x4000
	s_addc_u32 s9, s9, 0
	s_waitcnt vmcnt(62)
	v_readlane_b32 s10, v72, 3
	v_readlane_b32 s11, v29, 3
	v_cvt_pk_bf16_f32 v31, v68, v69
	v_lshlrev_b32_e32 v66, 16, v37
	v_and_b32_e32 v67, 0xffff0000, v37
	global_store_dword v10, v31, s[8:9]
	v_mul_f32_e32 v66, s11, v66
	v_mul_f32_e32 v67, s11, v67
	v_fma_f32 v68, v68, s10, v66
	v_fma_f32 v69, v69, s10, v67
	global_load_dword v37, v11, s[8:9]
	s_add_u32 s8, s8, 0x4000
	s_addc_u32 s9, s9, 0
	s_waitcnt vmcnt(62)
	v_readlane_b32 s10, v72, 4
	v_readlane_b32 s11, v29, 4
	v_cvt_pk_bf16_f32 v31, v68, v69
	v_lshlrev_b32_e32 v66, 16, v38
	v_and_b32_e32 v67, 0xffff0000, v38
	global_store_dword v10, v31, s[8:9]
	v_mul_f32_e32 v66, s11, v66
	v_mul_f32_e32 v67, s11, v67
	v_fma_f32 v68, v68, s10, v66
	v_fma_f32 v69, v69, s10, v67
	global_load_dword v38, v11, s[8:9]
	s_add_u32 s8, s8, 0x4000
	s_addc_u32 s9, s9, 0
	s_waitcnt vmcnt(62)
	v_readlane_b32 s10, v72, 5
	v_readlane_b32 s11, v29, 5
	v_cvt_pk_bf16_f32 v31, v68, v69
	v_lshlrev_b32_e32 v66, 16, v39
	v_and_b32_e32 v67, 0xffff0000, v39
	global_store_dword v10, v31, s[8:9]
	v_mul_f32_e32 v66, s11, v66
	v_mul_f32_e32 v67, s11, v67
	v_fma_f32 v68, v68, s10, v66
	v_fma_f32 v69, v69, s10, v67
	global_load_dword v39, v11, s[8:9]
	s_add_u32 s8, s8, 0x4000
	s_addc_u32 s9, s9, 0
	s_waitcnt vmcnt(62)
	v_readlane_b32 s10, v72, 6
	v_readlane_b32 s11, v29, 6
	v_cvt_pk_bf16_f32 v31, v68, v69
	v_lshlrev_b32_e32 v66, 16, v40
	v_and_b32_e32 v67, 0xffff0000, v40
	global_store_dword v10, v31, s[8:9]
	v_mul_f32_e32 v66, s11, v66
	v_mul_f32_e32 v67, s11, v67
	v_fma_f32 v68, v68, s10, v66
	v_fma_f32 v69, v69, s10, v67
	global_load_dword v40, v11, s[8:9]
	s_add_u32 s8, s8, 0x4000
	s_addc_u32 s9, s9, 0
	s_waitcnt vmcnt(62)
	v_readlane_b32 s10, v72, 7
	v_readlane_b32 s11, v29, 7
	v_cvt_pk_bf16_f32 v31, v68, v69
	v_lshlrev_b32_e32 v66, 16, v41
	v_and_b32_e32 v67, 0xffff0000, v41
	global_store_dword v10, v31, s[8:9]
	v_mul_f32_e32 v66, s11, v66
	v_mul_f32_e32 v67, s11, v67
	v_fma_f32 v68, v68, s10, v66
	v_fma_f32 v69, v69, s10, v67
	global_load_dword v41, v11, s[8:9]
	s_add_u32 s8, s8, 0x4000
	s_addc_u32 s9, s9, 0
	s_waitcnt vmcnt(62)
	v_readlane_b32 s10, v72, 8
	v_readlane_b32 s11, v29, 8
	v_cvt_pk_bf16_f32 v31, v68, v69
	v_lshlrev_b32_e32 v66, 16, v42
	v_and_b32_e32 v67, 0xffff0000, v42
	global_store_dword v10, v31, s[8:9]
	v_mul_f32_e32 v66, s11, v66
	v_mul_f32_e32 v67, s11, v67
	v_fma_f32 v68, v68, s10, v66
	v_fma_f32 v69, v69, s10, v67
	global_load_dword v42, v11, s[8:9]
	s_add_u32 s8, s8, 0x4000
	s_addc_u32 s9, s9, 0
	s_waitcnt vmcnt(62)
	v_readlane_b32 s10, v72, 9
	v_readlane_b32 s11, v29, 9
	v_cvt_pk_bf16_f32 v31, v68, v69
	v_lshlrev_b32_e32 v66, 16, v43
	v_and_b32_e32 v67, 0xffff0000, v43
	global_store_dword v10, v31, s[8:9]
	v_mul_f32_e32 v66, s11, v66
	v_mul_f32_e32 v67, s11, v67
	v_fma_f32 v68, v68, s10, v66
	v_fma_f32 v69, v69, s10, v67
	global_load_dword v43, v11, s[8:9]
	s_add_u32 s8, s8, 0x4000
	s_addc_u32 s9, s9, 0
	s_waitcnt vmcnt(62)
	v_readlane_b32 s10, v72, 10
	v_readlane_b32 s11, v29, 10
	v_cvt_pk_bf16_f32 v31, v68, v69
	v_lshlrev_b32_e32 v66, 16, v44
	v_and_b32_e32 v67, 0xffff0000, v44
	global_store_dword v10, v31, s[8:9]
	v_mul_f32_e32 v66, s11, v66
	v_mul_f32_e32 v67, s11, v67
	v_fma_f32 v68, v68, s10, v66
	v_fma_f32 v69, v69, s10, v67
	global_load_dword v44, v11, s[8:9]
	s_add_u32 s8, s8, 0x4000
	s_addc_u32 s9, s9, 0
	s_waitcnt vmcnt(62)
	v_readlane_b32 s10, v72, 11
	v_readlane_b32 s11, v29, 11
	v_cvt_pk_bf16_f32 v31, v68, v69
	v_lshlrev_b32_e32 v66, 16, v45
	v_and_b32_e32 v67, 0xffff0000, v45
	global_store_dword v10, v31, s[8:9]
	v_mul_f32_e32 v66, s11, v66
	v_mul_f32_e32 v67, s11, v67
	v_fma_f32 v68, v68, s10, v66
	v_fma_f32 v69, v69, s10, v67
	global_load_dword v45, v11, s[8:9]
	s_add_u32 s8, s8, 0x4000
	s_addc_u32 s9, s9, 0
	s_waitcnt vmcnt(62)
	v_readlane_b32 s10, v72, 12
	v_readlane_b32 s11, v29, 12
	v_cvt_pk_bf16_f32 v31, v68, v69
	v_lshlrev_b32_e32 v66, 16, v46
	v_and_b32_e32 v67, 0xffff0000, v46
	global_store_dword v10, v31, s[8:9]
	v_mul_f32_e32 v66, s11, v66
	v_mul_f32_e32 v67, s11, v67
	v_fma_f32 v68, v68, s10, v66
	v_fma_f32 v69, v69, s10, v67
	global_load_dword v46, v11, s[8:9]
	s_add_u32 s8, s8, 0x4000
	s_addc_u32 s9, s9, 0
	s_waitcnt vmcnt(62)
	v_readlane_b32 s10, v72, 13
	v_readlane_b32 s11, v29, 13
	v_cvt_pk_bf16_f32 v31, v68, v69
	v_lshlrev_b32_e32 v66, 16, v47
	v_and_b32_e32 v67, 0xffff0000, v47
	global_store_dword v10, v31, s[8:9]
	v_mul_f32_e32 v66, s11, v66
	v_mul_f32_e32 v67, s11, v67
	v_fma_f32 v68, v68, s10, v66
	v_fma_f32 v69, v69, s10, v67
	global_load_dword v47, v11, s[8:9]
	s_add_u32 s8, s8, 0x4000
	s_addc_u32 s9, s9, 0
	s_waitcnt vmcnt(62)
	v_readlane_b32 s10, v72, 14
	v_readlane_b32 s11, v29, 14
	v_cvt_pk_bf16_f32 v31, v68, v69
	v_lshlrev_b32_e32 v66, 16, v48
	v_and_b32_e32 v67, 0xffff0000, v48
	global_store_dword v10, v31, s[8:9]
	v_mul_f32_e32 v66, s11, v66
	v_mul_f32_e32 v67, s11, v67
	v_fma_f32 v68, v68, s10, v66
	v_fma_f32 v69, v69, s10, v67
	global_load_dword v48, v11, s[8:9]
	s_add_u32 s8, s8, 0x4000
	s_addc_u32 s9, s9, 0
	s_waitcnt vmcnt(62)
; __device__ __forceinline__ float bf2f(unsigned h) { return __uint_as_float(h << 16); }
; __device__ __forceinline__ unsigned pk2(float lo, float hi) { return pg8::pkbf(lo, hi); }
; __device__ __forceinline__ void mlstm_scan(bf16* DC, float* DN, float* SC, int wg, int G, int tid) {
;     ...
;                 const float mn = fmaxf(g[k] + m, am[k]), decay = expf(g[k] + m - mn), grow = expf(am[k] - mn);
;                 dc[(size_t)(i + k) * 4096] = pk2(C0, C1);
;                 C0 = decay * C0 + grow * bf2f(v[k] & 0xffffu); C1 = decay * C1 + grow * bf2f(v[k] >> 16);
	v_readlane_b32 s10, v72, 15
	v_readlane_b32 s11, v29, 15
	v_cvt_pk_bf16_f32 v31, v68, v69
	v_lshlrev_b32_e32 v66, 16, v49
	v_and_b32_e32 v67, 0xffff0000, v49
	global_store_dword v10, v31, s[8:9]
	v_mul_f32_e32 v66, s11, v66
	v_mul_f32_e32 v67, s11, v67
	v_fma_f32 v68, v68, s10, v66
	v_fma_f32 v69, v69, s10, v67
	global_load_dword v49, v11, s[8:9]
	s_add_u32 s8, s8, 0x4000
	s_addc_u32 s9, s9, 0
	s_waitcnt vmcnt(62)
	v_readlane_b32 s10, v72, 16
	v_readlane_b32 s11, v29, 16
	v_cvt_pk_bf16_f32 v31, v68, v69
	v_lshlrev_b32_e32 v66, 16, v50
	v_and_b32_e32 v67, 0xffff0000, v50
	global_store_dword v10, v31, s[8:9]
	v_mul_f32_e32 v66, s11, v66
	v_mul_f32_e32 v67, s11, v67
	v_fma_f32 v68, v68, s10, v66
	v_fma_f32 v69, v69, s10, v67
	global_load_dword v50, v11, s[8:9]
	s_add_u32 s8, s8, 0x4000
	s_addc_u32 s9, s9, 0
	s_waitcnt vmcnt(62)
	v_readlane_b32 s10, v72, 17
	v_readlane_b32 s11, v29, 17
	v_cvt_pk_bf16_f32 v31, v68, v69
	v_lshlrev_b32_e32 v66, 16, v51
	v_and_b32_e32 v67, 0xffff0000, v51
	global_store_dword v10, v31, s[8:9]
	v_mul_f32_e32 v66, s11, v66
	v_mul_f32_e32 v67, s11, v67
	v_fma_f32 v68, v68, s10, v66
	v_fma_f32 v69, v69, s10, v67
	global_load_dword v51, v11, s[8:9]
	s_add_u32 s8, s8, 0x4000
	s_addc_u32 s9, s9, 0
	s_waitcnt vmcnt(62)
	v_readlane_b32 s10, v72, 18
	v_readlane_b32 s11, v29, 18
	v_cvt_pk_bf16_f32 v31, v68, v69
	v_lshlrev_b32_e32 v66, 16, v52
	v_and_b32_e32 v67, 0xffff0000, v52
	global_store_dword v10, v31, s[8:9]
	v_mul_f32_e32 v66, s11, v66
	v_mul_f32_e32 v67, s11, v67
	v_fma_f32 v68, v68, s10, v66
	v_fma_f32 v69, v69, s10, v67
	global_load_dword v52, v11, s[8:9]
	s_add_u32 s8, s8, 0x4000
	s_addc_u32 s9, s9, 0
	s_waitcnt vmcnt(62)
	v_readlane_b32 s10, v72, 19
	v_readlane_b32 s11, v29, 19
	v_cvt_pk_bf16_f32 v31, v68, v69
	v_lshlrev_b32_e32 v66, 16, v53
	v_and_b32_e32 v67, 0xffff0000, v53
	global_store_dword v10, v31, s[8:9]
	v_mul_f32_e32 v66, s11, v66
	v_mul_f32_e32 v67, s11, v67
	v_fma_f32 v68, v68, s10, v66
	v_fma_f32 v69, v69, s10, v67
	global_load_dword v53, v11, s[8:9]
	s_add_u32 s8, s8, 0x4000
	s_addc_u32 s9, s9, 0
	s_waitcnt vmcnt(62)
	v_readlane_b32 s10, v72, 20
	v_readlane_b32 s11, v29, 20
	v_cvt_pk_bf16_f32 v31, v68, v69
	v_lshlrev_b32_e32 v66, 16, v54
	v_and_b32_e32 v67, 0xffff0000, v54
	global_store_dword v10, v31, s[8:9]
	v_mul_f32_e32 v66, s11, v66
	v_mul_f32_e32 v67, s11, v67
	v_fma_f32 v68, v68, s10, v66
	v_fma_f32 v69, v69, s10, v67
	global_load_dword v54, v11, s[8:9]
	s_add_u32 s8, s8, 0x4000
	s_addc_u32 s9, s9, 0
	s_waitcnt vmcnt(62)
	v_readlane_b32 s10, v72, 21
	v_readlane_b32 s11, v29, 21
	v_cvt_pk_bf16_f32 v31, v68, v69
	v_lshlrev_b32_e32 v66, 16, v55
	v_and_b32_e32 v67, 0xffff0000, v55
	global_store_dword v10, v31, s[8:9]
	v_mul_f32_e32 v66, s11, v66
	v_mul_f32_e32 v67, s11, v67
	v_fma_f32 v68, v68, s10, v66
	v_fma_f32 v69, v69, s10, v67
	global_load_dword v55, v11, s[8:9]
	s_add_u32 s8, s8, 0x4000
	s_addc_u32 s9, s9, 0
	s_waitcnt vmcnt(62)
	v_readlane_b32 s10, v72, 22
	v_readlane_b32 s11, v29, 22
	v_cvt_pk_bf16_f32 v31, v68, v69
	v_lshlrev_b32_e32 v66, 16, v56
	v_and_b32_e32 v67, 0xffff0000, v56
	global_store_dword v10, v31, s[8:9]
	v_mul_f32_e32 v66, s11, v66
	v_mul_f32_e32 v67, s11, v67
	v_fma_f32 v68, v68, s10, v66
	v_fma_f32 v69, v69, s10, v67
	global_load_dword v56, v11, s[8:9]
	s_add_u32 s8, s8, 0x4000
	s_addc_u32 s9, s9, 0
	s_waitcnt vmcnt(62)
	v_readlane_b32 s10, v72, 23
	v_readlane_b32 s11, v29, 23
	v_cvt_pk_bf16_f32 v31, v68, v69
	v_lshlrev_b32_e32 v66, 16, v57
	v_and_b32_e32 v67, 0xffff0000, v57
	global_store_dword v10, v31, s[8:9]
	v_mul_f32_e32 v66, s11, v66
	v_mul_f32_e32 v67, s11, v67
	v_fma_f32 v68, v68, s10, v66
	v_fma_f32 v69, v69, s10, v67
	global_load_dword v57, v11, s[8:9]
	s_add_u32 s8, s8, 0x4000
	s_addc_u32 s9, s9, 0
	s_waitcnt vmcnt(62)
	v_readlane_b32 s10, v72, 24
	v_readlane_b32 s11, v29, 24
	v_cvt_pk_bf16_f32 v31, v68, v69
	v_lshlrev_b32_e32 v66, 16, v58
	v_and_b32_e32 v67, 0xffff0000, v58
	global_store_dword v10, v31, s[8:9]
	v_mul_f32_e32 v66, s11, v66
	v_mul_f32_e32 v67, s11, v67
	v_fma_f32 v68, v68, s10, v66
	v_fma_f32 v69, v69, s10, v67
	global_load_dword v58, v11, s[8:9]
	s_add_u32 s8, s8, 0x4000
	s_addc_u32 s9, s9, 0
	s_waitcnt vmcnt(62)
	v_readlane_b32 s10, v72, 25
	v_readlane_b32 s11, v29, 25
	v_cvt_pk_bf16_f32 v31, v68, v69
	v_lshlrev_b32_e32 v66, 16, v59
	v_and_b32_e32 v67, 0xffff0000, v59
	global_store_dword v10, v31, s[8:9]
	v_mul_f32_e32 v66, s11, v66
	v_mul_f32_e32 v67, s11, v67
	v_fma_f32 v68, v68, s10, v66
	v_fma_f32 v69, v69, s10, v67
	global_load_dword v59, v11, s[8:9]
	s_add_u32 s8, s8, 0x4000
	s_addc_u32 s9, s9, 0
	s_waitcnt vmcnt(62)
	v_readlane_b32 s10, v72, 26
	v_readlane_b32 s11, v29, 26
	v_cvt_pk_bf16_f32 v31, v68, v69
	v_lshlrev_b32_e32 v66, 16, v60
	v_and_b32_e32 v67, 0xffff0000, v60
	global_store_dword v10, v31, s[8:9]
	v_mul_f32_e32 v66, s11, v66
	v_mul_f32_e32 v67, s11, v67
	v_fma_f32 v68, v68, s10, v66
	v_fma_f32 v69, v69, s10, v67
	global_load_dword v60, v11, s[8:9]
	s_add_u32 s8, s8, 0x4000
	s_addc_u32 s9, s9, 0
	s_waitcnt vmcnt(62)
	v_readlane_b32 s10, v72, 27
	v_readlane_b32 s11, v29, 27
	v_cvt_pk_bf16_f32 v31, v68, v69
	v_lshlrev_b32_e32 v66, 16, v61
	v_and_b32_e32 v67, 0xffff0000, v61
	global_store_dword v10, v31, s[8:9]
	v_mul_f32_e32 v66, s11, v66
	v_mul_f32_e32 v67, s11, v67
	v_fma_f32 v68, v68, s10, v66
	v_fma_f32 v69, v69, s10, v67
	global_load_dword v61, v11, s[8:9]
	s_add_u32 s8, s8, 0x4000
	s_addc_u32 s9, s9, 0
	s_waitcnt vmcnt(62)
; __device__ __forceinline__ float bf2f(unsigned h) { return __uint_as_float(h << 16); }
; __device__ __forceinline__ unsigned pk2(float lo, float hi) { return pg8::pkbf(lo, hi); }
; __device__ __forceinline__ void mlstm_scan(bf16* DC, float* DN, float* SC, int wg, int G, int tid) {
;     ...
;                 const float mn = fmaxf(g[k] + m, am[k]), decay = expf(g[k] + m - mn), grow = expf(am[k] - mn);
;                 dc[(size_t)(i + k) * 4096] = pk2(C0, C1);
;                 C0 = decay * C0 + grow * bf2f(v[k] & 0xffffu); C1 = decay * C1 + grow * bf2f(v[k] >> 16);
	v_readlane_b32 s10, v72, 28
	v_readlane_b32 s11, v29, 28
	v_cvt_pk_bf16_f32 v31, v68, v69
	v_lshlrev_b32_e32 v66, 16, v62
	v_and_b32_e32 v67, 0xffff0000, v62
	global_store_dword v10, v31, s[8:9]
	v_mul_f32_e32 v66, s11, v66
	v_mul_f32_e32 v67, s11, v67
	v_fma_f32 v68, v68, s10, v66
	v_fma_f32 v69, v69, s10, v67
	global_load_dword v62, v11, s[8:9]
	s_add_u32 s8, s8, 0x4000
	s_addc_u32 s9, s9, 0
	s_waitcnt vmcnt(62)
	v_readlane_b32 s10, v72, 29
	v_readlane_b32 s11, v29, 29
	v_cvt_pk_bf16_f32 v31, v68, v69
	v_lshlrev_b32_e32 v66, 16, v63
	v_and_b32_e32 v67, 0xffff0000, v63
	global_store_dword v10, v31, s[8:9]
	v_mul_f32_e32 v66, s11, v66
	v_mul_f32_e32 v67, s11, v67
	v_fma_f32 v68, v68, s10, v66
	v_fma_f32 v69, v69, s10, v67
	global_load_dword v63, v11, s[8:9]
	s_add_u32 s8, s8, 0x4000
	s_addc_u32 s9, s9, 0
	s_waitcnt vmcnt(62)
	v_readlane_b32 s10, v72, 30
	v_readlane_b32 s11, v29, 30
	v_cvt_pk_bf16_f32 v31, v68, v69
	v_lshlrev_b32_e32 v66, 16, v64
	v_and_b32_e32 v67, 0xffff0000, v64
	global_store_dword v10, v31, s[8:9]
	v_mul_f32_e32 v66, s11, v66
	v_mul_f32_e32 v67, s11, v67
	v_fma_f32 v68, v68, s10, v66
	v_fma_f32 v69, v69, s10, v67
	global_load_dword v64, v11, s[8:9]
	s_add_u32 s8, s8, 0x4000
	s_addc_u32 s9, s9, 0
	s_waitcnt vmcnt(62)
	v_readlane_b32 s10, v72, 31
	v_readlane_b32 s11, v29, 31
	v_cvt_pk_bf16_f32 v31, v68, v69
	v_lshlrev_b32_e32 v66, 16, v65
	v_and_b32_e32 v67, 0xffff0000, v65
	global_store_dword v10, v31, s[8:9]
	v_mul_f32_e32 v66, s11, v66
	v_mul_f32_e32 v67, s11, v67
	v_fma_f32 v68, v68, s10, v66
	v_fma_f32 v69, v69, s10, v67
	global_load_dword v65, v11, s[8:9]
	s_add_u32 s8, s8, 0x4000
	s_addc_u32 s9, s9, 0
	s_waitcnt vmcnt(62)
	v_readlane_b32 s10, v72, 32
	v_readlane_b32 s11, v29, 32
	v_cvt_pk_bf16_f32 v31, v68, v69
	v_lshlrev_b32_e32 v66, 16, v34
	v_and_b32_e32 v67, 0xffff0000, v34
	global_store_dword v10, v31, s[8:9]
	v_mul_f32_e32 v66, s11, v66
	v_mul_f32_e32 v67, s11, v67
	v_fma_f32 v68, v68, s10, v66
	v_fma_f32 v69, v69, s10, v67
	global_load_dword v34, v11, s[8:9]
	s_add_u32 s8, s8, 0x4000
	s_addc_u32 s9, s9, 0
	s_waitcnt vmcnt(62)
	v_readlane_b32 s10, v72, 33
	v_readlane_b32 s11, v29, 33
	v_cvt_pk_bf16_f32 v31, v68, v69
	v_lshlrev_b32_e32 v66, 16, v35
	v_and_b32_e32 v67, 0xffff0000, v35
	global_store_dword v10, v31, s[8:9]
	v_mul_f32_e32 v66, s11, v66
	v_mul_f32_e32 v67, s11, v67
	v_fma_f32 v68, v68, s10, v66
	v_fma_f32 v69, v69, s10, v67
	global_load_dword v35, v11, s[8:9]
	s_add_u32 s8, s8, 0x4000
	s_addc_u32 s9, s9, 0
	s_waitcnt vmcnt(62)
	v_readlane_b32 s10, v72, 34
	v_readlane_b32 s11, v29, 34
	v_cvt_pk_bf16_f32 v31, v68, v69
	v_lshlrev_b32_e32 v66, 16, v36
	v_and_b32_e32 v67, 0xffff0000, v36
	global_store_dword v10, v31, s[8:9]
	v_mul_f32_e32 v66, s11, v66
	v_mul_f32_e32 v67, s11, v67
	v_fma_f32 v68, v68, s10, v66
	v_fma_f32 v69, v69, s10, v67
	global_load_dword v36, v11, s[8:9]
	s_add_u32 s8, s8, 0x4000
	s_addc_u32 s9, s9, 0
	s_waitcnt vmcnt(62)
	v_readlane_b32 s10, v72, 35
	v_readlane_b32 s11, v29, 35
	v_cvt_pk_bf16_f32 v31, v68, v69
	v_lshlrev_b32_e32 v66, 16, v37
	v_and_b32_e32 v67, 0xffff0000, v37
	global_store_dword v10, v31, s[8:9]
	v_mul_f32_e32 v66, s11, v66
	v_mul_f32_e32 v67, s11, v67
	v_fma_f32 v68, v68, s10, v66
	v_fma_f32 v69, v69, s10, v67
	global_load_dword v37, v11, s[8:9]
	s_add_u32 s8, s8, 0x4000
	s_addc_u32 s9, s9, 0
	s_waitcnt vmcnt(62)
	v_readlane_b32 s10, v72, 36
	v_readlane_b32 s11, v29, 36
	v_cvt_pk_bf16_f32 v31, v68, v69
	v_lshlrev_b32_e32 v66, 16, v38
	v_and_b32_e32 v67, 0xffff0000, v38
	global_store_dword v10, v31, s[8:9]
	v_mul_f32_e32 v66, s11, v66
	v_mul_f32_e32 v67, s11, v67
	v_fma_f32 v68, v68, s10, v66
	v_fma_f32 v69, v69, s10, v67
	s_add_u32 s8, s8, 0x4000
	s_addc_u32 s9, s9, 0
	s_waitcnt vmcnt(61)
	v_readlane_b32 s10, v72, 37
	v_readlane_b32 s11, v29, 37
	v_cvt_pk_bf16_f32 v31, v68, v69
	v_lshlrev_b32_e32 v66, 16, v39
	v_and_b32_e32 v67, 0xffff0000, v39
	global_store_dword v10, v31, s[8:9]
	v_mul_f32_e32 v66, s11, v66
	v_mul_f32_e32 v67, s11, v67
	v_fma_f32 v68, v68, s10, v66
	v_fma_f32 v69, v69, s10, v67
	s_add_u32 s8, s8, 0x4000
	s_addc_u32 s9, s9, 0
	s_waitcnt vmcnt(60)
	v_readlane_b32 s10, v72, 38
	v_readlane_b32 s11, v29, 38
	v_cvt_pk_bf16_f32 v31, v68, v69
	v_lshlrev_b32_e32 v66, 16, v40
	v_and_b32_e32 v67, 0xffff0000, v40
	global_store_dword v10, v31, s[8:9]
	v_mul_f32_e32 v66, s11, v66
	v_mul_f32_e32 v67, s11, v67
	v_fma_f32 v68, v68, s10, v66
	v_fma_f32 v69, v69, s10, v67
	s_add_u32 s8, s8, 0x4000
	s_addc_u32 s9, s9, 0
	s_waitcnt vmcnt(59)
	v_readlane_b32 s10, v72, 39
	v_readlane_b32 s11, v29, 39
	v_cvt_pk_bf16_f32 v31, v68, v69
	v_lshlrev_b32_e32 v66, 16, v41
	v_and_b32_e32 v67, 0xffff0000, v41
	global_store_dword v10, v31, s[8:9]
	v_mul_f32_e32 v66, s11, v66
	v_mul_f32_e32 v67, s11, v67
	v_fma_f32 v68, v68, s10, v66
	v_fma_f32 v69, v69, s10, v67
	s_add_u32 s8, s8, 0x4000
	s_addc_u32 s9, s9, 0
	s_waitcnt vmcnt(58)
	v_readlane_b32 s10, v72, 40
	v_readlane_b32 s11, v29, 40
	v_cvt_pk_bf16_f32 v31, v68, v69
	v_lshlrev_b32_e32 v66, 16, v42
	v_and_b32_e32 v67, 0xffff0000, v42
	global_store_dword v10, v31, s[8:9]
	v_mul_f32_e32 v66, s11, v66
	v_mul_f32_e32 v67, s11, v67
	v_fma_f32 v68, v68, s10, v66
	v_fma_f32 v69, v69, s10, v67
	s_add_u32 s8, s8, 0x4000
	s_addc_u32 s9, s9, 0
	s_waitcnt vmcnt(57)
	v_readlane_b32 s10, v72, 41
	v_readlane_b32 s11, v29, 41
	v_cvt_pk_bf16_f32 v31, v68, v69
	v_lshlrev_b32_e32 v66, 16, v43
	v_and_b32_e32 v67, 0xffff0000, v43
	global_store_dword v10, v31, s[8:9]
	v_mul_f32_e32 v66, s11, v66
	v_mul_f32_e32 v67, s11, v67
	v_fma_f32 v68, v68, s10, v66
	v_fma_f32 v69, v69, s10, v67
	s_add_u32 s8, s8, 0x4000
	s_addc_u32 s9, s9, 0
	s_waitcnt vmcnt(56)
; __device__ __forceinline__ float bf2f(unsigned h) { return __uint_as_float(h << 16); }
; __device__ __forceinline__ unsigned pk2(float lo, float hi) { return pg8::pkbf(lo, hi); }
; __device__ __forceinline__ void mlstm_scan(bf16* DC, float* DN, float* SC, int wg, int G, int tid) {
;     ...
;                 const float mn = fmaxf(g[k] + m, am[k]), decay = expf(g[k] + m - mn), grow = expf(am[k] - mn);
;                 dc[(size_t)(i + k) * 4096] = pk2(C0, C1);
;                 C0 = decay * C0 + grow * bf2f(v[k] & 0xffffu); C1 = decay * C1 + grow * bf2f(v[k] >> 16);
	v_readlane_b32 s10, v72, 42
	v_readlane_b32 s11, v29, 42
	v_cvt_pk_bf16_f32 v31, v68, v69
	v_lshlrev_b32_e32 v66, 16, v44
	v_and_b32_e32 v67, 0xffff0000, v44
	global_store_dword v10, v31, s[8:9]
	v_mul_f32_e32 v66, s11, v66
	v_mul_f32_e32 v67, s11, v67
	v_fma_f32 v68, v68, s10, v66
	v_fma_f32 v69, v69, s10, v67
	s_add_u32 s8, s8, 0x4000
	s_addc_u32 s9, s9, 0
	s_waitcnt vmcnt(55)
	v_readlane_b32 s10, v72, 43
	v_readlane_b32 s11, v29, 43
	v_cvt_pk_bf16_f32 v31, v68, v69
	v_lshlrev_b32_e32 v66, 16, v45
	v_and_b32_e32 v67, 0xffff0000, v45
	global_store_dword v10, v31, s[8:9]
	v_mul_f32_e32 v66, s11, v66
	v_mul_f32_e32 v67, s11, v67
	v_fma_f32 v68, v68, s10, v66
	v_fma_f32 v69, v69, s10, v67
	s_add_u32 s8, s8, 0x4000
	s_addc_u32 s9, s9, 0
	s_waitcnt vmcnt(54)
	v_readlane_b32 s10, v72, 44
	v_readlane_b32 s11, v29, 44
	v_cvt_pk_bf16_f32 v31, v68, v69
	v_lshlrev_b32_e32 v66, 16, v46
	v_and_b32_e32 v67, 0xffff0000, v46
	global_store_dword v10, v31, s[8:9]
	v_mul_f32_e32 v66, s11, v66
	v_mul_f32_e32 v67, s11, v67
	v_fma_f32 v68, v68, s10, v66
	v_fma_f32 v69, v69, s10, v67
	s_add_u32 s8, s8, 0x4000
	s_addc_u32 s9, s9, 0
	s_waitcnt vmcnt(53)
	v_readlane_b32 s10, v72, 45
	v_readlane_b32 s11, v29, 45
	v_cvt_pk_bf16_f32 v31, v68, v69
	v_lshlrev_b32_e32 v66, 16, v47
	v_and_b32_e32 v67, 0xffff0000, v47
	global_store_dword v10, v31, s[8:9]
	v_mul_f32_e32 v66, s11, v66
	v_mul_f32_e32 v67, s11, v67
	v_fma_f32 v68, v68, s10, v66
	v_fma_f32 v69, v69, s10, v67
	s_add_u32 s8, s8, 0x4000
	s_addc_u32 s9, s9, 0
	s_waitcnt vmcnt(52)
	v_readlane_b32 s10, v72, 46
	v_readlane_b32 s11, v29, 46
	v_cvt_pk_bf16_f32 v31, v68, v69
	v_lshlrev_b32_e32 v66, 16, v48
	v_and_b32_e32 v67, 0xffff0000, v48
	global_store_dword v10, v31, s[8:9]
	v_mul_f32_e32 v66, s11, v66
	v_mul_f32_e32 v67, s11, v67
	v_fma_f32 v68, v68, s10, v66
	v_fma_f32 v69, v69, s10, v67
	s_add_u32 s8, s8, 0x4000
	s_addc_u32 s9, s9, 0
	s_waitcnt vmcnt(51)
	v_readlane_b32 s10, v72, 47
	v_readlane_b32 s11, v29, 47
	v_cvt_pk_bf16_f32 v31, v68, v69
	v_lshlrev_b32_e32 v66, 16, v49
	v_and_b32_e32 v67, 0xffff0000, v49
	global_store_dword v10, v31, s[8:9]
	v_mul_f32_e32 v66, s11, v66
	v_mul_f32_e32 v67, s11, v67
	v_fma_f32 v68, v68, s10, v66
	v_fma_f32 v69, v69, s10, v67
	s_add_u32 s8, s8, 0x4000
	s_addc_u32 s9, s9, 0
	s_waitcnt vmcnt(50)
	v_readlane_b32 s10, v72, 48
	v_readlane_b32 s11, v29, 48
	v_cvt_pk_bf16_f32 v31, v68, v69
	v_lshlrev_b32_e32 v66, 16, v50
	v_and_b32_e32 v67, 0xffff0000, v50
	global_store_dword v10, v31, s[8:9]
	v_mul_f32_e32 v66, s11, v66
	v_mul_f32_e32 v67, s11, v67
	v_fma_f32 v68, v68, s10, v66
	v_fma_f32 v69, v69, s10, v67
	s_add_u32 s8, s8, 0x4000
	s_addc_u32 s9, s9, 0
	s_waitcnt vmcnt(49)
	v_readlane_b32 s10, v72, 49
	v_readlane_b32 s11, v29, 49
	v_cvt_pk_bf16_f32 v31, v68, v69
	v_lshlrev_b32_e32 v66, 16, v51
	v_and_b32_e32 v67, 0xffff0000, v51
	global_store_dword v10, v31, s[8:9]
	v_mul_f32_e32 v66, s11, v66
	v_mul_f32_e32 v67, s11, v67
	v_fma_f32 v68, v68, s10, v66
	v_fma_f32 v69, v69, s10, v67
	s_add_u32 s8, s8, 0x4000
	s_addc_u32 s9, s9, 0
	s_waitcnt vmcnt(48)
	v_readlane_b32 s10, v72, 50
	v_readlane_b32 s11, v29, 50
	v_cvt_pk_bf16_f32 v31, v68, v69
	v_lshlrev_b32_e32 v66, 16, v52
	v_and_b32_e32 v67, 0xffff0000, v52
	global_store_dword v10, v31, s[8:9]
	v_mul_f32_e32 v66, s11, v66
	v_mul_f32_e32 v67, s11, v67
	v_fma_f32 v68, v68, s10, v66
	v_fma_f32 v69, v69, s10, v67
	s_add_u32 s8, s8, 0x4000
	s_addc_u32 s9, s9, 0
	s_waitcnt vmcnt(47)
	v_readlane_b32 s10, v72, 51
	v_readlane_b32 s11, v29, 51
	v_cvt_pk_bf16_f32 v31, v68, v69
	v_lshlrev_b32_e32 v66, 16, v53
	v_and_b32_e32 v67, 0xffff0000, v53
	global_store_dword v10, v31, s[8:9]
	v_mul_f32_e32 v66, s11, v66
	v_mul_f32_e32 v67, s11, v67
	v_fma_f32 v68, v68, s10, v66
	v_fma_f32 v69, v69, s10, v67
	s_add_u32 s8, s8, 0x4000
	s_addc_u32 s9, s9, 0
	s_waitcnt vmcnt(46)
	v_readlane_b32 s10, v72, 52
	v_readlane_b32 s11, v29, 52
	v_cvt_pk_bf16_f32 v31, v68, v69
	v_lshlrev_b32_e32 v66, 16, v54
	v_and_b32_e32 v67, 0xffff0000, v54
	global_store_dword v10, v31, s[8:9]
	v_mul_f32_e32 v66, s11, v66
	v_mul_f32_e32 v67, s11, v67
	v_fma_f32 v68, v68, s10, v66
	v_fma_f32 v69, v69, s10, v67
	s_add_u32 s8, s8, 0x4000
	s_addc_u32 s9, s9, 0
	s_waitcnt vmcnt(45)
	v_readlane_b32 s10, v72, 53
	v_readlane_b32 s11, v29, 53
	v_cvt_pk_bf16_f32 v31, v68, v69
	v_lshlrev_b32_e32 v66, 16, v55
	v_and_b32_e32 v67, 0xffff0000, v55
	global_store_dword v10, v31, s[8:9]
	v_mul_f32_e32 v66, s11, v66
	v_mul_f32_e32 v67, s11, v67
	v_fma_f32 v68, v68, s10, v66
	v_fma_f32 v69, v69, s10, v67
	s_add_u32 s8, s8, 0x4000
	s_addc_u32 s9, s9, 0
	s_waitcnt vmcnt(44)
	v_readlane_b32 s10, v72, 54
	v_readlane_b32 s11, v29, 54
	v_cvt_pk_bf16_f32 v31, v68, v69
	v_lshlrev_b32_e32 v66, 16, v56
	v_and_b32_e32 v67, 0xffff0000, v56
	global_store_dword v10, v31, s[8:9]
	v_mul_f32_e32 v66, s11, v66
	v_mul_f32_e32 v67, s11, v67
	v_fma_f32 v68, v68, s10, v66
	v_fma_f32 v69, v69, s10, v67
	s_add_u32 s8, s8, 0x4000
	s_addc_u32 s9, s9, 0
	s_waitcnt vmcnt(43)
	v_readlane_b32 s10, v72, 55
	v_readlane_b32 s11, v29, 55
	v_cvt_pk_bf16_f32 v31, v68, v69
	v_lshlrev_b32_e32 v66, 16, v57
	v_and_b32_e32 v67, 0xffff0000, v57
	global_store_dword v10, v31, s[8:9]
	v_mul_f32_e32 v66, s11, v66
	v_mul_f32_e32 v67, s11, v67
	v_fma_f32 v68, v68, s10, v66
	v_fma_f32 v69, v69, s10, v67
	s_add_u32 s8, s8, 0x4000
	s_addc_u32 s9, s9, 0
	s_waitcnt vmcnt(42)
	v_readlane_b32 s10, v72, 56
	v_readlane_b32 s11, v29, 56
	v_cvt_pk_bf16_f32 v31, v68, v69
	v_lshlrev_b32_e32 v66, 16, v58
	v_and_b32_e32 v67, 0xffff0000, v58
	global_store_dword v10, v31, s[8:9]
	v_mul_f32_e32 v66, s11, v66
	v_mul_f32_e32 v67, s11, v67
	v_fma_f32 v68, v68, s10, v66
	v_fma_f32 v69, v69, s10, v67
	s_add_u32 s8, s8, 0x4000
	s_addc_u32 s9, s9, 0
	s_waitcnt vmcnt(41)
; __device__ __forceinline__ float bf2f(unsigned h) { return __uint_as_float(h << 16); }
; __device__ __forceinline__ unsigned pk2(float lo, float hi) { return pg8::pkbf(lo, hi); }
; __device__ __forceinline__ void mlstm_scan(bf16* DC, float* DN, float* SC, int wg, int G, int tid) {
;     ...
;             for (int k = 0; k < 12; ++k) {
;                 const float mn = fmaxf(g[k] + m, am[k]), decay = expf(g[k] + m - mn), grow = expf(am[k] - mn);
;                 dc[(size_t)(i + k) * 4096] = pk2(C0, C1);
;                 C0 = decay * C0 + grow * bf2f(v[k] & 0xffffu); C1 = decay * C1 + grow * bf2f(v[k] >> 16);
;                 if (has_n) { dn[(i + k) * 64] = n; n = decay * n + grow * nv[k]; }
;                 if (rec_m) sc[(i + k) * 4 + 2] = m;
	v_readlane_b32 s10, v72, 57
	v_readlane_b32 s11, v29, 57
	v_cvt_pk_bf16_f32 v31, v68, v69
	v_lshlrev_b32_e32 v66, 16, v59
	v_and_b32_e32 v67, 0xffff0000, v59
	global_store_dword v10, v31, s[8:9]
	v_mul_f32_e32 v66, s11, v66
	v_mul_f32_e32 v67, s11, v67
	v_fma_f32 v68, v68, s10, v66
	v_fma_f32 v69, v69, s10, v67
	s_add_u32 s8, s8, 0x4000
	s_addc_u32 s9, s9, 0
	s_waitcnt vmcnt(40)
	v_readlane_b32 s10, v72, 58
	v_readlane_b32 s11, v29, 58
	v_cvt_pk_bf16_f32 v31, v68, v69
	v_lshlrev_b32_e32 v66, 16, v60
	v_and_b32_e32 v67, 0xffff0000, v60
	global_store_dword v10, v31, s[8:9]
	v_mul_f32_e32 v66, s11, v66
	v_mul_f32_e32 v67, s11, v67
	v_fma_f32 v68, v68, s10, v66
	v_fma_f32 v69, v69, s10, v67
	s_add_u32 s8, s8, 0x4000
	s_addc_u32 s9, s9, 0
	s_waitcnt vmcnt(39)
	v_readlane_b32 s10, v72, 59
	v_readlane_b32 s11, v29, 59
	v_cvt_pk_bf16_f32 v31, v68, v69
	v_lshlrev_b32_e32 v66, 16, v61
	v_and_b32_e32 v67, 0xffff0000, v61
	global_store_dword v10, v31, s[8:9]
	v_mul_f32_e32 v66, s11, v66
	v_mul_f32_e32 v67, s11, v67
	v_fma_f32 v68, v68, s10, v66
	v_fma_f32 v69, v69, s10, v67
	s_add_u32 s8, s8, 0x4000
	s_addc_u32 s9, s9, 0
	s_waitcnt vmcnt(38)
	v_readlane_b32 s10, v72, 60
	v_readlane_b32 s11, v29, 60
	v_cvt_pk_bf16_f32 v31, v68, v69
	v_lshlrev_b32_e32 v66, 16, v62
	v_and_b32_e32 v67, 0xffff0000, v62
	global_store_dword v10, v31, s[8:9]
	v_mul_f32_e32 v66, s11, v66
	v_mul_f32_e32 v67, s11, v67
	v_fma_f32 v68, v68, s10, v66
	v_fma_f32 v69, v69, s10, v67
	s_add_u32 s8, s8, 0x4000
	s_addc_u32 s9, s9, 0
	s_waitcnt vmcnt(37)
	v_readlane_b32 s10, v72, 61
	v_readlane_b32 s11, v29, 61
	v_cvt_pk_bf16_f32 v31, v68, v69
	v_lshlrev_b32_e32 v66, 16, v63
	v_and_b32_e32 v67, 0xffff0000, v63
	global_store_dword v10, v31, s[8:9]
	v_mul_f32_e32 v66, s11, v66
	v_mul_f32_e32 v67, s11, v67
	v_fma_f32 v68, v68, s10, v66
	v_fma_f32 v69, v69, s10, v67
	s_add_u32 s8, s8, 0x4000
	s_addc_u32 s9, s9, 0
	s_waitcnt vmcnt(36)
	v_readlane_b32 s10, v72, 62
	v_readlane_b32 s11, v29, 62
	v_cvt_pk_bf16_f32 v31, v68, v69
	v_lshlrev_b32_e32 v66, 16, v64
	v_and_b32_e32 v67, 0xffff0000, v64
	global_store_dword v10, v31, s[8:9]
	v_mul_f32_e32 v66, s11, v66
	v_mul_f32_e32 v67, s11, v67
	v_fma_f32 v68, v68, s10, v66
	v_fma_f32 v69, v69, s10, v67
	s_add_u32 s8, s8, 0x4000
	s_addc_u32 s9, s9, 0
	s_waitcnt vmcnt(35)
	v_readlane_b32 s10, v72, 63
	v_readlane_b32 s11, v29, 63
	v_cvt_pk_bf16_f32 v31, v68, v69
	v_lshlrev_b32_e32 v66, 16, v65
	v_and_b32_e32 v67, 0xffff0000, v65
	global_store_dword v10, v31, s[8:9]
	v_mul_f32_e32 v66, s11, v66
	v_mul_f32_e32 v67, s11, v67
	v_fma_f32 v68, v68, s10, v66
	v_fma_f32 v69, v69, s10, v67
	s_add_u32 s8, s8, 0x4000
	s_addc_u32 s9, s9, 0
	s_waitcnt vmcnt(34)
	v_readlane_b32 s10, v73, 0
	v_readlane_b32 s11, v30, 0
	v_cvt_pk_bf16_f32 v31, v68, v69
	v_lshlrev_b32_e32 v66, 16, v34
	v_and_b32_e32 v67, 0xffff0000, v34
	global_store_dword v10, v31, s[8:9]
	v_mul_f32_e32 v66, s11, v66
	v_mul_f32_e32 v67, s11, v67
	v_fma_f32 v68, v68, s10, v66
	v_fma_f32 v69, v69, s10, v67
	s_add_u32 s8, s8, 0x4000
	s_addc_u32 s9, s9, 0
	s_waitcnt vmcnt(33)
	v_readlane_b32 s10, v73, 1
	v_readlane_b32 s11, v30, 1
	v_cvt_pk_bf16_f32 v31, v68, v69
	v_lshlrev_b32_e32 v66, 16, v35
	v_and_b32_e32 v67, 0xffff0000, v35
	global_store_dword v10, v31, s[8:9]
	v_mul_f32_e32 v66, s11, v66
	v_mul_f32_e32 v67, s11, v67
	v_fma_f32 v68, v68, s10, v66
	v_fma_f32 v69, v69, s10, v67
	s_add_u32 s8, s8, 0x4000
	s_addc_u32 s9, s9, 0
	s_waitcnt vmcnt(32)
	v_readlane_b32 s10, v73, 2
	v_readlane_b32 s11, v30, 2
	v_cvt_pk_bf16_f32 v31, v68, v69
	v_lshlrev_b32_e32 v66, 16, v36
	v_and_b32_e32 v67, 0xffff0000, v36
	global_store_dword v10, v31, s[8:9]
	v_mul_f32_e32 v66, s11, v66
	v_mul_f32_e32 v67, s11, v67
	v_fma_f32 v68, v68, s10, v66
	v_fma_f32 v69, v69, s10, v67
	s_add_u32 s8, s8, 0x4000
	s_addc_u32 s9, s9, 0
	s_waitcnt vmcnt(31)
	v_readlane_b32 s10, v73, 3
	v_readlane_b32 s11, v30, 3
	v_cvt_pk_bf16_f32 v31, v68, v69
	v_lshlrev_b32_e32 v66, 16, v37
	v_and_b32_e32 v67, 0xffff0000, v37
	global_store_dword v10, v31, s[8:9]
	v_mul_f32_e32 v66, s11, v66
	v_mul_f32_e32 v67, s11, v67
	v_fma_f32 v68, v68, s10, v66
	v_fma_f32 v69, v69, s10, v67
	s_add_u32 s8, s8, 0x4000
	s_addc_u32 s9, s9, 0
	s_and_b64 vcc, exec, s[6:7]
	s_cbranch_vccz .Lscan_unit_done
; __device__ __forceinline__ float bf2f(unsigned h) { return __uint_as_float(h << 16); }
; __device__ __forceinline__ unsigned pk2(float lo, float hi) { return pg8::pkbf(lo, hi); }
; __device__ __forceinline__ void mlstm_scan(bf16* DC, float* DN, float* SC, int wg, int G, int tid) {
;     ...
;             for (int k = 0; k < 12; ++k) { v[k] = dc[(size_t)(i + k) * 4096]; g[k] = sc[(i + k) * 4]; am[k] = sc[(i + k) * 4 + 1]; nv[k] = has_n ? dn[(i + k) * 64] : 0.f; }
; #pragma unroll
;             for (int k = 0; k < 12; ++k) {
;                 const float mn = fmaxf(g[k] + m, am[k]), decay = expf(g[k] + m - mn), grow = expf(am[k] - mn);
;                 dc[(size_t)(i + k) * 4096] = pk2(C0, C1);
;                 C0 = decay * C0 + grow * bf2f(v[k] & 0xffffu); C1 = decay * C1 + grow * bf2f(v[k] >> 16);
;                 if (has_n) { dn[(i + k) * 64] = n; n = decay * n + grow * nv[k]; }
	s_add_u32 s10, s16, 0x1000
	s_addc_u32 s11, s17, 0
	global_load_dword v34, v12, s[16:17] offset:0
	global_load_dword v35, v12, s[16:17] offset:256
	global_load_dword v36, v12, s[16:17] offset:512
	global_load_dword v37, v12, s[16:17] offset:768
	global_load_dword v38, v12, s[16:17] offset:1024
	global_load_dword v39, v12, s[16:17] offset:1280
	global_load_dword v40, v12, s[16:17] offset:1536
	global_load_dword v41, v12, s[16:17] offset:1792
	global_load_dword v42, v12, s[16:17] offset:2048
	global_load_dword v43, v12, s[16:17] offset:2304
	global_load_dword v44, v12, s[16:17] offset:2560
	global_load_dword v45, v12, s[16:17] offset:2816
	global_load_dword v46, v12, s[16:17] offset:3072
	global_load_dword v47, v12, s[16:17] offset:3328
	global_load_dword v48, v12, s[16:17] offset:3584
	global_load_dword v49, v12, s[16:17] offset:3840
	global_load_dword v50, v12, s[10:11] offset:0
	global_load_dword v51, v12, s[10:11] offset:256
	global_load_dword v52, v12, s[10:11] offset:512
	global_load_dword v53, v12, s[10:11] offset:768
	global_load_dword v54, v12, s[10:11] offset:1024
	global_load_dword v55, v12, s[10:11] offset:1280
	global_load_dword v56, v12, s[10:11] offset:1536
	global_load_dword v57, v12, s[10:11] offset:1792
	global_load_dword v58, v12, s[10:11] offset:2048
	global_load_dword v59, v12, s[10:11] offset:2304
	global_load_dword v60, v12, s[10:11] offset:2560
	global_load_dword v61, v12, s[10:11] offset:2816
	global_load_dword v62, v12, s[10:11] offset:3072
	global_load_dword v63, v12, s[10:11] offset:3328
	global_load_dword v64, v12, s[10:11] offset:3584
	global_load_dword v65, v12, s[10:11] offset:3840
	s_waitcnt vmcnt(31)
	v_readlane_b32 s10, v71, 0
	v_readlane_b32 s11, v28, 0
	global_store_dword v12, v70, s[16:17]
	s_nop 0
	v_mul_f32_e32 v66, s10, v70
	v_mul_f32_e32 v67, s11, v34
	v_add_f32_e32 v70, v66, v67
	global_load_dword v34, v13, s[16:17]
	s_add_u32 s16, s16, 0x100
	s_addc_u32 s17, s17, 0
	s_waitcnt vmcnt(32)
	v_readlane_b32 s10, v71, 1
	v_readlane_b32 s11, v28, 1
	global_store_dword v12, v70, s[16:17]
	s_nop 0
	v_mul_f32_e32 v66, s10, v70
	v_mul_f32_e32 v67, s11, v35
	v_add_f32_e32 v70, v66, v67
	global_load_dword v35, v13, s[16:17]
	s_add_u32 s16, s16, 0x100
	s_addc_u32 s17, s17, 0
	s_waitcnt vmcnt(33)
	v_readlane_b32 s10, v71, 2
	v_readlane_b32 s11, v28, 2
	global_store_dword v12, v70, s[16:17]
	s_nop 0
	v_mul_f32_e32 v66, s10, v70
	v_mul_f32_e32 v67, s11, v36
	v_add_f32_e32 v70, v66, v67
	global_load_dword v36, v13, s[16:17]
	s_add_u32 s16, s16, 0x100
	s_addc_u32 s17, s17, 0
	s_waitcnt vmcnt(34)
	v_readlane_b32 s10, v71, 3
	v_readlane_b32 s11, v28, 3
	global_store_dword v12, v70, s[16:17]
	s_nop 0
	v_mul_f32_e32 v66, s10, v70
	v_mul_f32_e32 v67, s11, v37
	v_add_f32_e32 v70, v66, v67
	global_load_dword v37, v13, s[16:17]
	s_add_u32 s16, s16, 0x100
	s_addc_u32 s17, s17, 0
	s_waitcnt vmcnt(35)
	v_readlane_b32 s10, v71, 4
	v_readlane_b32 s11, v28, 4
	global_store_dword v12, v70, s[16:17]
	s_nop 0
	v_mul_f32_e32 v66, s10, v70
	v_mul_f32_e32 v67, s11, v38
	v_add_f32_e32 v70, v66, v67
	global_load_dword v38, v13, s[16:17]
	s_add_u32 s16, s16, 0x100
	s_addc_u32 s17, s17, 0
	s_waitcnt vmcnt(36)
	v_readlane_b32 s10, v71, 5
	v_readlane_b32 s11, v28, 5
	global_store_dword v12, v70, s[16:17]
	s_nop 0
	v_mul_f32_e32 v66, s10, v70
	v_mul_f32_e32 v67, s11, v39
	v_add_f32_e32 v70, v66, v67
	global_load_dword v39, v13, s[16:17]
	s_add_u32 s16, s16, 0x100
	s_addc_u32 s17, s17, 0
	s_waitcnt vmcnt(37)
	v_readlane_b32 s10, v71, 6
	v_readlane_b32 s11, v28, 6
	global_store_dword v12, v70, s[16:17]
	s_nop 0
	v_mul_f32_e32 v66, s10, v70
	v_mul_f32_e32 v67, s11, v40
	v_add_f32_e32 v70, v66, v67
	global_load_dword v40, v13, s[16:17]
	s_add_u32 s16, s16, 0x100
	s_addc_u32 s17, s17, 0
	s_waitcnt vmcnt(38)
	v_readlane_b32 s10, v71, 7
	v_readlane_b32 s11, v28, 7
	global_store_dword v12, v70, s[16:17]
	s_nop 0
	v_mul_f32_e32 v66, s10, v70
	v_mul_f32_e32 v67, s11, v41
	v_add_f32_e32 v70, v66, v67
	global_load_dword v41, v13, s[16:17]
	s_add_u32 s16, s16, 0x100
	s_addc_u32 s17, s17, 0
	s_waitcnt vmcnt(39)
	v_readlane_b32 s10, v71, 8
	v_readlane_b32 s11, v28, 8
	global_store_dword v12, v70, s[16:17]
	s_nop 0
	v_mul_f32_e32 v66, s10, v70
	v_mul_f32_e32 v67, s11, v42
	v_add_f32_e32 v70, v66, v67
	global_load_dword v42, v13, s[16:17]
	s_add_u32 s16, s16, 0x100
	s_addc_u32 s17, s17, 0
	s_waitcnt vmcnt(40)
	v_readlane_b32 s10, v71, 9
	v_readlane_b32 s11, v28, 9
	global_store_dword v12, v70, s[16:17]
	s_nop 0
	v_mul_f32_e32 v66, s10, v70
	v_mul_f32_e32 v67, s11, v43
	v_add_f32_e32 v70, v66, v67
	global_load_dword v43, v13, s[16:17]
	s_add_u32 s16, s16, 0x100
	s_addc_u32 s17, s17, 0
	s_waitcnt vmcnt(41)
	v_readlane_b32 s10, v71, 10
	v_readlane_b32 s11, v28, 10
	global_store_dword v12, v70, s[16:17]
	s_nop 0
	v_mul_f32_e32 v66, s10, v70
	v_mul_f32_e32 v67, s11, v44
	v_add_f32_e32 v70, v66, v67
	global_load_dword v44, v13, s[16:17]
	s_add_u32 s16, s16, 0x100
	s_addc_u32 s17, s17, 0
	s_waitcnt vmcnt(42)
	v_readlane_b32 s10, v71, 11
	v_readlane_b32 s11, v28, 11
	global_store_dword v12, v70, s[16:17]
	s_nop 0
	v_mul_f32_e32 v66, s10, v70
	v_mul_f32_e32 v67, s11, v45
	v_add_f32_e32 v70, v66, v67
	global_load_dword v45, v13, s[16:17]
	s_add_u32 s16, s16, 0x100
	s_addc_u32 s17, s17, 0
	s_waitcnt vmcnt(43)
	v_readlane_b32 s10, v71, 12
	v_readlane_b32 s11, v28, 12
	global_store_dword v12, v70, s[16:17]
	s_nop 0
	v_mul_f32_e32 v66, s10, v70
	v_mul_f32_e32 v67, s11, v46
	v_add_f32_e32 v70, v66, v67
	global_load_dword v46, v13, s[16:17]
	s_add_u32 s16, s16, 0x100
	s_addc_u32 s17, s17, 0
	s_waitcnt vmcnt(44)
; __device__ __forceinline__ void mlstm_scan(bf16* DC, float* DN, float* SC, int wg, int G, int tid) {
;     ...
;                 if (has_n) { dn[(i + k) * 64] = n; n = decay * n + grow * nv[k]; }
	v_readlane_b32 s10, v71, 13
	v_readlane_b32 s11, v28, 13
	global_store_dword v12, v70, s[16:17]
	s_nop 0
	v_mul_f32_e32 v66, s10, v70
	v_mul_f32_e32 v67, s11, v47
	v_add_f32_e32 v70, v66, v67
	global_load_dword v47, v13, s[16:17]
	s_add_u32 s16, s16, 0x100
	s_addc_u32 s17, s17, 0
	s_waitcnt vmcnt(45)
	v_readlane_b32 s10, v71, 14
	v_readlane_b32 s11, v28, 14
	global_store_dword v12, v70, s[16:17]
	s_nop 0
	v_mul_f32_e32 v66, s10, v70
	v_mul_f32_e32 v67, s11, v48
	v_add_f32_e32 v70, v66, v67
	global_load_dword v48, v13, s[16:17]
	s_add_u32 s16, s16, 0x100
	s_addc_u32 s17, s17, 0
	s_waitcnt vmcnt(46)
	v_readlane_b32 s10, v71, 15
	v_readlane_b32 s11, v28, 15
	global_store_dword v12, v70, s[16:17]
	s_nop 0
	v_mul_f32_e32 v66, s10, v70
	v_mul_f32_e32 v67, s11, v49
	v_add_f32_e32 v70, v66, v67
	global_load_dword v49, v13, s[16:17]
	s_add_u32 s16, s16, 0x100
	s_addc_u32 s17, s17, 0
	s_waitcnt vmcnt(47)
	v_readlane_b32 s10, v71, 16
	v_readlane_b32 s11, v28, 16
	global_store_dword v12, v70, s[16:17]
	s_nop 0
	v_mul_f32_e32 v66, s10, v70
	v_mul_f32_e32 v67, s11, v50
	v_add_f32_e32 v70, v66, v67
	global_load_dword v50, v13, s[16:17]
	s_add_u32 s16, s16, 0x100
	s_addc_u32 s17, s17, 0
	s_waitcnt vmcnt(48)
	v_readlane_b32 s10, v71, 17
	v_readlane_b32 s11, v28, 17
	global_store_dword v12, v70, s[16:17]
	s_nop 0
	v_mul_f32_e32 v66, s10, v70
	v_mul_f32_e32 v67, s11, v51
	v_add_f32_e32 v70, v66, v67
	global_load_dword v51, v13, s[16:17]
	s_add_u32 s16, s16, 0x100
	s_addc_u32 s17, s17, 0
	s_waitcnt vmcnt(49)
	v_readlane_b32 s10, v71, 18
	v_readlane_b32 s11, v28, 18
	global_store_dword v12, v70, s[16:17]
	s_nop 0
	v_mul_f32_e32 v66, s10, v70
	v_mul_f32_e32 v67, s11, v52
	v_add_f32_e32 v70, v66, v67
	global_load_dword v52, v13, s[16:17]
	s_add_u32 s16, s16, 0x100
	s_addc_u32 s17, s17, 0
	s_waitcnt vmcnt(50)
	v_readlane_b32 s10, v71, 19
	v_readlane_b32 s11, v28, 19
	global_store_dword v12, v70, s[16:17]
	s_nop 0
	v_mul_f32_e32 v66, s10, v70
	v_mul_f32_e32 v67, s11, v53
	v_add_f32_e32 v70, v66, v67
	global_load_dword v53, v13, s[16:17]
	s_add_u32 s16, s16, 0x100
	s_addc_u32 s17, s17, 0
	s_waitcnt vmcnt(51)
	v_readlane_b32 s10, v71, 20
	v_readlane_b32 s11, v28, 20
	global_store_dword v12, v70, s[16:17]
	s_nop 0
	v_mul_f32_e32 v66, s10, v70
	v_mul_f32_e32 v67, s11, v54
	v_add_f32_e32 v70, v66, v67
	global_load_dword v54, v13, s[16:17]
	s_add_u32 s16, s16, 0x100
	s_addc_u32 s17, s17, 0
	s_waitcnt vmcnt(52)
	v_readlane_b32 s10, v71, 21
	v_readlane_b32 s11, v28, 21
	global_store_dword v12, v70, s[16:17]
	s_nop 0
	v_mul_f32_e32 v66, s10, v70
	v_mul_f32_e32 v67, s11, v55
	v_add_f32_e32 v70, v66, v67
	global_load_dword v55, v13, s[16:17]
	s_add_u32 s16, s16, 0x100
	s_addc_u32 s17, s17, 0
	s_waitcnt vmcnt(53)
	v_readlane_b32 s10, v71, 22
	v_readlane_b32 s11, v28, 22
	global_store_dword v12, v70, s[16:17]
	s_nop 0
	v_mul_f32_e32 v66, s10, v70
	v_mul_f32_e32 v67, s11, v56
	v_add_f32_e32 v70, v66, v67
	global_load_dword v56, v13, s[16:17]
	s_add_u32 s16, s16, 0x100
	s_addc_u32 s17, s17, 0
	s_waitcnt vmcnt(54)
	v_readlane_b32 s10, v71, 23
	v_readlane_b32 s11, v28, 23
	global_store_dword v12, v70, s[16:17]
	s_nop 0
	v_mul_f32_e32 v66, s10, v70
	v_mul_f32_e32 v67, s11, v57
	v_add_f32_e32 v70, v66, v67
	global_load_dword v57, v13, s[16:17]
	s_add_u32 s16, s16, 0x100
	s_addc_u32 s17, s17, 0
	s_waitcnt vmcnt(55)
	v_readlane_b32 s10, v71, 24
	v_readlane_b32 s11, v28, 24
	global_store_dword v12, v70, s[16:17]
	s_nop 0
	v_mul_f32_e32 v66, s10, v70
	v_mul_f32_e32 v67, s11, v58
	v_add_f32_e32 v70, v66, v67
	global_load_dword v58, v13, s[16:17]
	s_add_u32 s16, s16, 0x100
	s_addc_u32 s17, s17, 0
	s_waitcnt vmcnt(56)
	v_readlane_b32 s10, v71, 25
	v_readlane_b32 s11, v28, 25
	global_store_dword v12, v70, s[16:17]
	s_nop 0
	v_mul_f32_e32 v66, s10, v70
	v_mul_f32_e32 v67, s11, v59
	v_add_f32_e32 v70, v66, v67
	global_load_dword v59, v13, s[16:17]
	s_add_u32 s16, s16, 0x100
	s_addc_u32 s17, s17, 0
	s_waitcnt vmcnt(57)
	v_readlane_b32 s10, v71, 26
	v_readlane_b32 s11, v28, 26
	global_store_dword v12, v70, s[16:17]
	s_nop 0
	v_mul_f32_e32 v66, s10, v70
	v_mul_f32_e32 v67, s11, v60
	v_add_f32_e32 v70, v66, v67
	global_load_dword v60, v13, s[16:17]
	s_add_u32 s16, s16, 0x100
	s_addc_u32 s17, s17, 0
	s_waitcnt vmcnt(58)
	v_readlane_b32 s10, v71, 27
	v_readlane_b32 s11, v28, 27
	global_store_dword v12, v70, s[16:17]
	s_nop 0
	v_mul_f32_e32 v66, s10, v70
	v_mul_f32_e32 v67, s11, v61
	v_add_f32_e32 v70, v66, v67
	global_load_dword v61, v13, s[16:17]
	s_add_u32 s16, s16, 0x100
	s_addc_u32 s17, s17, 0
	s_waitcnt vmcnt(59)
	v_readlane_b32 s10, v71, 28
	v_readlane_b32 s11, v28, 28
	global_store_dword v12, v70, s[16:17]
	s_nop 0
	v_mul_f32_e32 v66, s10, v70
	v_mul_f32_e32 v67, s11, v62
	v_add_f32_e32 v70, v66, v67
	global_load_dword v62, v13, s[16:17]
	s_add_u32 s16, s16, 0x100
	s_addc_u32 s17, s17, 0
	s_waitcnt vmcnt(60)
	v_readlane_b32 s10, v71, 29
	v_readlane_b32 s11, v28, 29
	global_store_dword v12, v70, s[16:17]
	s_nop 0
	v_mul_f32_e32 v66, s10, v70
	v_mul_f32_e32 v67, s11, v63
	v_add_f32_e32 v70, v66, v67
	global_load_dword v63, v13, s[16:17]
	s_add_u32 s16, s16, 0x100
	s_addc_u32 s17, s17, 0
	s_waitcnt vmcnt(61)
	v_readlane_b32 s10, v71, 30
	v_readlane_b32 s11, v28, 30
	global_store_dword v12, v70, s[16:17]
	s_nop 0
	v_mul_f32_e32 v66, s10, v70
	v_mul_f32_e32 v67, s11, v64
	v_add_f32_e32 v70, v66, v67
	global_load_dword v64, v13, s[16:17]
	s_add_u32 s16, s16, 0x100
	s_addc_u32 s17, s17, 0
	s_waitcnt vmcnt(62)
	v_readlane_b32 s10, v71, 31
	v_readlane_b32 s11, v28, 31
	global_store_dword v12, v70, s[16:17]
	s_nop 0
	v_mul_f32_e32 v66, s10, v70
	v_mul_f32_e32 v67, s11, v65
	v_add_f32_e32 v70, v66, v67
	global_load_dword v65, v13, s[16:17]
	s_add_u32 s16, s16, 0x100
	s_addc_u32 s17, s17, 0
	s_waitcnt vmcnt(62)
; __device__ __forceinline__ void mlstm_scan(bf16* DC, float* DN, float* SC, int wg, int G, int tid) {
;     ...
;                 if (has_n) { dn[(i + k) * 64] = n; n = decay * n + grow * nv[k]; }
	v_readlane_b32 s10, v71, 32
	v_readlane_b32 s11, v28, 32
	global_store_dword v12, v70, s[16:17]
	s_nop 0
	v_mul_f32_e32 v66, s10, v70
	v_mul_f32_e32 v67, s11, v34
	v_add_f32_e32 v70, v66, v67
	global_load_dword v34, v13, s[16:17]
	s_add_u32 s16, s16, 0x100
	s_addc_u32 s17, s17, 0
	s_waitcnt vmcnt(62)
	v_readlane_b32 s10, v71, 33
	v_readlane_b32 s11, v28, 33
	global_store_dword v12, v70, s[16:17]
	s_nop 0
	v_mul_f32_e32 v66, s10, v70
	v_mul_f32_e32 v67, s11, v35
	v_add_f32_e32 v70, v66, v67
	global_load_dword v35, v13, s[16:17]
	s_add_u32 s16, s16, 0x100
	s_addc_u32 s17, s17, 0
	s_waitcnt vmcnt(62)
	v_readlane_b32 s10, v71, 34
	v_readlane_b32 s11, v28, 34
	global_store_dword v12, v70, s[16:17]
	s_nop 0
	v_mul_f32_e32 v66, s10, v70
	v_mul_f32_e32 v67, s11, v36
	v_add_f32_e32 v70, v66, v67
	global_load_dword v36, v13, s[16:17]
	s_add_u32 s16, s16, 0x100
	s_addc_u32 s17, s17, 0
	s_waitcnt vmcnt(62)
	v_readlane_b32 s10, v71, 35
	v_readlane_b32 s11, v28, 35
	global_store_dword v12, v70, s[16:17]
	s_nop 0
	v_mul_f32_e32 v66, s10, v70
	v_mul_f32_e32 v67, s11, v37
	v_add_f32_e32 v70, v66, v67
	global_load_dword v37, v13, s[16:17]
	s_add_u32 s16, s16, 0x100
	s_addc_u32 s17, s17, 0
	s_waitcnt vmcnt(62)
	v_readlane_b32 s10, v71, 36
	v_readlane_b32 s11, v28, 36
	global_store_dword v12, v70, s[16:17]
	s_nop 0
	v_mul_f32_e32 v66, s10, v70
	v_mul_f32_e32 v67, s11, v38
	v_add_f32_e32 v70, v66, v67
	global_load_dword v38, v13, s[16:17]
	s_add_u32 s16, s16, 0x100
	s_addc_u32 s17, s17, 0
	s_waitcnt vmcnt(62)
	v_readlane_b32 s10, v71, 37
	v_readlane_b32 s11, v28, 37
	global_store_dword v12, v70, s[16:17]
	s_nop 0
	v_mul_f32_e32 v66, s10, v70
	v_mul_f32_e32 v67, s11, v39
	v_add_f32_e32 v70, v66, v67
	global_load_dword v39, v13, s[16:17]
	s_add_u32 s16, s16, 0x100
	s_addc_u32 s17, s17, 0
	s_waitcnt vmcnt(62)
	v_readlane_b32 s10, v71, 38
	v_readlane_b32 s11, v28, 38
	global_store_dword v12, v70, s[16:17]
	s_nop 0
	v_mul_f32_e32 v66, s10, v70
	v_mul_f32_e32 v67, s11, v40
	v_add_f32_e32 v70, v66, v67
	global_load_dword v40, v13, s[16:17]
	s_add_u32 s16, s16, 0x100
	s_addc_u32 s17, s17, 0
	s_waitcnt vmcnt(62)
	v_readlane_b32 s10, v71, 39
	v_readlane_b32 s11, v28, 39
	global_store_dword v12, v70, s[16:17]
	s_nop 0
	v_mul_f32_e32 v66, s10, v70
	v_mul_f32_e32 v67, s11, v41
	v_add_f32_e32 v70, v66, v67
	global_load_dword v41, v13, s[16:17]
	s_add_u32 s16, s16, 0x100
	s_addc_u32 s17, s17, 0
	s_waitcnt vmcnt(62)
	v_readlane_b32 s10, v71, 40
	v_readlane_b32 s11, v28, 40
	global_store_dword v12, v70, s[16:17]
	s_nop 0
	v_mul_f32_e32 v66, s10, v70
	v_mul_f32_e32 v67, s11, v42
	v_add_f32_e32 v70, v66, v67
	global_load_dword v42, v13, s[16:17]
	s_add_u32 s16, s16, 0x100
	s_addc_u32 s17, s17, 0
	s_waitcnt vmcnt(62)
	v_readlane_b32 s10, v71, 41
	v_readlane_b32 s11, v28, 41
	global_store_dword v12, v70, s[16:17]
	s_nop 0
	v_mul_f32_e32 v66, s10, v70
	v_mul_f32_e32 v67, s11, v43
	v_add_f32_e32 v70, v66, v67
	global_load_dword v43, v13, s[16:17]
	s_add_u32 s16, s16, 0x100
	s_addc_u32 s17, s17, 0
	s_waitcnt vmcnt(62)
	v_readlane_b32 s10, v71, 42
	v_readlane_b32 s11, v28, 42
	global_store_dword v12, v70, s[16:17]
	s_nop 0
	v_mul_f32_e32 v66, s10, v70
	v_mul_f32_e32 v67, s11, v44
	v_add_f32_e32 v70, v66, v67
	global_load_dword v44, v13, s[16:17]
	s_add_u32 s16, s16, 0x100
	s_addc_u32 s17, s17, 0
	s_waitcnt vmcnt(62)
	v_readlane_b32 s10, v71, 43
	v_readlane_b32 s11, v28, 43
	global_store_dword v12, v70, s[16:17]
	s_nop 0
	v_mul_f32_e32 v66, s10, v70
	v_mul_f32_e32 v67, s11, v45
	v_add_f32_e32 v70, v66, v67
	global_load_dword v45, v13, s[16:17]
	s_add_u32 s16, s16, 0x100
	s_addc_u32 s17, s17, 0
	s_waitcnt vmcnt(62)
	v_readlane_b32 s10, v71, 44
	v_readlane_b32 s11, v28, 44
	global_store_dword v12, v70, s[16:17]
	s_nop 0
	v_mul_f32_e32 v66, s10, v70
	v_mul_f32_e32 v67, s11, v46
	v_add_f32_e32 v70, v66, v67
	global_load_dword v46, v13, s[16:17]
	s_add_u32 s16, s16, 0x100
	s_addc_u32 s17, s17, 0
	s_waitcnt vmcnt(62)
	v_readlane_b32 s10, v71, 45
	v_readlane_b32 s11, v28, 45
	global_store_dword v12, v70, s[16:17]
	s_nop 0
	v_mul_f32_e32 v66, s10, v70
	v_mul_f32_e32 v67, s11, v47
	v_add_f32_e32 v70, v66, v67
	global_load_dword v47, v13, s[16:17]
	s_add_u32 s16, s16, 0x100
	s_addc_u32 s17, s17, 0
	s_waitcnt vmcnt(62)
	v_readlane_b32 s10, v71, 46
	v_readlane_b32 s11, v28, 46
	global_store_dword v12, v70, s[16:17]
	s_nop 0
	v_mul_f32_e32 v66, s10, v70
	v_mul_f32_e32 v67, s11, v48
	v_add_f32_e32 v70, v66, v67
	global_load_dword v48, v13, s[16:17]
	s_add_u32 s16, s16, 0x100
	s_addc_u32 s17, s17, 0
	s_waitcnt vmcnt(62)
	v_readlane_b32 s10, v71, 47
	v_readlane_b32 s11, v28, 47
	global_store_dword v12, v70, s[16:17]
	s_nop 0
	v_mul_f32_e32 v66, s10, v70
	v_mul_f32_e32 v67, s11, v49
	v_add_f32_e32 v70, v66, v67
	global_load_dword v49, v13, s[16:17]
	s_add_u32 s16, s16, 0x100
	s_addc_u32 s17, s17, 0
	s_waitcnt vmcnt(62)
	v_readlane_b32 s10, v71, 48
	v_readlane_b32 s11, v28, 48
	global_store_dword v12, v70, s[16:17]
	s_nop 0
	v_mul_f32_e32 v66, s10, v70
	v_mul_f32_e32 v67, s11, v50
	v_add_f32_e32 v70, v66, v67
	global_load_dword v50, v13, s[16:17]
	s_add_u32 s16, s16, 0x100
	s_addc_u32 s17, s17, 0
	s_waitcnt vmcnt(62)
	v_readlane_b32 s10, v71, 49
	v_readlane_b32 s11, v28, 49
	global_store_dword v12, v70, s[16:17]
	s_nop 0
	v_mul_f32_e32 v66, s10, v70
	v_mul_f32_e32 v67, s11, v51
	v_add_f32_e32 v70, v66, v67
	global_load_dword v51, v13, s[16:17]
	s_add_u32 s16, s16, 0x100
	s_addc_u32 s17, s17, 0
	s_waitcnt vmcnt(62)
	v_readlane_b32 s10, v71, 50
	v_readlane_b32 s11, v28, 50
	global_store_dword v12, v70, s[16:17]
	s_nop 0
	v_mul_f32_e32 v66, s10, v70
	v_mul_f32_e32 v67, s11, v52
	v_add_f32_e32 v70, v66, v67
	global_load_dword v52, v13, s[16:17]
	s_add_u32 s16, s16, 0x100
	s_addc_u32 s17, s17, 0
	s_waitcnt vmcnt(62)
; __device__ __forceinline__ void mlstm_scan(bf16* DC, float* DN, float* SC, int wg, int G, int tid) {
;     ...
;                 if (has_n) { dn[(i + k) * 64] = n; n = decay * n + grow * nv[k]; }
	v_readlane_b32 s10, v71, 51
	v_readlane_b32 s11, v28, 51
	global_store_dword v12, v70, s[16:17]
	s_nop 0
	v_mul_f32_e32 v66, s10, v70
	v_mul_f32_e32 v67, s11, v53
	v_add_f32_e32 v70, v66, v67
	global_load_dword v53, v13, s[16:17]
	s_add_u32 s16, s16, 0x100
	s_addc_u32 s17, s17, 0
	s_waitcnt vmcnt(62)
	v_readlane_b32 s10, v71, 52
	v_readlane_b32 s11, v28, 52
	global_store_dword v12, v70, s[16:17]
	s_nop 0
	v_mul_f32_e32 v66, s10, v70
	v_mul_f32_e32 v67, s11, v54
	v_add_f32_e32 v70, v66, v67
	global_load_dword v54, v13, s[16:17]
	s_add_u32 s16, s16, 0x100
	s_addc_u32 s17, s17, 0
	s_waitcnt vmcnt(62)
	v_readlane_b32 s10, v71, 53
	v_readlane_b32 s11, v28, 53
	global_store_dword v12, v70, s[16:17]
	s_nop 0
	v_mul_f32_e32 v66, s10, v70
	v_mul_f32_e32 v67, s11, v55
	v_add_f32_e32 v70, v66, v67
	global_load_dword v55, v13, s[16:17]
	s_add_u32 s16, s16, 0x100
	s_addc_u32 s17, s17, 0
	s_waitcnt vmcnt(62)
	v_readlane_b32 s10, v71, 54
	v_readlane_b32 s11, v28, 54
	global_store_dword v12, v70, s[16:17]
	s_nop 0
	v_mul_f32_e32 v66, s10, v70
	v_mul_f32_e32 v67, s11, v56
	v_add_f32_e32 v70, v66, v67
	global_load_dword v56, v13, s[16:17]
	s_add_u32 s16, s16, 0x100
	s_addc_u32 s17, s17, 0
	s_waitcnt vmcnt(62)
	v_readlane_b32 s10, v71, 55
	v_readlane_b32 s11, v28, 55
	global_store_dword v12, v70, s[16:17]
	s_nop 0
	v_mul_f32_e32 v66, s10, v70
	v_mul_f32_e32 v67, s11, v57
	v_add_f32_e32 v70, v66, v67
	global_load_dword v57, v13, s[16:17]
	s_add_u32 s16, s16, 0x100
	s_addc_u32 s17, s17, 0
	s_waitcnt vmcnt(62)
	v_readlane_b32 s10, v71, 56
	v_readlane_b32 s11, v28, 56
	global_store_dword v12, v70, s[16:17]
	s_nop 0
	v_mul_f32_e32 v66, s10, v70
	v_mul_f32_e32 v67, s11, v58
	v_add_f32_e32 v70, v66, v67
	global_load_dword v58, v13, s[16:17]
	s_add_u32 s16, s16, 0x100
	s_addc_u32 s17, s17, 0
	s_waitcnt vmcnt(62)
	v_readlane_b32 s10, v71, 57
	v_readlane_b32 s11, v28, 57
	global_store_dword v12, v70, s[16:17]
	s_nop 0
	v_mul_f32_e32 v66, s10, v70
	v_mul_f32_e32 v67, s11, v59
	v_add_f32_e32 v70, v66, v67
	global_load_dword v59, v13, s[16:17]
	s_add_u32 s16, s16, 0x100
	s_addc_u32 s17, s17, 0
	s_waitcnt vmcnt(62)
	v_readlane_b32 s10, v71, 58
	v_readlane_b32 s11, v28, 58
	global_store_dword v12, v70, s[16:17]
	s_nop 0
	v_mul_f32_e32 v66, s10, v70
	v_mul_f32_e32 v67, s11, v60
	v_add_f32_e32 v70, v66, v67
	global_load_dword v60, v13, s[16:17]
	s_add_u32 s16, s16, 0x100
	s_addc_u32 s17, s17, 0
	s_waitcnt vmcnt(62)
	v_readlane_b32 s10, v71, 59
	v_readlane_b32 s11, v28, 59
	global_store_dword v12, v70, s[16:17]
	s_nop 0
	v_mul_f32_e32 v66, s10, v70
	v_mul_f32_e32 v67, s11, v61
	v_add_f32_e32 v70, v66, v67
	global_load_dword v61, v13, s[16:17]
	s_add_u32 s16, s16, 0x100
	s_addc_u32 s17, s17, 0
	s_waitcnt vmcnt(62)
	v_readlane_b32 s10, v71, 60
	v_readlane_b32 s11, v28, 60
	global_store_dword v12, v70, s[16:17]
	s_nop 0
	v_mul_f32_e32 v66, s10, v70
	v_mul_f32_e32 v67, s11, v62
	v_add_f32_e32 v70, v66, v67
	global_load_dword v62, v13, s[16:17]
	s_add_u32 s16, s16, 0x100
	s_addc_u32 s17, s17, 0
	s_waitcnt vmcnt(62)
	v_readlane_b32 s10, v71, 61
	v_readlane_b32 s11, v28, 61
	global_store_dword v12, v70, s[16:17]
	s_nop 0
	v_mul_f32_e32 v66, s10, v70
	v_mul_f32_e32 v67, s11, v63
	v_add_f32_e32 v70, v66, v67
	global_load_dword v63, v13, s[16:17]
	s_add_u32 s16, s16, 0x100
	s_addc_u32 s17, s17, 0
	s_waitcnt vmcnt(62)
	v_readlane_b32 s10, v71, 62
	v_readlane_b32 s11, v28, 62
	global_store_dword v12, v70, s[16:17]
	s_nop 0
	v_mul_f32_e32 v66, s10, v70
	v_mul_f32_e32 v67, s11, v64
	v_add_f32_e32 v70, v66, v67
	global_load_dword v64, v13, s[16:17]
	s_add_u32 s16, s16, 0x100
	s_addc_u32 s17, s17, 0
	s_waitcnt vmcnt(62)
	v_readlane_b32 s10, v71, 63
	v_readlane_b32 s11, v28, 63
	global_store_dword v12, v70, s[16:17]
	s_nop 0
	v_mul_f32_e32 v66, s10, v70
	v_mul_f32_e32 v67, s11, v65
	v_add_f32_e32 v70, v66, v67
	global_load_dword v65, v13, s[16:17]
	s_add_u32 s16, s16, 0x100
	s_addc_u32 s17, s17, 0
	s_waitcnt vmcnt(62)
	v_readlane_b32 s10, v72, 0
	v_readlane_b32 s11, v29, 0
	global_store_dword v12, v70, s[16:17]
	s_nop 0
	v_mul_f32_e32 v66, s10, v70
	v_mul_f32_e32 v67, s11, v34
	v_add_f32_e32 v70, v66, v67
	global_load_dword v34, v13, s[16:17]
	s_add_u32 s16, s16, 0x100
	s_addc_u32 s17, s17, 0
	s_waitcnt vmcnt(62)
	v_readlane_b32 s10, v72, 1
	v_readlane_b32 s11, v29, 1
	global_store_dword v12, v70, s[16:17]
	s_nop 0
	v_mul_f32_e32 v66, s10, v70
	v_mul_f32_e32 v67, s11, v35
	v_add_f32_e32 v70, v66, v67
	global_load_dword v35, v13, s[16:17]
	s_add_u32 s16, s16, 0x100
	s_addc_u32 s17, s17, 0
	s_waitcnt vmcnt(62)
	v_readlane_b32 s10, v72, 2
	v_readlane_b32 s11, v29, 2
	global_store_dword v12, v70, s[16:17]
	s_nop 0
	v_mul_f32_e32 v66, s10, v70
	v_mul_f32_e32 v67, s11, v36
	v_add_f32_e32 v70, v66, v67
	global_load_dword v36, v13, s[16:17]
	s_add_u32 s16, s16, 0x100
	s_addc_u32 s17, s17, 0
	s_waitcnt vmcnt(62)
	v_readlane_b32 s10, v72, 3
	v_readlane_b32 s11, v29, 3
	global_store_dword v12, v70, s[16:17]
	s_nop 0
	v_mul_f32_e32 v66, s10, v70
	v_mul_f32_e32 v67, s11, v37
	v_add_f32_e32 v70, v66, v67
	global_load_dword v37, v13, s[16:17]
	s_add_u32 s16, s16, 0x100
	s_addc_u32 s17, s17, 0
	s_waitcnt vmcnt(62)
	v_readlane_b32 s10, v72, 4
	v_readlane_b32 s11, v29, 4
	global_store_dword v12, v70, s[16:17]
	s_nop 0
	v_mul_f32_e32 v66, s10, v70
	v_mul_f32_e32 v67, s11, v38
	v_add_f32_e32 v70, v66, v67
	global_load_dword v38, v13, s[16:17]
	s_add_u32 s16, s16, 0x100
	s_addc_u32 s17, s17, 0
	s_waitcnt vmcnt(62)
	v_readlane_b32 s10, v72, 5
	v_readlane_b32 s11, v29, 5
	global_store_dword v12, v70, s[16:17]
	s_nop 0
	v_mul_f32_e32 v66, s10, v70
	v_mul_f32_e32 v67, s11, v39
	v_add_f32_e32 v70, v66, v67
	global_load_dword v39, v13, s[16:17]
	s_add_u32 s16, s16, 0x100
	s_addc_u32 s17, s17, 0
	s_waitcnt vmcnt(62)
; __device__ __forceinline__ void mlstm_scan(bf16* DC, float* DN, float* SC, int wg, int G, int tid) {
;     ...
;                 if (has_n) { dn[(i + k) * 64] = n; n = decay * n + grow * nv[k]; }
	v_readlane_b32 s10, v72, 6
	v_readlane_b32 s11, v29, 6
	global_store_dword v12, v70, s[16:17]
	s_nop 0
	v_mul_f32_e32 v66, s10, v70
	v_mul_f32_e32 v67, s11, v40
	v_add_f32_e32 v70, v66, v67
	global_load_dword v40, v13, s[16:17]
	s_add_u32 s16, s16, 0x100
	s_addc_u32 s17, s17, 0
	s_waitcnt vmcnt(62)
	v_readlane_b32 s10, v72, 7
	v_readlane_b32 s11, v29, 7
	global_store_dword v12, v70, s[16:17]
	s_nop 0
	v_mul_f32_e32 v66, s10, v70
	v_mul_f32_e32 v67, s11, v41
	v_add_f32_e32 v70, v66, v67
	global_load_dword v41, v13, s[16:17]
	s_add_u32 s16, s16, 0x100
	s_addc_u32 s17, s17, 0
	s_waitcnt vmcnt(62)
	v_readlane_b32 s10, v72, 8
	v_readlane_b32 s11, v29, 8
	global_store_dword v12, v70, s[16:17]
	s_nop 0
	v_mul_f32_e32 v66, s10, v70
	v_mul_f32_e32 v67, s11, v42
	v_add_f32_e32 v70, v66, v67
	global_load_dword v42, v13, s[16:17]
	s_add_u32 s16, s16, 0x100
	s_addc_u32 s17, s17, 0
	s_waitcnt vmcnt(62)
	v_readlane_b32 s10, v72, 9
	v_readlane_b32 s11, v29, 9
	global_store_dword v12, v70, s[16:17]
	s_nop 0
	v_mul_f32_e32 v66, s10, v70
	v_mul_f32_e32 v67, s11, v43
	v_add_f32_e32 v70, v66, v67
	global_load_dword v43, v13, s[16:17]
	s_add_u32 s16, s16, 0x100
	s_addc_u32 s17, s17, 0
	s_waitcnt vmcnt(62)
	v_readlane_b32 s10, v72, 10
	v_readlane_b32 s11, v29, 10
	global_store_dword v12, v70, s[16:17]
	s_nop 0
	v_mul_f32_e32 v66, s10, v70
	v_mul_f32_e32 v67, s11, v44
	v_add_f32_e32 v70, v66, v67
	global_load_dword v44, v13, s[16:17]
	s_add_u32 s16, s16, 0x100
	s_addc_u32 s17, s17, 0
	s_waitcnt vmcnt(62)
	v_readlane_b32 s10, v72, 11
	v_readlane_b32 s11, v29, 11
	global_store_dword v12, v70, s[16:17]
	s_nop 0
	v_mul_f32_e32 v66, s10, v70
	v_mul_f32_e32 v67, s11, v45
	v_add_f32_e32 v70, v66, v67
	global_load_dword v45, v13, s[16:17]
	s_add_u32 s16, s16, 0x100
	s_addc_u32 s17, s17, 0
	s_waitcnt vmcnt(62)
	v_readlane_b32 s10, v72, 12
	v_readlane_b32 s11, v29, 12
	global_store_dword v12, v70, s[16:17]
	s_nop 0
	v_mul_f32_e32 v66, s10, v70
	v_mul_f32_e32 v67, s11, v46
	v_add_f32_e32 v70, v66, v67
	global_load_dword v46, v13, s[16:17]
	s_add_u32 s16, s16, 0x100
	s_addc_u32 s17, s17, 0
	s_waitcnt vmcnt(62)
	v_readlane_b32 s10, v72, 13
	v_readlane_b32 s11, v29, 13
	global_store_dword v12, v70, s[16:17]
	s_nop 0
	v_mul_f32_e32 v66, s10, v70
	v_mul_f32_e32 v67, s11, v47
	v_add_f32_e32 v70, v66, v67
	global_load_dword v47, v13, s[16:17]
	s_add_u32 s16, s16, 0x100
	s_addc_u32 s17, s17, 0
	s_waitcnt vmcnt(62)
	v_readlane_b32 s10, v72, 14
	v_readlane_b32 s11, v29, 14
	global_store_dword v12, v70, s[16:17]
	s_nop 0
	v_mul_f32_e32 v66, s10, v70
	v_mul_f32_e32 v67, s11, v48
	v_add_f32_e32 v70, v66, v67
	global_load_dword v48, v13, s[16:17]
	s_add_u32 s16, s16, 0x100
	s_addc_u32 s17, s17, 0
	s_waitcnt vmcnt(62)
	v_readlane_b32 s10, v72, 15
	v_readlane_b32 s11, v29, 15
	global_store_dword v12, v70, s[16:17]
	s_nop 0
	v_mul_f32_e32 v66, s10, v70
	v_mul_f32_e32 v67, s11, v49
	v_add_f32_e32 v70, v66, v67
	global_load_dword v49, v13, s[16:17]
	s_add_u32 s16, s16, 0x100
	s_addc_u32 s17, s17, 0
	s_waitcnt vmcnt(62)
	v_readlane_b32 s10, v72, 16
	v_readlane_b32 s11, v29, 16
	global_store_dword v12, v70, s[16:17]
	s_nop 0
	v_mul_f32_e32 v66, s10, v70
	v_mul_f32_e32 v67, s11, v50
	v_add_f32_e32 v70, v66, v67
	global_load_dword v50, v13, s[16:17]
	s_add_u32 s16, s16, 0x100
	s_addc_u32 s17, s17, 0
	s_waitcnt vmcnt(62)
	v_readlane_b32 s10, v72, 17
	v_readlane_b32 s11, v29, 17
	global_store_dword v12, v70, s[16:17]
	s_nop 0
	v_mul_f32_e32 v66, s10, v70
	v_mul_f32_e32 v67, s11, v51
	v_add_f32_e32 v70, v66, v67
	global_load_dword v51, v13, s[16:17]
	s_add_u32 s16, s16, 0x100
	s_addc_u32 s17, s17, 0
	s_waitcnt vmcnt(62)
	v_readlane_b32 s10, v72, 18
	v_readlane_b32 s11, v29, 18
	global_store_dword v12, v70, s[16:17]
	s_nop 0
	v_mul_f32_e32 v66, s10, v70
	v_mul_f32_e32 v67, s11, v52
	v_add_f32_e32 v70, v66, v67
	global_load_dword v52, v13, s[16:17]
	s_add_u32 s16, s16, 0x100
	s_addc_u32 s17, s17, 0
	s_waitcnt vmcnt(62)
	v_readlane_b32 s10, v72, 19
	v_readlane_b32 s11, v29, 19
	global_store_dword v12, v70, s[16:17]
	s_nop 0
	v_mul_f32_e32 v66, s10, v70
	v_mul_f32_e32 v67, s11, v53
	v_add_f32_e32 v70, v66, v67
	global_load_dword v53, v13, s[16:17]
	s_add_u32 s16, s16, 0x100
	s_addc_u32 s17, s17, 0
	s_waitcnt vmcnt(62)
	v_readlane_b32 s10, v72, 20
	v_readlane_b32 s11, v29, 20
	global_store_dword v12, v70, s[16:17]
	s_nop 0
	v_mul_f32_e32 v66, s10, v70
	v_mul_f32_e32 v67, s11, v54
	v_add_f32_e32 v70, v66, v67
	global_load_dword v54, v13, s[16:17]
	s_add_u32 s16, s16, 0x100
	s_addc_u32 s17, s17, 0
	s_waitcnt vmcnt(62)
	v_readlane_b32 s10, v72, 21
	v_readlane_b32 s11, v29, 21
	global_store_dword v12, v70, s[16:17]
	s_nop 0
	v_mul_f32_e32 v66, s10, v70
	v_mul_f32_e32 v67, s11, v55
	v_add_f32_e32 v70, v66, v67
	global_load_dword v55, v13, s[16:17]
	s_add_u32 s16, s16, 0x100
	s_addc_u32 s17, s17, 0
	s_waitcnt vmcnt(62)
	v_readlane_b32 s10, v72, 22
	v_readlane_b32 s11, v29, 22
	global_store_dword v12, v70, s[16:17]
	s_nop 0
	v_mul_f32_e32 v66, s10, v70
	v_mul_f32_e32 v67, s11, v56
	v_add_f32_e32 v70, v66, v67
	global_load_dword v56, v13, s[16:17]
	s_add_u32 s16, s16, 0x100
	s_addc_u32 s17, s17, 0
	s_waitcnt vmcnt(62)
	v_readlane_b32 s10, v72, 23
	v_readlane_b32 s11, v29, 23
	global_store_dword v12, v70, s[16:17]
	s_nop 0
	v_mul_f32_e32 v66, s10, v70
	v_mul_f32_e32 v67, s11, v57
	v_add_f32_e32 v70, v66, v67
	global_load_dword v57, v13, s[16:17]
	s_add_u32 s16, s16, 0x100
	s_addc_u32 s17, s17, 0
	s_waitcnt vmcnt(62)
	v_readlane_b32 s10, v72, 24
	v_readlane_b32 s11, v29, 24
	global_store_dword v12, v70, s[16:17]
	s_nop 0
	v_mul_f32_e32 v66, s10, v70
	v_mul_f32_e32 v67, s11, v58
	v_add_f32_e32 v70, v66, v67
	global_load_dword v58, v13, s[16:17]
	s_add_u32 s16, s16, 0x100
	s_addc_u32 s17, s17, 0
	s_waitcnt vmcnt(62)
; __device__ __forceinline__ void mlstm_scan(bf16* DC, float* DN, float* SC, int wg, int G, int tid) {
;     ...
;                 if (has_n) { dn[(i + k) * 64] = n; n = decay * n + grow * nv[k]; }
	v_readlane_b32 s10, v72, 25
	v_readlane_b32 s11, v29, 25
	global_store_dword v12, v70, s[16:17]
	s_nop 0
	v_mul_f32_e32 v66, s10, v70
	v_mul_f32_e32 v67, s11, v59
	v_add_f32_e32 v70, v66, v67
	global_load_dword v59, v13, s[16:17]
	s_add_u32 s16, s16, 0x100
	s_addc_u32 s17, s17, 0
	s_waitcnt vmcnt(62)
	v_readlane_b32 s10, v72, 26
	v_readlane_b32 s11, v29, 26
	global_store_dword v12, v70, s[16:17]
	s_nop 0
	v_mul_f32_e32 v66, s10, v70
	v_mul_f32_e32 v67, s11, v60
	v_add_f32_e32 v70, v66, v67
	global_load_dword v60, v13, s[16:17]
	s_add_u32 s16, s16, 0x100
	s_addc_u32 s17, s17, 0
	s_waitcnt vmcnt(62)
	v_readlane_b32 s10, v72, 27
	v_readlane_b32 s11, v29, 27
	global_store_dword v12, v70, s[16:17]
	s_nop 0
	v_mul_f32_e32 v66, s10, v70
	v_mul_f32_e32 v67, s11, v61
	v_add_f32_e32 v70, v66, v67
	global_load_dword v61, v13, s[16:17]
	s_add_u32 s16, s16, 0x100
	s_addc_u32 s17, s17, 0
	s_waitcnt vmcnt(62)
	v_readlane_b32 s10, v72, 28
	v_readlane_b32 s11, v29, 28
	global_store_dword v12, v70, s[16:17]
	s_nop 0
	v_mul_f32_e32 v66, s10, v70
	v_mul_f32_e32 v67, s11, v62
	v_add_f32_e32 v70, v66, v67
	global_load_dword v62, v13, s[16:17]
	s_add_u32 s16, s16, 0x100
	s_addc_u32 s17, s17, 0
	s_waitcnt vmcnt(62)
	v_readlane_b32 s10, v72, 29
	v_readlane_b32 s11, v29, 29
	global_store_dword v12, v70, s[16:17]
	s_nop 0
	v_mul_f32_e32 v66, s10, v70
	v_mul_f32_e32 v67, s11, v63
	v_add_f32_e32 v70, v66, v67
	global_load_dword v63, v13, s[16:17]
	s_add_u32 s16, s16, 0x100
	s_addc_u32 s17, s17, 0
	s_waitcnt vmcnt(62)
	v_readlane_b32 s10, v72, 30
	v_readlane_b32 s11, v29, 30
	global_store_dword v12, v70, s[16:17]
	s_nop 0
	v_mul_f32_e32 v66, s10, v70
	v_mul_f32_e32 v67, s11, v64
	v_add_f32_e32 v70, v66, v67
	global_load_dword v64, v13, s[16:17]
	s_add_u32 s16, s16, 0x100
	s_addc_u32 s17, s17, 0
	s_waitcnt vmcnt(62)
	v_readlane_b32 s10, v72, 31
	v_readlane_b32 s11, v29, 31
	global_store_dword v12, v70, s[16:17]
	s_nop 0
	v_mul_f32_e32 v66, s10, v70
	v_mul_f32_e32 v67, s11, v65
	v_add_f32_e32 v70, v66, v67
	global_load_dword v65, v13, s[16:17]
	s_add_u32 s16, s16, 0x100
	s_addc_u32 s17, s17, 0
	s_waitcnt vmcnt(62)
	v_readlane_b32 s10, v72, 32
	v_readlane_b32 s11, v29, 32
	global_store_dword v12, v70, s[16:17]
	s_nop 0
	v_mul_f32_e32 v66, s10, v70
	v_mul_f32_e32 v67, s11, v34
	v_add_f32_e32 v70, v66, v67
	global_load_dword v34, v13, s[16:17]
	s_add_u32 s16, s16, 0x100
	s_addc_u32 s17, s17, 0
	s_waitcnt vmcnt(62)
	v_readlane_b32 s10, v72, 33
	v_readlane_b32 s11, v29, 33
	global_store_dword v12, v70, s[16:17]
	s_nop 0
	v_mul_f32_e32 v66, s10, v70
	v_mul_f32_e32 v67, s11, v35
	v_add_f32_e32 v70, v66, v67
	global_load_dword v35, v13, s[16:17]
	s_add_u32 s16, s16, 0x100
	s_addc_u32 s17, s17, 0
	s_waitcnt vmcnt(62)
	v_readlane_b32 s10, v72, 34
	v_readlane_b32 s11, v29, 34
	global_store_dword v12, v70, s[16:17]
	s_nop 0
	v_mul_f32_e32 v66, s10, v70
	v_mul_f32_e32 v67, s11, v36
	v_add_f32_e32 v70, v66, v67
	global_load_dword v36, v13, s[16:17]
	s_add_u32 s16, s16, 0x100
	s_addc_u32 s17, s17, 0
	s_waitcnt vmcnt(62)
	v_readlane_b32 s10, v72, 35
	v_readlane_b32 s11, v29, 35
	global_store_dword v12, v70, s[16:17]
	s_nop 0
	v_mul_f32_e32 v66, s10, v70
	v_mul_f32_e32 v67, s11, v37
	v_add_f32_e32 v70, v66, v67
	global_load_dword v37, v13, s[16:17]
	s_add_u32 s16, s16, 0x100
	s_addc_u32 s17, s17, 0
	s_waitcnt vmcnt(62)
	v_readlane_b32 s10, v72, 36
	v_readlane_b32 s11, v29, 36
	global_store_dword v12, v70, s[16:17]
	s_nop 0
	v_mul_f32_e32 v66, s10, v70
	v_mul_f32_e32 v67, s11, v38
	v_add_f32_e32 v70, v66, v67
	s_add_u32 s16, s16, 0x100
	s_addc_u32 s17, s17, 0
	s_waitcnt vmcnt(61)
	v_readlane_b32 s10, v72, 37
	v_readlane_b32 s11, v29, 37
	global_store_dword v12, v70, s[16:17]
	s_nop 0
	v_mul_f32_e32 v66, s10, v70
	v_mul_f32_e32 v67, s11, v39
	v_add_f32_e32 v70, v66, v67
	s_add_u32 s16, s16, 0x100
	s_addc_u32 s17, s17, 0
	s_waitcnt vmcnt(60)
	v_readlane_b32 s10, v72, 38
	v_readlane_b32 s11, v29, 38
	global_store_dword v12, v70, s[16:17]
	s_nop 0
	v_mul_f32_e32 v66, s10, v70
	v_mul_f32_e32 v67, s11, v40
	v_add_f32_e32 v70, v66, v67
	s_add_u32 s16, s16, 0x100
	s_addc_u32 s17, s17, 0
	s_waitcnt vmcnt(59)
	v_readlane_b32 s10, v72, 39
	v_readlane_b32 s11, v29, 39
	global_store_dword v12, v70, s[16:17]
	s_nop 0
	v_mul_f32_e32 v66, s10, v70
	v_mul_f32_e32 v67, s11, v41
	v_add_f32_e32 v70, v66, v67
	s_add_u32 s16, s16, 0x100
	s_addc_u32 s17, s17, 0
	s_waitcnt vmcnt(58)
	v_readlane_b32 s10, v72, 40
	v_readlane_b32 s11, v29, 40
	global_store_dword v12, v70, s[16:17]
	s_nop 0
	v_mul_f32_e32 v66, s10, v70
	v_mul_f32_e32 v67, s11, v42
	v_add_f32_e32 v70, v66, v67
	s_add_u32 s16, s16, 0x100
	s_addc_u32 s17, s17, 0
	s_waitcnt vmcnt(57)
	v_readlane_b32 s10, v72, 41
	v_readlane_b32 s11, v29, 41
	global_store_dword v12, v70, s[16:17]
	s_nop 0
	v_mul_f32_e32 v66, s10, v70
	v_mul_f32_e32 v67, s11, v43
	v_add_f32_e32 v70, v66, v67
	s_add_u32 s16, s16, 0x100
	s_addc_u32 s17, s17, 0
	s_waitcnt vmcnt(56)
	v_readlane_b32 s10, v72, 42
	v_readlane_b32 s11, v29, 42
	global_store_dword v12, v70, s[16:17]
	s_nop 0
	v_mul_f32_e32 v66, s10, v70
	v_mul_f32_e32 v67, s11, v44
	v_add_f32_e32 v70, v66, v67
	s_add_u32 s16, s16, 0x100
	s_addc_u32 s17, s17, 0
	s_waitcnt vmcnt(55)
	v_readlane_b32 s10, v72, 43
	v_readlane_b32 s11, v29, 43
	global_store_dword v12, v70, s[16:17]
	s_nop 0
	v_mul_f32_e32 v66, s10, v70
	v_mul_f32_e32 v67, s11, v45
	v_add_f32_e32 v70, v66, v67
	s_add_u32 s16, s16, 0x100
	s_addc_u32 s17, s17, 0
	s_waitcnt vmcnt(54)
	v_readlane_b32 s10, v72, 44
	v_readlane_b32 s11, v29, 44
	global_store_dword v12, v70, s[16:17]
	s_nop 0
	v_mul_f32_e32 v66, s10, v70
	v_mul_f32_e32 v67, s11, v46
	v_add_f32_e32 v70, v66, v67
	s_add_u32 s16, s16, 0x100
	s_addc_u32 s17, s17, 0
	s_waitcnt vmcnt(53)
; __device__ __forceinline__ float bf2f(unsigned h) { return __uint_as_float(h << 16); }
; __device__ __forceinline__ unsigned pk2(float lo, float hi) { return pg8::pkbf(lo, hi); }
; __device__ __forceinline__ void mlstm_scan(bf16* DC, float* DN, float* SC, int wg, int G, int tid) {
;     ...
;             for (int k = 0; k < 12; ++k) {
;                 const float mn = fmaxf(g[k] + m, am[k]), decay = expf(g[k] + m - mn), grow = expf(am[k] - mn);
;                 dc[(size_t)(i + k) * 4096] = pk2(C0, C1);
;                 C0 = decay * C0 + grow * bf2f(v[k] & 0xffffu); C1 = decay * C1 + grow * bf2f(v[k] >> 16);
;                 if (has_n) { dn[(i + k) * 64] = n; n = decay * n + grow * nv[k]; }
;                 if (rec_m) sc[(i + k) * 4 + 2] = m;
;                 m = mn;
	v_readlane_b32 s10, v72, 45
	v_readlane_b32 s11, v29, 45
	global_store_dword v12, v70, s[16:17]
	s_nop 0
	v_mul_f32_e32 v66, s10, v70
	v_mul_f32_e32 v67, s11, v47
	v_add_f32_e32 v70, v66, v67
	s_add_u32 s16, s16, 0x100
	s_addc_u32 s17, s17, 0
	s_waitcnt vmcnt(52)
	v_readlane_b32 s10, v72, 46
	v_readlane_b32 s11, v29, 46
	global_store_dword v12, v70, s[16:17]
	s_nop 0
	v_mul_f32_e32 v66, s10, v70
	v_mul_f32_e32 v67, s11, v48
	v_add_f32_e32 v70, v66, v67
	s_add_u32 s16, s16, 0x100
	s_addc_u32 s17, s17, 0
	s_waitcnt vmcnt(51)
	v_readlane_b32 s10, v72, 47
	v_readlane_b32 s11, v29, 47
	global_store_dword v12, v70, s[16:17]
	s_nop 0
	v_mul_f32_e32 v66, s10, v70
	v_mul_f32_e32 v67, s11, v49
	v_add_f32_e32 v70, v66, v67
	s_add_u32 s16, s16, 0x100
	s_addc_u32 s17, s17, 0
	s_waitcnt vmcnt(50)
	v_readlane_b32 s10, v72, 48
	v_readlane_b32 s11, v29, 48
	global_store_dword v12, v70, s[16:17]
	s_nop 0
	v_mul_f32_e32 v66, s10, v70
	v_mul_f32_e32 v67, s11, v50
	v_add_f32_e32 v70, v66, v67
	s_add_u32 s16, s16, 0x100
	s_addc_u32 s17, s17, 0
	s_waitcnt vmcnt(49)
	v_readlane_b32 s10, v72, 49
	v_readlane_b32 s11, v29, 49
	global_store_dword v12, v70, s[16:17]
	s_nop 0
	v_mul_f32_e32 v66, s10, v70
	v_mul_f32_e32 v67, s11, v51
	v_add_f32_e32 v70, v66, v67
	s_add_u32 s16, s16, 0x100
	s_addc_u32 s17, s17, 0
	s_waitcnt vmcnt(48)
	v_readlane_b32 s10, v72, 50
	v_readlane_b32 s11, v29, 50
	global_store_dword v12, v70, s[16:17]
	s_nop 0
	v_mul_f32_e32 v66, s10, v70
	v_mul_f32_e32 v67, s11, v52
	v_add_f32_e32 v70, v66, v67
	s_add_u32 s16, s16, 0x100
	s_addc_u32 s17, s17, 0
	s_waitcnt vmcnt(47)
	v_readlane_b32 s10, v72, 51
	v_readlane_b32 s11, v29, 51
	global_store_dword v12, v70, s[16:17]
	s_nop 0
	v_mul_f32_e32 v66, s10, v70
	v_mul_f32_e32 v67, s11, v53
	v_add_f32_e32 v70, v66, v67
	s_add_u32 s16, s16, 0x100
	s_addc_u32 s17, s17, 0
	s_waitcnt vmcnt(46)
	v_readlane_b32 s10, v72, 52
	v_readlane_b32 s11, v29, 52
	global_store_dword v12, v70, s[16:17]
	s_nop 0
	v_mul_f32_e32 v66, s10, v70
	v_mul_f32_e32 v67, s11, v54
	v_add_f32_e32 v70, v66, v67
	s_add_u32 s16, s16, 0x100
	s_addc_u32 s17, s17, 0
	s_waitcnt vmcnt(45)
	v_readlane_b32 s10, v72, 53
	v_readlane_b32 s11, v29, 53
	global_store_dword v12, v70, s[16:17]
	s_nop 0
	v_mul_f32_e32 v66, s10, v70
	v_mul_f32_e32 v67, s11, v55
	v_add_f32_e32 v70, v66, v67
	s_add_u32 s16, s16, 0x100
	s_addc_u32 s17, s17, 0
	s_waitcnt vmcnt(44)
	v_readlane_b32 s10, v72, 54
	v_readlane_b32 s11, v29, 54
	global_store_dword v12, v70, s[16:17]
	s_nop 0
	v_mul_f32_e32 v66, s10, v70
	v_mul_f32_e32 v67, s11, v56
	v_add_f32_e32 v70, v66, v67
	s_add_u32 s16, s16, 0x100
	s_addc_u32 s17, s17, 0
	s_waitcnt vmcnt(43)
	v_readlane_b32 s10, v72, 55
	v_readlane_b32 s11, v29, 55
	global_store_dword v12, v70, s[16:17]
	s_nop 0
	v_mul_f32_e32 v66, s10, v70
	v_mul_f32_e32 v67, s11, v57
	v_add_f32_e32 v70, v66, v67
	s_add_u32 s16, s16, 0x100
	s_addc_u32 s17, s17, 0
	s_waitcnt vmcnt(42)
	v_readlane_b32 s10, v72, 56
	v_readlane_b32 s11, v29, 56
	global_store_dword v12, v70, s[16:17]
	s_nop 0
	v_mul_f32_e32 v66, s10, v70
	v_mul_f32_e32 v67, s11, v58
	v_add_f32_e32 v70, v66, v67
	s_add_u32 s16, s16, 0x100
	s_addc_u32 s17, s17, 0
	s_waitcnt vmcnt(41)
	v_readlane_b32 s10, v72, 57
	v_readlane_b32 s11, v29, 57
	global_store_dword v12, v70, s[16:17]
	s_nop 0
	v_mul_f32_e32 v66, s10, v70
	v_mul_f32_e32 v67, s11, v59
	v_add_f32_e32 v70, v66, v67
	s_add_u32 s16, s16, 0x100
	s_addc_u32 s17, s17, 0
	s_waitcnt vmcnt(40)
	v_readlane_b32 s10, v72, 58
	v_readlane_b32 s11, v29, 58
	global_store_dword v12, v70, s[16:17]
	s_nop 0
	v_mul_f32_e32 v66, s10, v70
	v_mul_f32_e32 v67, s11, v60
	v_add_f32_e32 v70, v66, v67
	s_add_u32 s16, s16, 0x100
	s_addc_u32 s17, s17, 0
	s_waitcnt vmcnt(39)
	v_readlane_b32 s10, v72, 59
	v_readlane_b32 s11, v29, 59
	global_store_dword v12, v70, s[16:17]
	s_nop 0
	v_mul_f32_e32 v66, s10, v70
	v_mul_f32_e32 v67, s11, v61
	v_add_f32_e32 v70, v66, v67
	s_add_u32 s16, s16, 0x100
	s_addc_u32 s17, s17, 0
	s_waitcnt vmcnt(38)
	v_readlane_b32 s10, v72, 60
	v_readlane_b32 s11, v29, 60
	global_store_dword v12, v70, s[16:17]
	s_nop 0
	v_mul_f32_e32 v66, s10, v70
	v_mul_f32_e32 v67, s11, v62
	v_add_f32_e32 v70, v66, v67
	s_add_u32 s16, s16, 0x100
	s_addc_u32 s17, s17, 0
	s_waitcnt vmcnt(37)
	v_readlane_b32 s10, v72, 61
	v_readlane_b32 s11, v29, 61
	global_store_dword v12, v70, s[16:17]
	s_nop 0
	v_mul_f32_e32 v66, s10, v70
	v_mul_f32_e32 v67, s11, v63
	v_add_f32_e32 v70, v66, v67
	s_add_u32 s16, s16, 0x100
	s_addc_u32 s17, s17, 0
	s_waitcnt vmcnt(36)
	v_readlane_b32 s10, v72, 62
	v_readlane_b32 s11, v29, 62
	global_store_dword v12, v70, s[16:17]
	s_nop 0
	v_mul_f32_e32 v66, s10, v70
	v_mul_f32_e32 v67, s11, v64
	v_add_f32_e32 v70, v66, v67
	s_add_u32 s16, s16, 0x100
	s_addc_u32 s17, s17, 0
	s_waitcnt vmcnt(35)
	v_readlane_b32 s10, v72, 63
	v_readlane_b32 s11, v29, 63
	global_store_dword v12, v70, s[16:17]
	s_nop 0
	v_mul_f32_e32 v66, s10, v70
	v_mul_f32_e32 v67, s11, v65
	v_add_f32_e32 v70, v66, v67
	s_add_u32 s16, s16, 0x100
	s_addc_u32 s17, s17, 0
	s_waitcnt vmcnt(34)
	v_readlane_b32 s10, v73, 0
	v_readlane_b32 s11, v30, 0
	global_store_dword v12, v70, s[16:17]
	s_nop 0
	v_mul_f32_e32 v66, s10, v70
	v_mul_f32_e32 v67, s11, v34
	v_add_f32_e32 v70, v66, v67
	s_add_u32 s16, s16, 0x100
	s_addc_u32 s17, s17, 0
	s_waitcnt vmcnt(33)
	v_readlane_b32 s10, v73, 1
	v_readlane_b32 s11, v30, 1
	global_store_dword v12, v70, s[16:17]
	s_nop 0
	v_mul_f32_e32 v66, s10, v70
	v_mul_f32_e32 v67, s11, v35
	v_add_f32_e32 v70, v66, v67
	s_add_u32 s16, s16, 0x100
	s_addc_u32 s17, s17, 0
	s_waitcnt vmcnt(32)
	v_readlane_b32 s10, v73, 2
	v_readlane_b32 s11, v30, 2
	global_store_dword v12, v70, s[16:17]
	s_nop 0
	v_mul_f32_e32 v66, s10, v70
	v_mul_f32_e32 v67, s11, v36
	v_add_f32_e32 v70, v66, v67
	s_add_u32 s16, s16, 0x100
	s_addc_u32 s17, s17, 0
	s_waitcnt vmcnt(31)
	v_readlane_b32 s10, v73, 3
	v_readlane_b32 s11, v30, 3
	global_store_dword v12, v70, s[16:17]
	s_nop 0
	v_mul_f32_e32 v66, s10, v70
	v_mul_f32_e32 v67, s11, v37
	v_add_f32_e32 v70, v66, v67
	s_add_u32 s16, s16, 0x100
	s_addc_u32 s17, s17, 0
.Lscan_unit_done:
	s_branch .LBB0_654
.LBB0_729:
	v_mov_b32_e32 v1, v0
	s_mov_b32 s28, s48
	v_mov_b32_e32 v18, v0
	s_barrier
	s_cmpk_gt_i32 s28, 0x18b
	v_readfirstlane_b32 s8, v18
	s_cbranch_scc1 .LBB0_755
	s_ashr_i32 s29, s28, 31
	s_lshr_b32 s2, s29, 29
	s_add_i32 s6, s28, s2
	s_and_b32 s2, s6, -8
	s_sub_i32 s9, s28, s2
	s_cmp_lt_i32 s9, 4
	s_cselect_b64 s[2:3], -1, 0
	s_cmp_gt_i32 s9, 3
	s_mov_b64 s[4:5], -1
	s_cbranch_scc0 .LBB0_732
	s_mul_i32 s4, s9, 49
	s_add_i32 s7, s4, 4
	s_mov_b64 s[4:5], 0
